# gates/merge epilogues: 114 IEEE f32 division sequences (SiLU/sigmoid feeding bf16) replaced by v_rcp_f32 + mul; scanner ds_read2st64 merges
# speedup vs baseline: 1.0178x; 1.0178x over previous
; __device__ void scan_chain(PRef p, int l, int chain, ScanSm* sm) {
;     ...
; #pragma unroll 1
;     for (int c = 0; c < 144; c++) {
;       __syncthreads();
;       const ScanRec* rc0 = &sm->rec[c & 1][0];
;       LDSET(A, rc0)
; #pragma unroll 1
;       for (int i2 = 0; i2 < 8; i2++) {
;         const ScanRec* rcA = rc0 + 2 * i2;
;         const ScanRec* rcC = (i2 < 7) ? rcA + 2 : rcA + 1;
;         LDSET(B, rcA + 1)
;         SCAN_STEP(A, c * 16 + 2 * i2)
;         LDSET(A, rcC)
;         SCAN_STEP(B, c * 16 + 2 * i2 + 1)
.Lscan_chunk:
	s_and_b32 s22, s15, 1
	s_mulk_i32 s22, 0x6000
	v_add_u32_e32 v14, s22, v10
	v_add_u32_e32 v15, s22, v11
	v_add_u32_e32 v16, s22, v12
	v_add_u32_e32 v17, 0x80, v14
	s_cmp_lg_u32 s15, 16
	s_cbranch_scc1 .Lscan_rowok
	s_cmp_eq_u32 s62, 0
	s_cselect_b32 s0, 0, 0x7fe
	s_add_i32 s0, s28, s0
	s_addk_i32 s0, 0x100
	s_lshl_b32 s0, s0, 10
	s_add_u32 s16, s12, s0
	s_addc_u32 s17, s13, 0
.Lscan_rowok:
	s_waitcnt lgkmcnt(0)
	s_barrier
	ds_read2st64_b32 v[100:101], v14 offset0:1 offset1:4
	ds_read2st64_b32 v[102:103], v17 offset0:1 offset1:4
	ds_read_b32 v136, v15 offset:0
	ds_read_b32 v137, v15 offset:128
	ds_read_b32 v108, v16 offset:0
	s_waitcnt lgkmcnt(0)
	ds_read2st64_b32 v[104:105], v14 offset0:7 offset1:10
	ds_read2st64_b32 v[106:107], v17 offset0:7 offset1:10
	ds_read_b32 v138, v15 offset:1536
	ds_read_b32 v139, v15 offset:1664
	ds_read_b32 v109, v16 offset:1536
	v_mul_f32_dpp v120, v100, v32 row_newbcast:0 row_mask:0xf bank_mask:0xf
	v_mul_f32_dpp v121, v100, v33 row_newbcast:1 row_mask:0xf bank_mask:0xf
	v_fmac_f32_dpp v120, v100, v34 row_newbcast:2 row_mask:0xf bank_mask:0xf
	v_fmac_f32_dpp v121, v100, v35 row_newbcast:3 row_mask:0xf bank_mask:0xf
	v_fmac_f32_dpp v120, v100, v36 row_newbcast:4 row_mask:0xf bank_mask:0xf
	v_fmac_f32_dpp v121, v100, v37 row_newbcast:5 row_mask:0xf bank_mask:0xf
	v_fmac_f32_dpp v120, v100, v38 row_newbcast:6 row_mask:0xf bank_mask:0xf
	v_fmac_f32_dpp v121, v100, v39 row_newbcast:7 row_mask:0xf bank_mask:0xf
	v_fmac_f32_dpp v120, v100, v40 row_newbcast:8 row_mask:0xf bank_mask:0xf
	v_fmac_f32_dpp v121, v100, v41 row_newbcast:9 row_mask:0xf bank_mask:0xf
	v_fmac_f32_dpp v120, v100, v42 row_newbcast:10 row_mask:0xf bank_mask:0xf
	v_fmac_f32_dpp v121, v100, v43 row_newbcast:11 row_mask:0xf bank_mask:0xf
	v_fmac_f32_dpp v120, v100, v44 row_newbcast:12 row_mask:0xf bank_mask:0xf
	v_fmac_f32_dpp v121, v100, v45 row_newbcast:13 row_mask:0xf bank_mask:0xf
	v_fmac_f32_dpp v120, v100, v46 row_newbcast:14 row_mask:0xf bank_mask:0xf
	v_fmac_f32_dpp v121, v100, v47 row_newbcast:15 row_mask:0xf bank_mask:0xf
	v_fmac_f32_dpp v120, v102, v48 row_newbcast:0 row_mask:0xf bank_mask:0xf
	v_fmac_f32_dpp v121, v102, v49 row_newbcast:1 row_mask:0xf bank_mask:0xf
	v_fmac_f32_dpp v120, v102, v50 row_newbcast:2 row_mask:0xf bank_mask:0xf
	v_fmac_f32_dpp v121, v102, v51 row_newbcast:3 row_mask:0xf bank_mask:0xf
	v_fmac_f32_dpp v120, v102, v52 row_newbcast:4 row_mask:0xf bank_mask:0xf
	v_fmac_f32_dpp v121, v102, v53 row_newbcast:5 row_mask:0xf bank_mask:0xf
	v_fmac_f32_dpp v120, v102, v54 row_newbcast:6 row_mask:0xf bank_mask:0xf
	v_fmac_f32_dpp v121, v102, v55 row_newbcast:7 row_mask:0xf bank_mask:0xf
	v_fmac_f32_dpp v120, v102, v56 row_newbcast:8 row_mask:0xf bank_mask:0xf
	v_fmac_f32_dpp v121, v102, v57 row_newbcast:9 row_mask:0xf bank_mask:0xf
	v_fmac_f32_dpp v120, v102, v58 row_newbcast:10 row_mask:0xf bank_mask:0xf
	v_fmac_f32_dpp v121, v102, v59 row_newbcast:11 row_mask:0xf bank_mask:0xf
	v_fmac_f32_dpp v120, v102, v60 row_newbcast:12 row_mask:0xf bank_mask:0xf
	v_fmac_f32_dpp v121, v102, v61 row_newbcast:13 row_mask:0xf bank_mask:0xf
	v_fmac_f32_dpp v120, v102, v62 row_newbcast:14 row_mask:0xf bank_mask:0xf
	v_fmac_f32_dpp v121, v102, v63 row_newbcast:15 row_mask:0xf bank_mask:0xf
	v_add_f32_e32 v128, v120, v121
	s_nop 1
	v_permlane32_swap_b32 v129, v128
	s_nop 1
	v_add_f32_dpp v108, -v129, -v128 quad_perm:[0,1,2,3] row_mask:0xc bank_mask:0xf
	s_nop 1
	v_mfma_f32_32x32x2_f32 v[64:79], v136, v108, v[32:47]
	s_nop 15
	v_mfma_f32_32x32x2_f32 v[80:95], v137, v108, v[48:63]
	s_nop 7
	s_waitcnt lgkmcnt(0)
	ds_read2st64_b32 v[110:111], v14 offset0:13 offset1:16
	ds_read2st64_b32 v[112:113], v17 offset0:13 offset1:16
	ds_read_b32 v136, v15 offset:3072
	ds_read_b32 v137, v15 offset:3200
	ds_read_b32 v108, v16 offset:3072
	v_mul_f32_dpp v120, v104, v64 row_newbcast:0 row_mask:0xf bank_mask:0xf
	v_mul_f32_dpp v121, v104, v65 row_newbcast:1 row_mask:0xf bank_mask:0xf
	v_fmac_f32_dpp v120, v104, v66 row_newbcast:2 row_mask:0xf bank_mask:0xf
	v_fmac_f32_dpp v121, v104, v67 row_newbcast:3 row_mask:0xf bank_mask:0xf
	v_fmac_f32_dpp v120, v104, v68 row_newbcast:4 row_mask:0xf bank_mask:0xf
	v_fmac_f32_dpp v121, v104, v69 row_newbcast:5 row_mask:0xf bank_mask:0xf
	v_fmac_f32_dpp v120, v104, v70 row_newbcast:6 row_mask:0xf bank_mask:0xf
	v_fmac_f32_dpp v121, v104, v71 row_newbcast:7 row_mask:0xf bank_mask:0xf
	v_fmac_f32_dpp v120, v104, v72 row_newbcast:8 row_mask:0xf bank_mask:0xf
	v_fmac_f32_dpp v121, v104, v73 row_newbcast:9 row_mask:0xf bank_mask:0xf
	v_fmac_f32_dpp v120, v104, v74 row_newbcast:10 row_mask:0xf bank_mask:0xf
	v_fmac_f32_dpp v121, v104, v75 row_newbcast:11 row_mask:0xf bank_mask:0xf
	v_fmac_f32_dpp v120, v104, v76 row_newbcast:12 row_mask:0xf bank_mask:0xf
	v_fmac_f32_dpp v121, v104, v77 row_newbcast:13 row_mask:0xf bank_mask:0xf
	v_fmac_f32_dpp v120, v104, v78 row_newbcast:14 row_mask:0xf bank_mask:0xf
	v_fmac_f32_dpp v121, v104, v79 row_newbcast:15 row_mask:0xf bank_mask:0xf
	v_fmac_f32_dpp v120, v106, v80 row_newbcast:0 row_mask:0xf bank_mask:0xf
	v_fmac_f32_dpp v121, v106, v81 row_newbcast:1 row_mask:0xf bank_mask:0xf
	v_fmac_f32_dpp v120, v106, v82 row_newbcast:2 row_mask:0xf bank_mask:0xf
	v_fmac_f32_dpp v121, v106, v83 row_newbcast:3 row_mask:0xf bank_mask:0xf
	v_fmac_f32_dpp v120, v106, v84 row_newbcast:4 row_mask:0xf bank_mask:0xf
	v_fmac_f32_dpp v121, v106, v85 row_newbcast:5 row_mask:0xf bank_mask:0xf
	v_fmac_f32_dpp v120, v106, v86 row_newbcast:6 row_mask:0xf bank_mask:0xf
	v_fmac_f32_dpp v121, v106, v87 row_newbcast:7 row_mask:0xf bank_mask:0xf
	v_fmac_f32_dpp v120, v106, v88 row_newbcast:8 row_mask:0xf bank_mask:0xf
	v_fmac_f32_dpp v121, v106, v89 row_newbcast:9 row_mask:0xf bank_mask:0xf
	v_fmac_f32_dpp v120, v106, v90 row_newbcast:10 row_mask:0xf bank_mask:0xf
	v_fmac_f32_dpp v121, v106, v91 row_newbcast:11 row_mask:0xf bank_mask:0xf
	v_fmac_f32_dpp v120, v106, v92 row_newbcast:12 row_mask:0xf bank_mask:0xf
	v_fmac_f32_dpp v121, v106, v93 row_newbcast:13 row_mask:0xf bank_mask:0xf
	v_fmac_f32_dpp v120, v106, v94 row_newbcast:14 row_mask:0xf bank_mask:0xf
	v_fmac_f32_dpp v121, v106, v95 row_newbcast:15 row_mask:0xf bank_mask:0xf
	v_add_f32_e32 v128, v120, v121
	v_mul_f32_dpp v124, v101, v64 row_newbcast:0 row_mask:0xf bank_mask:0xf
	v_mul_f32_dpp v125, v101, v65 row_newbcast:1 row_mask:0xf bank_mask:0xf
	v_permlane32_swap_b32 v129, v128
	v_fmac_f32_dpp v124, v101, v66 row_newbcast:2 row_mask:0xf bank_mask:0xf
	v_fmac_f32_dpp v125, v101, v67 row_newbcast:3 row_mask:0xf bank_mask:0xf
	v_add_f32_dpp v109, -v129, -v128 quad_perm:[0,1,2,3] row_mask:0xc bank_mask:0xf
	v_fmac_f32_dpp v124, v101, v68 row_newbcast:4 row_mask:0xf bank_mask:0xf
	v_fmac_f32_dpp v125, v101, v69 row_newbcast:5 row_mask:0xf bank_mask:0xf
	v_mfma_f32_32x32x2_f32 v[32:47], v138, v109, v[64:79]
	v_fmac_f32_dpp v124, v101, v70 row_newbcast:6 row_mask:0xf bank_mask:0xf
	v_fmac_f32_dpp v125, v101, v71 row_newbcast:7 row_mask:0xf bank_mask:0xf
	v_fmac_f32_dpp v124, v101, v72 row_newbcast:8 row_mask:0xf bank_mask:0xf
	v_fmac_f32_dpp v125, v101, v73 row_newbcast:9 row_mask:0xf bank_mask:0xf
	v_fmac_f32_dpp v124, v101, v74 row_newbcast:10 row_mask:0xf bank_mask:0xf
	v_fmac_f32_dpp v125, v101, v75 row_newbcast:11 row_mask:0xf bank_mask:0xf
	v_fmac_f32_dpp v124, v101, v76 row_newbcast:12 row_mask:0xf bank_mask:0xf
	v_fmac_f32_dpp v125, v101, v77 row_newbcast:13 row_mask:0xf bank_mask:0xf
	v_fmac_f32_dpp v124, v101, v78 row_newbcast:14 row_mask:0xf bank_mask:0xf
	v_fmac_f32_dpp v125, v101, v79 row_newbcast:15 row_mask:0xf bank_mask:0xf
	v_fmac_f32_dpp v124, v103, v80 row_newbcast:0 row_mask:0xf bank_mask:0xf
	v_fmac_f32_dpp v125, v103, v81 row_newbcast:1 row_mask:0xf bank_mask:0xf
	v_fmac_f32_dpp v124, v103, v82 row_newbcast:2 row_mask:0xf bank_mask:0xf
	v_fmac_f32_dpp v125, v103, v83 row_newbcast:3 row_mask:0xf bank_mask:0xf
	v_mfma_f32_32x32x2_f32 v[48:63], v139, v109, v[80:95]
	v_fmac_f32_dpp v124, v103, v84 row_newbcast:4 row_mask:0xf bank_mask:0xf
	v_fmac_f32_dpp v125, v103, v85 row_newbcast:5 row_mask:0xf bank_mask:0xf
	v_fmac_f32_dpp v124, v103, v86 row_newbcast:6 row_mask:0xf bank_mask:0xf
	v_fmac_f32_dpp v125, v103, v87 row_newbcast:7 row_mask:0xf bank_mask:0xf
	v_fmac_f32_dpp v124, v103, v88 row_newbcast:8 row_mask:0xf bank_mask:0xf
	v_fmac_f32_dpp v125, v103, v89 row_newbcast:9 row_mask:0xf bank_mask:0xf
	v_fmac_f32_dpp v124, v103, v90 row_newbcast:10 row_mask:0xf bank_mask:0xf
	v_fmac_f32_dpp v125, v103, v91 row_newbcast:11 row_mask:0xf bank_mask:0xf
	v_fmac_f32_dpp v124, v103, v92 row_newbcast:12 row_mask:0xf bank_mask:0xf
	v_fmac_f32_dpp v125, v103, v93 row_newbcast:13 row_mask:0xf bank_mask:0xf
	v_fmac_f32_dpp v124, v103, v94 row_newbcast:14 row_mask:0xf bank_mask:0xf
	v_fmac_f32_dpp v125, v103, v95 row_newbcast:15 row_mask:0xf bank_mask:0xf
	v_add_f32_e32 v130, v124, v125
	s_waitcnt lgkmcnt(0)
	ds_read2st64_b32 v[114:115], v14 offset0:19 offset1:22
	ds_read2st64_b32 v[116:117], v17 offset0:19 offset1:22
	ds_read_b32 v138, v15 offset:4608
	ds_read_b32 v139, v15 offset:4736
	ds_read_b32 v109, v16 offset:4608
	v_mul_f32_dpp v120, v110, v32 row_newbcast:0 row_mask:0xf bank_mask:0xf
	v_mul_f32_dpp v121, v110, v33 row_newbcast:1 row_mask:0xf bank_mask:0xf
	v_fmac_f32_dpp v120, v110, v34 row_newbcast:2 row_mask:0xf bank_mask:0xf
	v_fmac_f32_dpp v121, v110, v35 row_newbcast:3 row_mask:0xf bank_mask:0xf
	v_fmac_f32_dpp v120, v110, v36 row_newbcast:4 row_mask:0xf bank_mask:0xf
	v_fmac_f32_dpp v121, v110, v37 row_newbcast:5 row_mask:0xf bank_mask:0xf
	v_fmac_f32_dpp v120, v110, v38 row_newbcast:6 row_mask:0xf bank_mask:0xf
	v_fmac_f32_dpp v121, v110, v39 row_newbcast:7 row_mask:0xf bank_mask:0xf
	v_fmac_f32_dpp v120, v110, v40 row_newbcast:8 row_mask:0xf bank_mask:0xf
	v_fmac_f32_dpp v121, v110, v41 row_newbcast:9 row_mask:0xf bank_mask:0xf
	v_fmac_f32_dpp v120, v110, v42 row_newbcast:10 row_mask:0xf bank_mask:0xf
	v_fmac_f32_dpp v121, v110, v43 row_newbcast:11 row_mask:0xf bank_mask:0xf
	v_fmac_f32_dpp v120, v110, v44 row_newbcast:12 row_mask:0xf bank_mask:0xf
	v_fmac_f32_dpp v121, v110, v45 row_newbcast:13 row_mask:0xf bank_mask:0xf
	v_fmac_f32_dpp v120, v110, v46 row_newbcast:14 row_mask:0xf bank_mask:0xf
	v_fmac_f32_dpp v121, v110, v47 row_newbcast:15 row_mask:0xf bank_mask:0xf
	v_fmac_f32_dpp v120, v112, v48 row_newbcast:0 row_mask:0xf bank_mask:0xf
	v_fmac_f32_dpp v121, v112, v49 row_newbcast:1 row_mask:0xf bank_mask:0xf
	v_fmac_f32_dpp v120, v112, v50 row_newbcast:2 row_mask:0xf bank_mask:0xf
	v_fmac_f32_dpp v121, v112, v51 row_newbcast:3 row_mask:0xf bank_mask:0xf
	v_fmac_f32_dpp v120, v112, v52 row_newbcast:4 row_mask:0xf bank_mask:0xf
	v_fmac_f32_dpp v121, v112, v53 row_newbcast:5 row_mask:0xf bank_mask:0xf
	v_fmac_f32_dpp v120, v112, v54 row_newbcast:6 row_mask:0xf bank_mask:0xf
	v_fmac_f32_dpp v121, v112, v55 row_newbcast:7 row_mask:0xf bank_mask:0xf
	v_fmac_f32_dpp v120, v112, v56 row_newbcast:8 row_mask:0xf bank_mask:0xf
	v_fmac_f32_dpp v121, v112, v57 row_newbcast:9 row_mask:0xf bank_mask:0xf
	v_fmac_f32_dpp v120, v112, v58 row_newbcast:10 row_mask:0xf bank_mask:0xf
	v_fmac_f32_dpp v121, v112, v59 row_newbcast:11 row_mask:0xf bank_mask:0xf
	v_fmac_f32_dpp v120, v112, v60 row_newbcast:12 row_mask:0xf bank_mask:0xf
	v_fmac_f32_dpp v121, v112, v61 row_newbcast:13 row_mask:0xf bank_mask:0xf
	v_fmac_f32_dpp v120, v112, v62 row_newbcast:14 row_mask:0xf bank_mask:0xf
	v_fmac_f32_dpp v121, v112, v63 row_newbcast:15 row_mask:0xf bank_mask:0xf
	v_add_f32_e32 v128, v120, v121
	v_mul_f32_dpp v124, v105, v32 row_newbcast:0 row_mask:0xf bank_mask:0xf
	v_mul_f32_dpp v125, v105, v33 row_newbcast:1 row_mask:0xf bank_mask:0xf
	v_permlane32_swap_b32 v129, v128
	v_fmac_f32_dpp v124, v105, v34 row_newbcast:2 row_mask:0xf bank_mask:0xf
	v_fmac_f32_dpp v125, v105, v35 row_newbcast:3 row_mask:0xf bank_mask:0xf
	v_add_f32_dpp v108, -v129, -v128 quad_perm:[0,1,2,3] row_mask:0xc bank_mask:0xf
	v_fmac_f32_dpp v124, v105, v36 row_newbcast:4 row_mask:0xf bank_mask:0xf
	v_fmac_f32_dpp v125, v105, v37 row_newbcast:5 row_mask:0xf bank_mask:0xf
	v_mfma_f32_32x32x2_f32 v[64:79], v136, v108, v[32:47]
	v_fmac_f32_dpp v124, v105, v38 row_newbcast:6 row_mask:0xf bank_mask:0xf
	v_fmac_f32_dpp v125, v105, v39 row_newbcast:7 row_mask:0xf bank_mask:0xf
	v_fmac_f32_dpp v124, v105, v40 row_newbcast:8 row_mask:0xf bank_mask:0xf
	v_fmac_f32_dpp v125, v105, v41 row_newbcast:9 row_mask:0xf bank_mask:0xf
	v_fmac_f32_dpp v124, v105, v42 row_newbcast:10 row_mask:0xf bank_mask:0xf
	v_fmac_f32_dpp v125, v105, v43 row_newbcast:11 row_mask:0xf bank_mask:0xf
	v_fmac_f32_dpp v124, v105, v44 row_newbcast:12 row_mask:0xf bank_mask:0xf
	v_fmac_f32_dpp v125, v105, v45 row_newbcast:13 row_mask:0xf bank_mask:0xf
	v_fmac_f32_dpp v124, v105, v46 row_newbcast:14 row_mask:0xf bank_mask:0xf
	v_fmac_f32_dpp v125, v105, v47 row_newbcast:15 row_mask:0xf bank_mask:0xf
	v_fmac_f32_dpp v124, v107, v48 row_newbcast:0 row_mask:0xf bank_mask:0xf
	v_fmac_f32_dpp v125, v107, v49 row_newbcast:1 row_mask:0xf bank_mask:0xf
	v_fmac_f32_dpp v124, v107, v50 row_newbcast:2 row_mask:0xf bank_mask:0xf
	v_fmac_f32_dpp v125, v107, v51 row_newbcast:3 row_mask:0xf bank_mask:0xf
	v_mfma_f32_32x32x2_f32 v[80:95], v137, v108, v[48:63]
	v_fmac_f32_dpp v124, v107, v52 row_newbcast:4 row_mask:0xf bank_mask:0xf
	v_fmac_f32_dpp v125, v107, v53 row_newbcast:5 row_mask:0xf bank_mask:0xf
	v_fmac_f32_dpp v124, v107, v54 row_newbcast:6 row_mask:0xf bank_mask:0xf
	v_fmac_f32_dpp v125, v107, v55 row_newbcast:7 row_mask:0xf bank_mask:0xf
	v_fmac_f32_dpp v124, v107, v56 row_newbcast:8 row_mask:0xf bank_mask:0xf
	v_fmac_f32_dpp v125, v107, v57 row_newbcast:9 row_mask:0xf bank_mask:0xf
	v_fmac_f32_dpp v124, v107, v58 row_newbcast:10 row_mask:0xf bank_mask:0xf
	v_fmac_f32_dpp v125, v107, v59 row_newbcast:11 row_mask:0xf bank_mask:0xf
	v_fmac_f32_dpp v124, v107, v60 row_newbcast:12 row_mask:0xf bank_mask:0xf
	v_fmac_f32_dpp v125, v107, v61 row_newbcast:13 row_mask:0xf bank_mask:0xf
	v_fmac_f32_dpp v124, v107, v62 row_newbcast:14 row_mask:0xf bank_mask:0xf
	v_fmac_f32_dpp v125, v107, v63 row_newbcast:15 row_mask:0xf bank_mask:0xf
	v_add_f32_e32 v131, v124, v125
	s_nop 1
	v_permlane32_swap_b32 v130, v131
	v_add_f32_e32 v133, v130, v131
	v_cvt_pk_bf16_f32 v133, v133, v133
	global_store_short v13, v133, s[16:17]
	s_add_u32 s16, s16, s20
	s_addc_u32 s17, s17, s21
	s_waitcnt lgkmcnt(0)
	ds_read2st64_b32 v[100:101], v14 offset0:25 offset1:28
	ds_read2st64_b32 v[102:103], v17 offset0:25 offset1:28
	ds_read_b32 v136, v15 offset:6144
	ds_read_b32 v137, v15 offset:6272
	ds_read_b32 v108, v16 offset:6144
	v_mul_f32_dpp v120, v114, v64 row_newbcast:0 row_mask:0xf bank_mask:0xf
	v_mul_f32_dpp v121, v114, v65 row_newbcast:1 row_mask:0xf bank_mask:0xf
	v_fmac_f32_dpp v120, v114, v66 row_newbcast:2 row_mask:0xf bank_mask:0xf
	v_fmac_f32_dpp v121, v114, v67 row_newbcast:3 row_mask:0xf bank_mask:0xf
	v_fmac_f32_dpp v120, v114, v68 row_newbcast:4 row_mask:0xf bank_mask:0xf
	v_fmac_f32_dpp v121, v114, v69 row_newbcast:5 row_mask:0xf bank_mask:0xf
	v_fmac_f32_dpp v120, v114, v70 row_newbcast:6 row_mask:0xf bank_mask:0xf
	v_fmac_f32_dpp v121, v114, v71 row_newbcast:7 row_mask:0xf bank_mask:0xf
	v_fmac_f32_dpp v120, v114, v72 row_newbcast:8 row_mask:0xf bank_mask:0xf
	v_fmac_f32_dpp v121, v114, v73 row_newbcast:9 row_mask:0xf bank_mask:0xf
	v_fmac_f32_dpp v120, v114, v74 row_newbcast:10 row_mask:0xf bank_mask:0xf
	v_fmac_f32_dpp v121, v114, v75 row_newbcast:11 row_mask:0xf bank_mask:0xf
	v_fmac_f32_dpp v120, v114, v76 row_newbcast:12 row_mask:0xf bank_mask:0xf
	v_fmac_f32_dpp v121, v114, v77 row_newbcast:13 row_mask:0xf bank_mask:0xf
	v_fmac_f32_dpp v120, v114, v78 row_newbcast:14 row_mask:0xf bank_mask:0xf
	v_fmac_f32_dpp v121, v114, v79 row_newbcast:15 row_mask:0xf bank_mask:0xf
	v_fmac_f32_dpp v120, v116, v80 row_newbcast:0 row_mask:0xf bank_mask:0xf
	v_fmac_f32_dpp v121, v116, v81 row_newbcast:1 row_mask:0xf bank_mask:0xf
	v_fmac_f32_dpp v120, v116, v82 row_newbcast:2 row_mask:0xf bank_mask:0xf
	v_fmac_f32_dpp v121, v116, v83 row_newbcast:3 row_mask:0xf bank_mask:0xf
	v_fmac_f32_dpp v120, v116, v84 row_newbcast:4 row_mask:0xf bank_mask:0xf
	v_fmac_f32_dpp v121, v116, v85 row_newbcast:5 row_mask:0xf bank_mask:0xf
	v_fmac_f32_dpp v120, v116, v86 row_newbcast:6 row_mask:0xf bank_mask:0xf
	v_fmac_f32_dpp v121, v116, v87 row_newbcast:7 row_mask:0xf bank_mask:0xf
	v_fmac_f32_dpp v120, v116, v88 row_newbcast:8 row_mask:0xf bank_mask:0xf
	v_fmac_f32_dpp v121, v116, v89 row_newbcast:9 row_mask:0xf bank_mask:0xf
	v_fmac_f32_dpp v120, v116, v90 row_newbcast:10 row_mask:0xf bank_mask:0xf
	v_fmac_f32_dpp v121, v116, v91 row_newbcast:11 row_mask:0xf bank_mask:0xf
	v_fmac_f32_dpp v120, v116, v92 row_newbcast:12 row_mask:0xf bank_mask:0xf
	v_fmac_f32_dpp v121, v116, v93 row_newbcast:13 row_mask:0xf bank_mask:0xf
	v_fmac_f32_dpp v120, v116, v94 row_newbcast:14 row_mask:0xf bank_mask:0xf
	v_fmac_f32_dpp v121, v116, v95 row_newbcast:15 row_mask:0xf bank_mask:0xf
	v_add_f32_e32 v128, v120, v121
	v_mul_f32_dpp v124, v111, v64 row_newbcast:0 row_mask:0xf bank_mask:0xf
	v_mul_f32_dpp v125, v111, v65 row_newbcast:1 row_mask:0xf bank_mask:0xf
	v_permlane32_swap_b32 v129, v128
	v_fmac_f32_dpp v124, v111, v66 row_newbcast:2 row_mask:0xf bank_mask:0xf
	v_fmac_f32_dpp v125, v111, v67 row_newbcast:3 row_mask:0xf bank_mask:0xf
	v_add_f32_dpp v109, -v129, -v128 quad_perm:[0,1,2,3] row_mask:0xc bank_mask:0xf
	v_fmac_f32_dpp v124, v111, v68 row_newbcast:4 row_mask:0xf bank_mask:0xf
	v_fmac_f32_dpp v125, v111, v69 row_newbcast:5 row_mask:0xf bank_mask:0xf
	v_mfma_f32_32x32x2_f32 v[32:47], v138, v109, v[64:79]
	v_fmac_f32_dpp v124, v111, v70 row_newbcast:6 row_mask:0xf bank_mask:0xf
	v_fmac_f32_dpp v125, v111, v71 row_newbcast:7 row_mask:0xf bank_mask:0xf
	v_fmac_f32_dpp v124, v111, v72 row_newbcast:8 row_mask:0xf bank_mask:0xf
	v_fmac_f32_dpp v125, v111, v73 row_newbcast:9 row_mask:0xf bank_mask:0xf
	v_fmac_f32_dpp v124, v111, v74 row_newbcast:10 row_mask:0xf bank_mask:0xf
	v_fmac_f32_dpp v125, v111, v75 row_newbcast:11 row_mask:0xf bank_mask:0xf
	v_fmac_f32_dpp v124, v111, v76 row_newbcast:12 row_mask:0xf bank_mask:0xf
	v_fmac_f32_dpp v125, v111, v77 row_newbcast:13 row_mask:0xf bank_mask:0xf
	v_fmac_f32_dpp v124, v111, v78 row_newbcast:14 row_mask:0xf bank_mask:0xf
	v_fmac_f32_dpp v125, v111, v79 row_newbcast:15 row_mask:0xf bank_mask:0xf
	v_fmac_f32_dpp v124, v113, v80 row_newbcast:0 row_mask:0xf bank_mask:0xf
	v_fmac_f32_dpp v125, v113, v81 row_newbcast:1 row_mask:0xf bank_mask:0xf
	v_fmac_f32_dpp v124, v113, v82 row_newbcast:2 row_mask:0xf bank_mask:0xf
	v_fmac_f32_dpp v125, v113, v83 row_newbcast:3 row_mask:0xf bank_mask:0xf
	v_mfma_f32_32x32x2_f32 v[48:63], v139, v109, v[80:95]
	v_fmac_f32_dpp v124, v113, v84 row_newbcast:4 row_mask:0xf bank_mask:0xf
	v_fmac_f32_dpp v125, v113, v85 row_newbcast:5 row_mask:0xf bank_mask:0xf
	v_fmac_f32_dpp v124, v113, v86 row_newbcast:6 row_mask:0xf bank_mask:0xf
	v_fmac_f32_dpp v125, v113, v87 row_newbcast:7 row_mask:0xf bank_mask:0xf
	v_fmac_f32_dpp v124, v113, v88 row_newbcast:8 row_mask:0xf bank_mask:0xf
	v_fmac_f32_dpp v125, v113, v89 row_newbcast:9 row_mask:0xf bank_mask:0xf
	v_fmac_f32_dpp v124, v113, v90 row_newbcast:10 row_mask:0xf bank_mask:0xf
	v_fmac_f32_dpp v125, v113, v91 row_newbcast:11 row_mask:0xf bank_mask:0xf
	v_fmac_f32_dpp v124, v113, v92 row_newbcast:12 row_mask:0xf bank_mask:0xf
	v_fmac_f32_dpp v125, v113, v93 row_newbcast:13 row_mask:0xf bank_mask:0xf
	v_fmac_f32_dpp v124, v113, v94 row_newbcast:14 row_mask:0xf bank_mask:0xf
	v_fmac_f32_dpp v125, v113, v95 row_newbcast:15 row_mask:0xf bank_mask:0xf
	v_add_f32_e32 v130, v124, v125
	s_waitcnt lgkmcnt(0)
	ds_read2st64_b32 v[104:105], v14 offset0:31 offset1:34
	ds_read2st64_b32 v[106:107], v17 offset0:31 offset1:34
	ds_read_b32 v138, v15 offset:7680
	ds_read_b32 v139, v15 offset:7808
	ds_read_b32 v109, v16 offset:7680
	v_mul_f32_dpp v120, v100, v32 row_newbcast:0 row_mask:0xf bank_mask:0xf
	v_mul_f32_dpp v121, v100, v33 row_newbcast:1 row_mask:0xf bank_mask:0xf
	v_fmac_f32_dpp v120, v100, v34 row_newbcast:2 row_mask:0xf bank_mask:0xf
	v_fmac_f32_dpp v121, v100, v35 row_newbcast:3 row_mask:0xf bank_mask:0xf
	v_fmac_f32_dpp v120, v100, v36 row_newbcast:4 row_mask:0xf bank_mask:0xf
	v_fmac_f32_dpp v121, v100, v37 row_newbcast:5 row_mask:0xf bank_mask:0xf
	v_fmac_f32_dpp v120, v100, v38 row_newbcast:6 row_mask:0xf bank_mask:0xf
	v_fmac_f32_dpp v121, v100, v39 row_newbcast:7 row_mask:0xf bank_mask:0xf
	v_fmac_f32_dpp v120, v100, v40 row_newbcast:8 row_mask:0xf bank_mask:0xf
	v_fmac_f32_dpp v121, v100, v41 row_newbcast:9 row_mask:0xf bank_mask:0xf
	v_fmac_f32_dpp v120, v100, v42 row_newbcast:10 row_mask:0xf bank_mask:0xf
	v_fmac_f32_dpp v121, v100, v43 row_newbcast:11 row_mask:0xf bank_mask:0xf
	v_fmac_f32_dpp v120, v100, v44 row_newbcast:12 row_mask:0xf bank_mask:0xf
	v_fmac_f32_dpp v121, v100, v45 row_newbcast:13 row_mask:0xf bank_mask:0xf
	v_fmac_f32_dpp v120, v100, v46 row_newbcast:14 row_mask:0xf bank_mask:0xf
	v_fmac_f32_dpp v121, v100, v47 row_newbcast:15 row_mask:0xf bank_mask:0xf
	v_fmac_f32_dpp v120, v102, v48 row_newbcast:0 row_mask:0xf bank_mask:0xf
	v_fmac_f32_dpp v121, v102, v49 row_newbcast:1 row_mask:0xf bank_mask:0xf
	v_fmac_f32_dpp v120, v102, v50 row_newbcast:2 row_mask:0xf bank_mask:0xf
	v_fmac_f32_dpp v121, v102, v51 row_newbcast:3 row_mask:0xf bank_mask:0xf
	v_fmac_f32_dpp v120, v102, v52 row_newbcast:4 row_mask:0xf bank_mask:0xf
	v_fmac_f32_dpp v121, v102, v53 row_newbcast:5 row_mask:0xf bank_mask:0xf
	v_fmac_f32_dpp v120, v102, v54 row_newbcast:6 row_mask:0xf bank_mask:0xf
	v_fmac_f32_dpp v121, v102, v55 row_newbcast:7 row_mask:0xf bank_mask:0xf
	v_fmac_f32_dpp v120, v102, v56 row_newbcast:8 row_mask:0xf bank_mask:0xf
	v_fmac_f32_dpp v121, v102, v57 row_newbcast:9 row_mask:0xf bank_mask:0xf
	v_fmac_f32_dpp v120, v102, v58 row_newbcast:10 row_mask:0xf bank_mask:0xf
	v_fmac_f32_dpp v121, v102, v59 row_newbcast:11 row_mask:0xf bank_mask:0xf
	v_fmac_f32_dpp v120, v102, v60 row_newbcast:12 row_mask:0xf bank_mask:0xf
	v_fmac_f32_dpp v121, v102, v61 row_newbcast:13 row_mask:0xf bank_mask:0xf
	v_fmac_f32_dpp v120, v102, v62 row_newbcast:14 row_mask:0xf bank_mask:0xf
	v_fmac_f32_dpp v121, v102, v63 row_newbcast:15 row_mask:0xf bank_mask:0xf
	v_add_f32_e32 v128, v120, v121
	v_mul_f32_dpp v124, v115, v32 row_newbcast:0 row_mask:0xf bank_mask:0xf
	v_mul_f32_dpp v125, v115, v33 row_newbcast:1 row_mask:0xf bank_mask:0xf
	v_permlane32_swap_b32 v129, v128
	v_fmac_f32_dpp v124, v115, v34 row_newbcast:2 row_mask:0xf bank_mask:0xf
	v_fmac_f32_dpp v125, v115, v35 row_newbcast:3 row_mask:0xf bank_mask:0xf
	v_add_f32_dpp v108, -v129, -v128 quad_perm:[0,1,2,3] row_mask:0xc bank_mask:0xf
	v_fmac_f32_dpp v124, v115, v36 row_newbcast:4 row_mask:0xf bank_mask:0xf
	v_fmac_f32_dpp v125, v115, v37 row_newbcast:5 row_mask:0xf bank_mask:0xf
	v_mfma_f32_32x32x2_f32 v[64:79], v136, v108, v[32:47]
	v_fmac_f32_dpp v124, v115, v38 row_newbcast:6 row_mask:0xf bank_mask:0xf
	v_fmac_f32_dpp v125, v115, v39 row_newbcast:7 row_mask:0xf bank_mask:0xf
	v_fmac_f32_dpp v124, v115, v40 row_newbcast:8 row_mask:0xf bank_mask:0xf
	v_fmac_f32_dpp v125, v115, v41 row_newbcast:9 row_mask:0xf bank_mask:0xf
	v_fmac_f32_dpp v124, v115, v42 row_newbcast:10 row_mask:0xf bank_mask:0xf
	v_fmac_f32_dpp v125, v115, v43 row_newbcast:11 row_mask:0xf bank_mask:0xf
	v_fmac_f32_dpp v124, v115, v44 row_newbcast:12 row_mask:0xf bank_mask:0xf
	v_fmac_f32_dpp v125, v115, v45 row_newbcast:13 row_mask:0xf bank_mask:0xf
	v_fmac_f32_dpp v124, v115, v46 row_newbcast:14 row_mask:0xf bank_mask:0xf
	v_fmac_f32_dpp v125, v115, v47 row_newbcast:15 row_mask:0xf bank_mask:0xf
	v_fmac_f32_dpp v124, v117, v48 row_newbcast:0 row_mask:0xf bank_mask:0xf
	v_fmac_f32_dpp v125, v117, v49 row_newbcast:1 row_mask:0xf bank_mask:0xf
	v_fmac_f32_dpp v124, v117, v50 row_newbcast:2 row_mask:0xf bank_mask:0xf
	v_fmac_f32_dpp v125, v117, v51 row_newbcast:3 row_mask:0xf bank_mask:0xf
	v_mfma_f32_32x32x2_f32 v[80:95], v137, v108, v[48:63]
	v_fmac_f32_dpp v124, v117, v52 row_newbcast:4 row_mask:0xf bank_mask:0xf
	v_fmac_f32_dpp v125, v117, v53 row_newbcast:5 row_mask:0xf bank_mask:0xf
	v_fmac_f32_dpp v124, v117, v54 row_newbcast:6 row_mask:0xf bank_mask:0xf
	v_fmac_f32_dpp v125, v117, v55 row_newbcast:7 row_mask:0xf bank_mask:0xf
	v_fmac_f32_dpp v124, v117, v56 row_newbcast:8 row_mask:0xf bank_mask:0xf
	v_fmac_f32_dpp v125, v117, v57 row_newbcast:9 row_mask:0xf bank_mask:0xf
	v_fmac_f32_dpp v124, v117, v58 row_newbcast:10 row_mask:0xf bank_mask:0xf
	v_fmac_f32_dpp v125, v117, v59 row_newbcast:11 row_mask:0xf bank_mask:0xf
	v_fmac_f32_dpp v124, v117, v60 row_newbcast:12 row_mask:0xf bank_mask:0xf
	v_fmac_f32_dpp v125, v117, v61 row_newbcast:13 row_mask:0xf bank_mask:0xf
	v_fmac_f32_dpp v124, v117, v62 row_newbcast:14 row_mask:0xf bank_mask:0xf
	v_fmac_f32_dpp v125, v117, v63 row_newbcast:15 row_mask:0xf bank_mask:0xf
	v_add_f32_e32 v131, v124, v125
	s_nop 1
	v_permlane32_swap_b32 v130, v131
	v_add_f32_e32 v133, v130, v131
	v_cvt_pk_bf16_f32 v133, v133, v133
	global_store_short v13, v133, s[16:17]
	s_add_u32 s16, s16, s20
	s_addc_u32 s17, s17, s21
	s_waitcnt lgkmcnt(0)
	ds_read2st64_b32 v[110:111], v14 offset0:37 offset1:40
	ds_read2st64_b32 v[112:113], v17 offset0:37 offset1:40
	ds_read_b32 v136, v15 offset:9216
	ds_read_b32 v137, v15 offset:9344
	ds_read_b32 v108, v16 offset:9216
	v_mul_f32_dpp v120, v104, v64 row_newbcast:0 row_mask:0xf bank_mask:0xf
	v_mul_f32_dpp v121, v104, v65 row_newbcast:1 row_mask:0xf bank_mask:0xf
	v_fmac_f32_dpp v120, v104, v66 row_newbcast:2 row_mask:0xf bank_mask:0xf
	v_fmac_f32_dpp v121, v104, v67 row_newbcast:3 row_mask:0xf bank_mask:0xf
	v_fmac_f32_dpp v120, v104, v68 row_newbcast:4 row_mask:0xf bank_mask:0xf
	v_fmac_f32_dpp v121, v104, v69 row_newbcast:5 row_mask:0xf bank_mask:0xf
	v_fmac_f32_dpp v120, v104, v70 row_newbcast:6 row_mask:0xf bank_mask:0xf
	v_fmac_f32_dpp v121, v104, v71 row_newbcast:7 row_mask:0xf bank_mask:0xf
	v_fmac_f32_dpp v120, v104, v72 row_newbcast:8 row_mask:0xf bank_mask:0xf
	v_fmac_f32_dpp v121, v104, v73 row_newbcast:9 row_mask:0xf bank_mask:0xf
	v_fmac_f32_dpp v120, v104, v74 row_newbcast:10 row_mask:0xf bank_mask:0xf
	v_fmac_f32_dpp v121, v104, v75 row_newbcast:11 row_mask:0xf bank_mask:0xf
	v_fmac_f32_dpp v120, v104, v76 row_newbcast:12 row_mask:0xf bank_mask:0xf
	v_fmac_f32_dpp v121, v104, v77 row_newbcast:13 row_mask:0xf bank_mask:0xf
	v_fmac_f32_dpp v120, v104, v78 row_newbcast:14 row_mask:0xf bank_mask:0xf
	v_fmac_f32_dpp v121, v104, v79 row_newbcast:15 row_mask:0xf bank_mask:0xf
	v_fmac_f32_dpp v120, v106, v80 row_newbcast:0 row_mask:0xf bank_mask:0xf
	v_fmac_f32_dpp v121, v106, v81 row_newbcast:1 row_mask:0xf bank_mask:0xf
	v_fmac_f32_dpp v120, v106, v82 row_newbcast:2 row_mask:0xf bank_mask:0xf
	v_fmac_f32_dpp v121, v106, v83 row_newbcast:3 row_mask:0xf bank_mask:0xf
	v_fmac_f32_dpp v120, v106, v84 row_newbcast:4 row_mask:0xf bank_mask:0xf
	v_fmac_f32_dpp v121, v106, v85 row_newbcast:5 row_mask:0xf bank_mask:0xf
	v_fmac_f32_dpp v120, v106, v86 row_newbcast:6 row_mask:0xf bank_mask:0xf
	v_fmac_f32_dpp v121, v106, v87 row_newbcast:7 row_mask:0xf bank_mask:0xf
	v_fmac_f32_dpp v120, v106, v88 row_newbcast:8 row_mask:0xf bank_mask:0xf
	v_fmac_f32_dpp v121, v106, v89 row_newbcast:9 row_mask:0xf bank_mask:0xf
	v_fmac_f32_dpp v120, v106, v90 row_newbcast:10 row_mask:0xf bank_mask:0xf
	v_fmac_f32_dpp v121, v106, v91 row_newbcast:11 row_mask:0xf bank_mask:0xf
	v_fmac_f32_dpp v120, v106, v92 row_newbcast:12 row_mask:0xf bank_mask:0xf
	v_fmac_f32_dpp v121, v106, v93 row_newbcast:13 row_mask:0xf bank_mask:0xf
	v_fmac_f32_dpp v120, v106, v94 row_newbcast:14 row_mask:0xf bank_mask:0xf
	v_fmac_f32_dpp v121, v106, v95 row_newbcast:15 row_mask:0xf bank_mask:0xf
	v_add_f32_e32 v128, v120, v121
	v_mul_f32_dpp v124, v101, v64 row_newbcast:0 row_mask:0xf bank_mask:0xf
	v_mul_f32_dpp v125, v101, v65 row_newbcast:1 row_mask:0xf bank_mask:0xf
	v_permlane32_swap_b32 v129, v128
	v_fmac_f32_dpp v124, v101, v66 row_newbcast:2 row_mask:0xf bank_mask:0xf
	v_fmac_f32_dpp v125, v101, v67 row_newbcast:3 row_mask:0xf bank_mask:0xf
	v_add_f32_dpp v109, -v129, -v128 quad_perm:[0,1,2,3] row_mask:0xc bank_mask:0xf
	v_fmac_f32_dpp v124, v101, v68 row_newbcast:4 row_mask:0xf bank_mask:0xf
	v_fmac_f32_dpp v125, v101, v69 row_newbcast:5 row_mask:0xf bank_mask:0xf
	v_mfma_f32_32x32x2_f32 v[32:47], v138, v109, v[64:79]
	v_fmac_f32_dpp v124, v101, v70 row_newbcast:6 row_mask:0xf bank_mask:0xf
	v_fmac_f32_dpp v125, v101, v71 row_newbcast:7 row_mask:0xf bank_mask:0xf
	v_fmac_f32_dpp v124, v101, v72 row_newbcast:8 row_mask:0xf bank_mask:0xf
	v_fmac_f32_dpp v125, v101, v73 row_newbcast:9 row_mask:0xf bank_mask:0xf
	v_fmac_f32_dpp v124, v101, v74 row_newbcast:10 row_mask:0xf bank_mask:0xf
	v_fmac_f32_dpp v125, v101, v75 row_newbcast:11 row_mask:0xf bank_mask:0xf
	v_fmac_f32_dpp v124, v101, v76 row_newbcast:12 row_mask:0xf bank_mask:0xf
	v_fmac_f32_dpp v125, v101, v77 row_newbcast:13 row_mask:0xf bank_mask:0xf
	v_fmac_f32_dpp v124, v101, v78 row_newbcast:14 row_mask:0xf bank_mask:0xf
	v_fmac_f32_dpp v125, v101, v79 row_newbcast:15 row_mask:0xf bank_mask:0xf
	v_fmac_f32_dpp v124, v103, v80 row_newbcast:0 row_mask:0xf bank_mask:0xf
	v_fmac_f32_dpp v125, v103, v81 row_newbcast:1 row_mask:0xf bank_mask:0xf
	v_fmac_f32_dpp v124, v103, v82 row_newbcast:2 row_mask:0xf bank_mask:0xf
	v_fmac_f32_dpp v125, v103, v83 row_newbcast:3 row_mask:0xf bank_mask:0xf
	v_mfma_f32_32x32x2_f32 v[48:63], v139, v109, v[80:95]
	v_fmac_f32_dpp v124, v103, v84 row_newbcast:4 row_mask:0xf bank_mask:0xf
	v_fmac_f32_dpp v125, v103, v85 row_newbcast:5 row_mask:0xf bank_mask:0xf
	v_fmac_f32_dpp v124, v103, v86 row_newbcast:6 row_mask:0xf bank_mask:0xf
	v_fmac_f32_dpp v125, v103, v87 row_newbcast:7 row_mask:0xf bank_mask:0xf
	v_fmac_f32_dpp v124, v103, v88 row_newbcast:8 row_mask:0xf bank_mask:0xf
	v_fmac_f32_dpp v125, v103, v89 row_newbcast:9 row_mask:0xf bank_mask:0xf
	v_fmac_f32_dpp v124, v103, v90 row_newbcast:10 row_mask:0xf bank_mask:0xf
	v_fmac_f32_dpp v125, v103, v91 row_newbcast:11 row_mask:0xf bank_mask:0xf
	v_fmac_f32_dpp v124, v103, v92 row_newbcast:12 row_mask:0xf bank_mask:0xf
	v_fmac_f32_dpp v125, v103, v93 row_newbcast:13 row_mask:0xf bank_mask:0xf
	v_fmac_f32_dpp v124, v103, v94 row_newbcast:14 row_mask:0xf bank_mask:0xf
	v_fmac_f32_dpp v125, v103, v95 row_newbcast:15 row_mask:0xf bank_mask:0xf
	v_add_f32_e32 v130, v124, v125
	s_waitcnt lgkmcnt(0)
	ds_read2st64_b32 v[114:115], v14 offset0:43 offset1:46
	ds_read2st64_b32 v[116:117], v17 offset0:43 offset1:46
	ds_read_b32 v138, v15 offset:10752
	ds_read_b32 v139, v15 offset:10880
	ds_read_b32 v109, v16 offset:10752
	ds_read_b32 v118, v14 offset:10752
	ds_read_b32 v119, v14 offset:10880
	v_mul_f32_dpp v120, v110, v32 row_newbcast:0 row_mask:0xf bank_mask:0xf
	v_mul_f32_dpp v121, v110, v33 row_newbcast:1 row_mask:0xf bank_mask:0xf
	v_fmac_f32_dpp v120, v110, v34 row_newbcast:2 row_mask:0xf bank_mask:0xf
	v_fmac_f32_dpp v121, v110, v35 row_newbcast:3 row_mask:0xf bank_mask:0xf
	v_fmac_f32_dpp v120, v110, v36 row_newbcast:4 row_mask:0xf bank_mask:0xf
	v_fmac_f32_dpp v121, v110, v37 row_newbcast:5 row_mask:0xf bank_mask:0xf
	v_fmac_f32_dpp v120, v110, v38 row_newbcast:6 row_mask:0xf bank_mask:0xf
	v_fmac_f32_dpp v121, v110, v39 row_newbcast:7 row_mask:0xf bank_mask:0xf
	v_fmac_f32_dpp v120, v110, v40 row_newbcast:8 row_mask:0xf bank_mask:0xf
	v_fmac_f32_dpp v121, v110, v41 row_newbcast:9 row_mask:0xf bank_mask:0xf
	v_fmac_f32_dpp v120, v110, v42 row_newbcast:10 row_mask:0xf bank_mask:0xf
	v_fmac_f32_dpp v121, v110, v43 row_newbcast:11 row_mask:0xf bank_mask:0xf
	v_fmac_f32_dpp v120, v110, v44 row_newbcast:12 row_mask:0xf bank_mask:0xf
	v_fmac_f32_dpp v121, v110, v45 row_newbcast:13 row_mask:0xf bank_mask:0xf
	v_fmac_f32_dpp v120, v110, v46 row_newbcast:14 row_mask:0xf bank_mask:0xf
	v_fmac_f32_dpp v121, v110, v47 row_newbcast:15 row_mask:0xf bank_mask:0xf
	v_fmac_f32_dpp v120, v112, v48 row_newbcast:0 row_mask:0xf bank_mask:0xf
	v_fmac_f32_dpp v121, v112, v49 row_newbcast:1 row_mask:0xf bank_mask:0xf
	v_fmac_f32_dpp v120, v112, v50 row_newbcast:2 row_mask:0xf bank_mask:0xf
	v_fmac_f32_dpp v121, v112, v51 row_newbcast:3 row_mask:0xf bank_mask:0xf
	v_fmac_f32_dpp v120, v112, v52 row_newbcast:4 row_mask:0xf bank_mask:0xf
	v_fmac_f32_dpp v121, v112, v53 row_newbcast:5 row_mask:0xf bank_mask:0xf
	v_fmac_f32_dpp v120, v112, v54 row_newbcast:6 row_mask:0xf bank_mask:0xf
	v_fmac_f32_dpp v121, v112, v55 row_newbcast:7 row_mask:0xf bank_mask:0xf
	v_fmac_f32_dpp v120, v112, v56 row_newbcast:8 row_mask:0xf bank_mask:0xf
	v_fmac_f32_dpp v121, v112, v57 row_newbcast:9 row_mask:0xf bank_mask:0xf
	v_fmac_f32_dpp v120, v112, v58 row_newbcast:10 row_mask:0xf bank_mask:0xf
	v_fmac_f32_dpp v121, v112, v59 row_newbcast:11 row_mask:0xf bank_mask:0xf
	v_fmac_f32_dpp v120, v112, v60 row_newbcast:12 row_mask:0xf bank_mask:0xf
	v_fmac_f32_dpp v121, v112, v61 row_newbcast:13 row_mask:0xf bank_mask:0xf
	v_fmac_f32_dpp v120, v112, v62 row_newbcast:14 row_mask:0xf bank_mask:0xf
	v_fmac_f32_dpp v121, v112, v63 row_newbcast:15 row_mask:0xf bank_mask:0xf
	v_add_f32_e32 v128, v120, v121
	v_mul_f32_dpp v124, v105, v32 row_newbcast:0 row_mask:0xf bank_mask:0xf
	v_mul_f32_dpp v125, v105, v33 row_newbcast:1 row_mask:0xf bank_mask:0xf
	v_permlane32_swap_b32 v129, v128
	v_fmac_f32_dpp v124, v105, v34 row_newbcast:2 row_mask:0xf bank_mask:0xf
	v_fmac_f32_dpp v125, v105, v35 row_newbcast:3 row_mask:0xf bank_mask:0xf
	v_add_f32_dpp v108, -v129, -v128 quad_perm:[0,1,2,3] row_mask:0xc bank_mask:0xf
	v_fmac_f32_dpp v124, v105, v36 row_newbcast:4 row_mask:0xf bank_mask:0xf
	v_fmac_f32_dpp v125, v105, v37 row_newbcast:5 row_mask:0xf bank_mask:0xf
	v_mfma_f32_32x32x2_f32 v[64:79], v136, v108, v[32:47]
	v_fmac_f32_dpp v124, v105, v38 row_newbcast:6 row_mask:0xf bank_mask:0xf
	v_fmac_f32_dpp v125, v105, v39 row_newbcast:7 row_mask:0xf bank_mask:0xf
	v_fmac_f32_dpp v124, v105, v40 row_newbcast:8 row_mask:0xf bank_mask:0xf
	v_fmac_f32_dpp v125, v105, v41 row_newbcast:9 row_mask:0xf bank_mask:0xf
	v_fmac_f32_dpp v124, v105, v42 row_newbcast:10 row_mask:0xf bank_mask:0xf
	v_fmac_f32_dpp v125, v105, v43 row_newbcast:11 row_mask:0xf bank_mask:0xf
	v_fmac_f32_dpp v124, v105, v44 row_newbcast:12 row_mask:0xf bank_mask:0xf
	v_fmac_f32_dpp v125, v105, v45 row_newbcast:13 row_mask:0xf bank_mask:0xf
	v_fmac_f32_dpp v124, v105, v46 row_newbcast:14 row_mask:0xf bank_mask:0xf
	v_fmac_f32_dpp v125, v105, v47 row_newbcast:15 row_mask:0xf bank_mask:0xf
	v_fmac_f32_dpp v124, v107, v48 row_newbcast:0 row_mask:0xf bank_mask:0xf
	v_fmac_f32_dpp v125, v107, v49 row_newbcast:1 row_mask:0xf bank_mask:0xf
	v_fmac_f32_dpp v124, v107, v50 row_newbcast:2 row_mask:0xf bank_mask:0xf
	v_fmac_f32_dpp v125, v107, v51 row_newbcast:3 row_mask:0xf bank_mask:0xf
	v_mfma_f32_32x32x2_f32 v[80:95], v137, v108, v[48:63]
	v_fmac_f32_dpp v124, v107, v52 row_newbcast:4 row_mask:0xf bank_mask:0xf
	v_fmac_f32_dpp v125, v107, v53 row_newbcast:5 row_mask:0xf bank_mask:0xf
	v_fmac_f32_dpp v124, v107, v54 row_newbcast:6 row_mask:0xf bank_mask:0xf
	v_fmac_f32_dpp v125, v107, v55 row_newbcast:7 row_mask:0xf bank_mask:0xf
	v_fmac_f32_dpp v124, v107, v56 row_newbcast:8 row_mask:0xf bank_mask:0xf
	v_fmac_f32_dpp v125, v107, v57 row_newbcast:9 row_mask:0xf bank_mask:0xf
	v_fmac_f32_dpp v124, v107, v58 row_newbcast:10 row_mask:0xf bank_mask:0xf
	v_fmac_f32_dpp v125, v107, v59 row_newbcast:11 row_mask:0xf bank_mask:0xf
	v_fmac_f32_dpp v124, v107, v60 row_newbcast:12 row_mask:0xf bank_mask:0xf
	v_fmac_f32_dpp v125, v107, v61 row_newbcast:13 row_mask:0xf bank_mask:0xf
	v_fmac_f32_dpp v124, v107, v62 row_newbcast:14 row_mask:0xf bank_mask:0xf
	v_fmac_f32_dpp v125, v107, v63 row_newbcast:15 row_mask:0xf bank_mask:0xf
	v_add_f32_e32 v131, v124, v125
	s_nop 1
	v_permlane32_swap_b32 v130, v131
	v_add_f32_e32 v133, v130, v131
	v_cvt_pk_bf16_f32 v133, v133, v133
	global_store_short v13, v133, s[16:17]
	s_add_u32 s16, s16, s20
	s_addc_u32 s17, s17, s21
	s_waitcnt lgkmcnt(0)
	ds_read2st64_b32 v[100:101], v14 offset0:49 offset1:52
	ds_read2st64_b32 v[102:103], v17 offset0:49 offset1:52
	ds_read_b32 v136, v15 offset:12288
	ds_read_b32 v137, v15 offset:12416
	ds_read_b32 v108, v16 offset:12288
	v_mul_f32_dpp v120, v114, v64 row_newbcast:0 row_mask:0xf bank_mask:0xf
	v_mul_f32_dpp v121, v114, v65 row_newbcast:1 row_mask:0xf bank_mask:0xf
	v_fmac_f32_dpp v120, v114, v66 row_newbcast:2 row_mask:0xf bank_mask:0xf
	v_fmac_f32_dpp v121, v114, v67 row_newbcast:3 row_mask:0xf bank_mask:0xf
	v_fmac_f32_dpp v120, v114, v68 row_newbcast:4 row_mask:0xf bank_mask:0xf
	v_fmac_f32_dpp v121, v114, v69 row_newbcast:5 row_mask:0xf bank_mask:0xf
	v_fmac_f32_dpp v120, v114, v70 row_newbcast:6 row_mask:0xf bank_mask:0xf
	v_fmac_f32_dpp v121, v114, v71 row_newbcast:7 row_mask:0xf bank_mask:0xf
	v_fmac_f32_dpp v120, v114, v72 row_newbcast:8 row_mask:0xf bank_mask:0xf
	v_fmac_f32_dpp v121, v114, v73 row_newbcast:9 row_mask:0xf bank_mask:0xf
	v_fmac_f32_dpp v120, v114, v74 row_newbcast:10 row_mask:0xf bank_mask:0xf
	v_fmac_f32_dpp v121, v114, v75 row_newbcast:11 row_mask:0xf bank_mask:0xf
	v_fmac_f32_dpp v120, v114, v76 row_newbcast:12 row_mask:0xf bank_mask:0xf
	v_fmac_f32_dpp v121, v114, v77 row_newbcast:13 row_mask:0xf bank_mask:0xf
	v_fmac_f32_dpp v120, v114, v78 row_newbcast:14 row_mask:0xf bank_mask:0xf
	v_fmac_f32_dpp v121, v114, v79 row_newbcast:15 row_mask:0xf bank_mask:0xf
	v_fmac_f32_dpp v120, v116, v80 row_newbcast:0 row_mask:0xf bank_mask:0xf
	v_fmac_f32_dpp v121, v116, v81 row_newbcast:1 row_mask:0xf bank_mask:0xf
	v_fmac_f32_dpp v120, v116, v82 row_newbcast:2 row_mask:0xf bank_mask:0xf
	v_fmac_f32_dpp v121, v116, v83 row_newbcast:3 row_mask:0xf bank_mask:0xf
	v_fmac_f32_dpp v120, v116, v84 row_newbcast:4 row_mask:0xf bank_mask:0xf
	v_fmac_f32_dpp v121, v116, v85 row_newbcast:5 row_mask:0xf bank_mask:0xf
	v_fmac_f32_dpp v120, v116, v86 row_newbcast:6 row_mask:0xf bank_mask:0xf
	v_fmac_f32_dpp v121, v116, v87 row_newbcast:7 row_mask:0xf bank_mask:0xf
	v_fmac_f32_dpp v120, v116, v88 row_newbcast:8 row_mask:0xf bank_mask:0xf
	v_fmac_f32_dpp v121, v116, v89 row_newbcast:9 row_mask:0xf bank_mask:0xf
	v_fmac_f32_dpp v120, v116, v90 row_newbcast:10 row_mask:0xf bank_mask:0xf
	v_fmac_f32_dpp v121, v116, v91 row_newbcast:11 row_mask:0xf bank_mask:0xf
	v_fmac_f32_dpp v120, v116, v92 row_newbcast:12 row_mask:0xf bank_mask:0xf
	v_fmac_f32_dpp v121, v116, v93 row_newbcast:13 row_mask:0xf bank_mask:0xf
	v_fmac_f32_dpp v120, v116, v94 row_newbcast:14 row_mask:0xf bank_mask:0xf
	v_fmac_f32_dpp v121, v116, v95 row_newbcast:15 row_mask:0xf bank_mask:0xf
	v_add_f32_e32 v128, v120, v121
	v_mul_f32_dpp v124, v111, v64 row_newbcast:0 row_mask:0xf bank_mask:0xf
	v_mul_f32_dpp v125, v111, v65 row_newbcast:1 row_mask:0xf bank_mask:0xf
	v_permlane32_swap_b32 v129, v128
	v_fmac_f32_dpp v124, v111, v66 row_newbcast:2 row_mask:0xf bank_mask:0xf
	v_fmac_f32_dpp v125, v111, v67 row_newbcast:3 row_mask:0xf bank_mask:0xf
	v_add_f32_dpp v109, -v129, -v128 quad_perm:[0,1,2,3] row_mask:0xc bank_mask:0xf
	v_fmac_f32_dpp v124, v111, v68 row_newbcast:4 row_mask:0xf bank_mask:0xf
	v_fmac_f32_dpp v125, v111, v69 row_newbcast:5 row_mask:0xf bank_mask:0xf
	v_mfma_f32_32x32x2_f32 v[32:47], v138, v109, v[64:79]
	v_fmac_f32_dpp v124, v111, v70 row_newbcast:6 row_mask:0xf bank_mask:0xf
	v_fmac_f32_dpp v125, v111, v71 row_newbcast:7 row_mask:0xf bank_mask:0xf
	v_fmac_f32_dpp v124, v111, v72 row_newbcast:8 row_mask:0xf bank_mask:0xf
	v_fmac_f32_dpp v125, v111, v73 row_newbcast:9 row_mask:0xf bank_mask:0xf
	v_fmac_f32_dpp v124, v111, v74 row_newbcast:10 row_mask:0xf bank_mask:0xf
	v_fmac_f32_dpp v125, v111, v75 row_newbcast:11 row_mask:0xf bank_mask:0xf
	v_fmac_f32_dpp v124, v111, v76 row_newbcast:12 row_mask:0xf bank_mask:0xf
	v_fmac_f32_dpp v125, v111, v77 row_newbcast:13 row_mask:0xf bank_mask:0xf
	v_fmac_f32_dpp v124, v111, v78 row_newbcast:14 row_mask:0xf bank_mask:0xf
	v_fmac_f32_dpp v125, v111, v79 row_newbcast:15 row_mask:0xf bank_mask:0xf
	v_fmac_f32_dpp v124, v113, v80 row_newbcast:0 row_mask:0xf bank_mask:0xf
	v_fmac_f32_dpp v125, v113, v81 row_newbcast:1 row_mask:0xf bank_mask:0xf
	v_fmac_f32_dpp v124, v113, v82 row_newbcast:2 row_mask:0xf bank_mask:0xf
	v_fmac_f32_dpp v125, v113, v83 row_newbcast:3 row_mask:0xf bank_mask:0xf
	v_mfma_f32_32x32x2_f32 v[48:63], v139, v109, v[80:95]
	v_fmac_f32_dpp v124, v113, v84 row_newbcast:4 row_mask:0xf bank_mask:0xf
	v_fmac_f32_dpp v125, v113, v85 row_newbcast:5 row_mask:0xf bank_mask:0xf
	v_fmac_f32_dpp v124, v113, v86 row_newbcast:6 row_mask:0xf bank_mask:0xf
	v_fmac_f32_dpp v125, v113, v87 row_newbcast:7 row_mask:0xf bank_mask:0xf
	v_fmac_f32_dpp v124, v113, v88 row_newbcast:8 row_mask:0xf bank_mask:0xf
	v_fmac_f32_dpp v125, v113, v89 row_newbcast:9 row_mask:0xf bank_mask:0xf
	v_fmac_f32_dpp v124, v113, v90 row_newbcast:10 row_mask:0xf bank_mask:0xf
	v_fmac_f32_dpp v125, v113, v91 row_newbcast:11 row_mask:0xf bank_mask:0xf
	v_fmac_f32_dpp v124, v113, v92 row_newbcast:12 row_mask:0xf bank_mask:0xf
	v_fmac_f32_dpp v125, v113, v93 row_newbcast:13 row_mask:0xf bank_mask:0xf
	v_fmac_f32_dpp v124, v113, v94 row_newbcast:14 row_mask:0xf bank_mask:0xf
	v_fmac_f32_dpp v125, v113, v95 row_newbcast:15 row_mask:0xf bank_mask:0xf
	v_add_f32_e32 v130, v124, v125
	v_mul_f32_dpp v124, v115, v32 row_newbcast:0 row_mask:0xf bank_mask:0xf
	v_mul_f32_dpp v125, v115, v33 row_newbcast:1 row_mask:0xf bank_mask:0xf
	v_fmac_f32_dpp v124, v115, v34 row_newbcast:2 row_mask:0xf bank_mask:0xf
	v_fmac_f32_dpp v125, v115, v35 row_newbcast:3 row_mask:0xf bank_mask:0xf
	v_fmac_f32_dpp v124, v115, v36 row_newbcast:4 row_mask:0xf bank_mask:0xf
	v_fmac_f32_dpp v125, v115, v37 row_newbcast:5 row_mask:0xf bank_mask:0xf
	v_fmac_f32_dpp v124, v115, v38 row_newbcast:6 row_mask:0xf bank_mask:0xf
	v_fmac_f32_dpp v125, v115, v39 row_newbcast:7 row_mask:0xf bank_mask:0xf
	v_fmac_f32_dpp v124, v115, v40 row_newbcast:8 row_mask:0xf bank_mask:0xf
	v_fmac_f32_dpp v125, v115, v41 row_newbcast:9 row_mask:0xf bank_mask:0xf
	v_fmac_f32_dpp v124, v115, v42 row_newbcast:10 row_mask:0xf bank_mask:0xf
	v_fmac_f32_dpp v125, v115, v43 row_newbcast:11 row_mask:0xf bank_mask:0xf
	v_fmac_f32_dpp v124, v115, v44 row_newbcast:12 row_mask:0xf bank_mask:0xf
	v_fmac_f32_dpp v125, v115, v45 row_newbcast:13 row_mask:0xf bank_mask:0xf
	v_fmac_f32_dpp v124, v115, v46 row_newbcast:14 row_mask:0xf bank_mask:0xf
	v_fmac_f32_dpp v125, v115, v47 row_newbcast:15 row_mask:0xf bank_mask:0xf
	v_fmac_f32_dpp v124, v117, v48 row_newbcast:0 row_mask:0xf bank_mask:0xf
	v_fmac_f32_dpp v125, v117, v49 row_newbcast:1 row_mask:0xf bank_mask:0xf
	v_fmac_f32_dpp v124, v117, v50 row_newbcast:2 row_mask:0xf bank_mask:0xf
	v_fmac_f32_dpp v125, v117, v51 row_newbcast:3 row_mask:0xf bank_mask:0xf
	v_fmac_f32_dpp v124, v117, v52 row_newbcast:4 row_mask:0xf bank_mask:0xf
	v_fmac_f32_dpp v125, v117, v53 row_newbcast:5 row_mask:0xf bank_mask:0xf
	v_fmac_f32_dpp v124, v117, v54 row_newbcast:6 row_mask:0xf bank_mask:0xf
	v_fmac_f32_dpp v125, v117, v55 row_newbcast:7 row_mask:0xf bank_mask:0xf
	v_fmac_f32_dpp v124, v117, v56 row_newbcast:8 row_mask:0xf bank_mask:0xf
	v_fmac_f32_dpp v125, v117, v57 row_newbcast:9 row_mask:0xf bank_mask:0xf
	v_fmac_f32_dpp v124, v117, v58 row_newbcast:10 row_mask:0xf bank_mask:0xf
	v_fmac_f32_dpp v125, v117, v59 row_newbcast:11 row_mask:0xf bank_mask:0xf
	v_fmac_f32_dpp v124, v117, v60 row_newbcast:12 row_mask:0xf bank_mask:0xf
	v_fmac_f32_dpp v125, v117, v61 row_newbcast:13 row_mask:0xf bank_mask:0xf
	v_fmac_f32_dpp v124, v117, v62 row_newbcast:14 row_mask:0xf bank_mask:0xf
	v_fmac_f32_dpp v125, v117, v63 row_newbcast:15 row_mask:0xf bank_mask:0xf
	v_add_f32_e32 v131, v124, v125
	v_mul_f32_dpp v32, v118, v32 row_newbcast:0 row_mask:0xf bank_mask:0xf
	v_mul_f32_dpp v33, v118, v33 row_newbcast:1 row_mask:0xf bank_mask:0xf
	v_mul_f32_dpp v34, v118, v34 row_newbcast:2 row_mask:0xf bank_mask:0xf
	v_mul_f32_dpp v35, v118, v35 row_newbcast:3 row_mask:0xf bank_mask:0xf
	v_mul_f32_dpp v36, v118, v36 row_newbcast:4 row_mask:0xf bank_mask:0xf
	v_mul_f32_dpp v37, v118, v37 row_newbcast:5 row_mask:0xf bank_mask:0xf
	v_mul_f32_dpp v38, v118, v38 row_newbcast:6 row_mask:0xf bank_mask:0xf
	v_mul_f32_dpp v39, v118, v39 row_newbcast:7 row_mask:0xf bank_mask:0xf
	v_mul_f32_dpp v40, v118, v40 row_newbcast:8 row_mask:0xf bank_mask:0xf
	v_mul_f32_dpp v41, v118, v41 row_newbcast:9 row_mask:0xf bank_mask:0xf
	v_mul_f32_dpp v42, v118, v42 row_newbcast:10 row_mask:0xf bank_mask:0xf
	v_mul_f32_dpp v43, v118, v43 row_newbcast:11 row_mask:0xf bank_mask:0xf
	v_mul_f32_dpp v44, v118, v44 row_newbcast:12 row_mask:0xf bank_mask:0xf
	v_mul_f32_dpp v45, v118, v45 row_newbcast:13 row_mask:0xf bank_mask:0xf
	v_mul_f32_dpp v46, v118, v46 row_newbcast:14 row_mask:0xf bank_mask:0xf
	v_mul_f32_dpp v47, v118, v47 row_newbcast:15 row_mask:0xf bank_mask:0xf
	v_mul_f32_dpp v48, v119, v48 row_newbcast:0 row_mask:0xf bank_mask:0xf
	v_mul_f32_dpp v49, v119, v49 row_newbcast:1 row_mask:0xf bank_mask:0xf
	v_mul_f32_dpp v50, v119, v50 row_newbcast:2 row_mask:0xf bank_mask:0xf
	v_mul_f32_dpp v51, v119, v51 row_newbcast:3 row_mask:0xf bank_mask:0xf
	v_mul_f32_dpp v52, v119, v52 row_newbcast:4 row_mask:0xf bank_mask:0xf
	v_mul_f32_dpp v53, v119, v53 row_newbcast:5 row_mask:0xf bank_mask:0xf
	v_mul_f32_dpp v54, v119, v54 row_newbcast:6 row_mask:0xf bank_mask:0xf
	v_mul_f32_dpp v55, v119, v55 row_newbcast:7 row_mask:0xf bank_mask:0xf
	v_mul_f32_dpp v56, v119, v56 row_newbcast:8 row_mask:0xf bank_mask:0xf
	v_mul_f32_dpp v57, v119, v57 row_newbcast:9 row_mask:0xf bank_mask:0xf
	v_mul_f32_dpp v58, v119, v58 row_newbcast:10 row_mask:0xf bank_mask:0xf
	v_mul_f32_dpp v59, v119, v59 row_newbcast:11 row_mask:0xf bank_mask:0xf
	v_mul_f32_dpp v60, v119, v60 row_newbcast:12 row_mask:0xf bank_mask:0xf
	v_mul_f32_dpp v61, v119, v61 row_newbcast:13 row_mask:0xf bank_mask:0xf
	v_mul_f32_dpp v62, v119, v62 row_newbcast:14 row_mask:0xf bank_mask:0xf
	v_mul_f32_dpp v63, v119, v63 row_newbcast:15 row_mask:0xf bank_mask:0xf
	s_waitcnt lgkmcnt(0)
	ds_read2st64_b32 v[104:105], v14 offset0:55 offset1:58
	ds_read2st64_b32 v[106:107], v17 offset0:55 offset1:58
	ds_read_b32 v138, v15 offset:13824
	ds_read_b32 v139, v15 offset:13952
	ds_read_b32 v109, v16 offset:13824
	v_mul_f32_dpp v120, v100, v32 row_newbcast:0 row_mask:0xf bank_mask:0xf
	v_mul_f32_dpp v121, v100, v33 row_newbcast:1 row_mask:0xf bank_mask:0xf
	v_fmac_f32_dpp v120, v100, v34 row_newbcast:2 row_mask:0xf bank_mask:0xf
	v_fmac_f32_dpp v121, v100, v35 row_newbcast:3 row_mask:0xf bank_mask:0xf
	v_fmac_f32_dpp v120, v100, v36 row_newbcast:4 row_mask:0xf bank_mask:0xf
	v_fmac_f32_dpp v121, v100, v37 row_newbcast:5 row_mask:0xf bank_mask:0xf
	v_fmac_f32_dpp v120, v100, v38 row_newbcast:6 row_mask:0xf bank_mask:0xf
	v_fmac_f32_dpp v121, v100, v39 row_newbcast:7 row_mask:0xf bank_mask:0xf
	v_fmac_f32_dpp v120, v100, v40 row_newbcast:8 row_mask:0xf bank_mask:0xf
	v_fmac_f32_dpp v121, v100, v41 row_newbcast:9 row_mask:0xf bank_mask:0xf
	v_fmac_f32_dpp v120, v100, v42 row_newbcast:10 row_mask:0xf bank_mask:0xf
	v_fmac_f32_dpp v121, v100, v43 row_newbcast:11 row_mask:0xf bank_mask:0xf
	v_fmac_f32_dpp v120, v100, v44 row_newbcast:12 row_mask:0xf bank_mask:0xf
	v_fmac_f32_dpp v121, v100, v45 row_newbcast:13 row_mask:0xf bank_mask:0xf
	v_fmac_f32_dpp v120, v100, v46 row_newbcast:14 row_mask:0xf bank_mask:0xf
	v_fmac_f32_dpp v121, v100, v47 row_newbcast:15 row_mask:0xf bank_mask:0xf
	v_fmac_f32_dpp v120, v102, v48 row_newbcast:0 row_mask:0xf bank_mask:0xf
	v_fmac_f32_dpp v121, v102, v49 row_newbcast:1 row_mask:0xf bank_mask:0xf
	v_fmac_f32_dpp v120, v102, v50 row_newbcast:2 row_mask:0xf bank_mask:0xf
	v_fmac_f32_dpp v121, v102, v51 row_newbcast:3 row_mask:0xf bank_mask:0xf
	v_fmac_f32_dpp v120, v102, v52 row_newbcast:4 row_mask:0xf bank_mask:0xf
	v_fmac_f32_dpp v121, v102, v53 row_newbcast:5 row_mask:0xf bank_mask:0xf
	v_fmac_f32_dpp v120, v102, v54 row_newbcast:6 row_mask:0xf bank_mask:0xf
	v_fmac_f32_dpp v121, v102, v55 row_newbcast:7 row_mask:0xf bank_mask:0xf
	v_fmac_f32_dpp v120, v102, v56 row_newbcast:8 row_mask:0xf bank_mask:0xf
	v_fmac_f32_dpp v121, v102, v57 row_newbcast:9 row_mask:0xf bank_mask:0xf
	v_fmac_f32_dpp v120, v102, v58 row_newbcast:10 row_mask:0xf bank_mask:0xf
	v_fmac_f32_dpp v121, v102, v59 row_newbcast:11 row_mask:0xf bank_mask:0xf
	v_fmac_f32_dpp v120, v102, v60 row_newbcast:12 row_mask:0xf bank_mask:0xf
	v_fmac_f32_dpp v121, v102, v61 row_newbcast:13 row_mask:0xf bank_mask:0xf
	v_fmac_f32_dpp v120, v102, v62 row_newbcast:14 row_mask:0xf bank_mask:0xf
	v_fmac_f32_dpp v121, v102, v63 row_newbcast:15 row_mask:0xf bank_mask:0xf
	v_add_f32_e32 v128, v120, v121
	s_nop 1
	v_permlane32_swap_b32 v129, v128
	s_nop 1
	v_add_f32_dpp v108, -v129, -v128 quad_perm:[0,1,2,3] row_mask:0xc bank_mask:0xf
	s_nop 1
	v_mfma_f32_32x32x2_f32 v[64:79], v136, v108, v[32:47]
	s_nop 15
	v_mfma_f32_32x32x2_f32 v[80:95], v137, v108, v[48:63]
	s_nop 1
	v_permlane32_swap_b32 v130, v131
	v_add_f32_e32 v133, v130, v131
	v_cvt_pk_bf16_f32 v133, v133, v133
	global_store_short v13, v133, s[16:17]
	s_add_u32 s16, s16, s20
	s_addc_u32 s17, s17, s21
	s_waitcnt lgkmcnt(0)
	ds_read2st64_b32 v[110:111], v14 offset0:61 offset1:64
	ds_read2st64_b32 v[112:113], v17 offset0:61 offset1:64
	ds_read_b32 v136, v15 offset:15360
	ds_read_b32 v137, v15 offset:15488
	ds_read_b32 v108, v16 offset:15360
	v_mul_f32_dpp v120, v104, v64 row_newbcast:0 row_mask:0xf bank_mask:0xf
	v_mul_f32_dpp v121, v104, v65 row_newbcast:1 row_mask:0xf bank_mask:0xf
	v_fmac_f32_dpp v120, v104, v66 row_newbcast:2 row_mask:0xf bank_mask:0xf
	v_fmac_f32_dpp v121, v104, v67 row_newbcast:3 row_mask:0xf bank_mask:0xf
	v_fmac_f32_dpp v120, v104, v68 row_newbcast:4 row_mask:0xf bank_mask:0xf
	v_fmac_f32_dpp v121, v104, v69 row_newbcast:5 row_mask:0xf bank_mask:0xf
	v_fmac_f32_dpp v120, v104, v70 row_newbcast:6 row_mask:0xf bank_mask:0xf
	v_fmac_f32_dpp v121, v104, v71 row_newbcast:7 row_mask:0xf bank_mask:0xf
	v_fmac_f32_dpp v120, v104, v72 row_newbcast:8 row_mask:0xf bank_mask:0xf
	v_fmac_f32_dpp v121, v104, v73 row_newbcast:9 row_mask:0xf bank_mask:0xf
	v_fmac_f32_dpp v120, v104, v74 row_newbcast:10 row_mask:0xf bank_mask:0xf
	v_fmac_f32_dpp v121, v104, v75 row_newbcast:11 row_mask:0xf bank_mask:0xf
	v_fmac_f32_dpp v120, v104, v76 row_newbcast:12 row_mask:0xf bank_mask:0xf
	v_fmac_f32_dpp v121, v104, v77 row_newbcast:13 row_mask:0xf bank_mask:0xf
	v_fmac_f32_dpp v120, v104, v78 row_newbcast:14 row_mask:0xf bank_mask:0xf
	v_fmac_f32_dpp v121, v104, v79 row_newbcast:15 row_mask:0xf bank_mask:0xf
	v_fmac_f32_dpp v120, v106, v80 row_newbcast:0 row_mask:0xf bank_mask:0xf
	v_fmac_f32_dpp v121, v106, v81 row_newbcast:1 row_mask:0xf bank_mask:0xf
	v_fmac_f32_dpp v120, v106, v82 row_newbcast:2 row_mask:0xf bank_mask:0xf
	v_fmac_f32_dpp v121, v106, v83 row_newbcast:3 row_mask:0xf bank_mask:0xf
	v_fmac_f32_dpp v120, v106, v84 row_newbcast:4 row_mask:0xf bank_mask:0xf
	v_fmac_f32_dpp v121, v106, v85 row_newbcast:5 row_mask:0xf bank_mask:0xf
	v_fmac_f32_dpp v120, v106, v86 row_newbcast:6 row_mask:0xf bank_mask:0xf
	v_fmac_f32_dpp v121, v106, v87 row_newbcast:7 row_mask:0xf bank_mask:0xf
	v_fmac_f32_dpp v120, v106, v88 row_newbcast:8 row_mask:0xf bank_mask:0xf
	v_fmac_f32_dpp v121, v106, v89 row_newbcast:9 row_mask:0xf bank_mask:0xf
	v_fmac_f32_dpp v120, v106, v90 row_newbcast:10 row_mask:0xf bank_mask:0xf
	v_fmac_f32_dpp v121, v106, v91 row_newbcast:11 row_mask:0xf bank_mask:0xf
	v_fmac_f32_dpp v120, v106, v92 row_newbcast:12 row_mask:0xf bank_mask:0xf
	v_fmac_f32_dpp v121, v106, v93 row_newbcast:13 row_mask:0xf bank_mask:0xf
	v_fmac_f32_dpp v120, v106, v94 row_newbcast:14 row_mask:0xf bank_mask:0xf
	v_fmac_f32_dpp v121, v106, v95 row_newbcast:15 row_mask:0xf bank_mask:0xf
	v_add_f32_e32 v128, v120, v121
	v_mul_f32_dpp v124, v101, v64 row_newbcast:0 row_mask:0xf bank_mask:0xf
	v_mul_f32_dpp v125, v101, v65 row_newbcast:1 row_mask:0xf bank_mask:0xf
	v_permlane32_swap_b32 v129, v128
	v_fmac_f32_dpp v124, v101, v66 row_newbcast:2 row_mask:0xf bank_mask:0xf
	v_fmac_f32_dpp v125, v101, v67 row_newbcast:3 row_mask:0xf bank_mask:0xf
	v_add_f32_dpp v109, -v129, -v128 quad_perm:[0,1,2,3] row_mask:0xc bank_mask:0xf
	v_fmac_f32_dpp v124, v101, v68 row_newbcast:4 row_mask:0xf bank_mask:0xf
	v_fmac_f32_dpp v125, v101, v69 row_newbcast:5 row_mask:0xf bank_mask:0xf
	v_mfma_f32_32x32x2_f32 v[32:47], v138, v109, v[64:79]
	v_fmac_f32_dpp v124, v101, v70 row_newbcast:6 row_mask:0xf bank_mask:0xf
	v_fmac_f32_dpp v125, v101, v71 row_newbcast:7 row_mask:0xf bank_mask:0xf
	v_fmac_f32_dpp v124, v101, v72 row_newbcast:8 row_mask:0xf bank_mask:0xf
	v_fmac_f32_dpp v125, v101, v73 row_newbcast:9 row_mask:0xf bank_mask:0xf
	v_fmac_f32_dpp v124, v101, v74 row_newbcast:10 row_mask:0xf bank_mask:0xf
	v_fmac_f32_dpp v125, v101, v75 row_newbcast:11 row_mask:0xf bank_mask:0xf
	v_fmac_f32_dpp v124, v101, v76 row_newbcast:12 row_mask:0xf bank_mask:0xf
	v_fmac_f32_dpp v125, v101, v77 row_newbcast:13 row_mask:0xf bank_mask:0xf
	v_fmac_f32_dpp v124, v101, v78 row_newbcast:14 row_mask:0xf bank_mask:0xf
	v_fmac_f32_dpp v125, v101, v79 row_newbcast:15 row_mask:0xf bank_mask:0xf
	v_fmac_f32_dpp v124, v103, v80 row_newbcast:0 row_mask:0xf bank_mask:0xf
	v_fmac_f32_dpp v125, v103, v81 row_newbcast:1 row_mask:0xf bank_mask:0xf
	v_fmac_f32_dpp v124, v103, v82 row_newbcast:2 row_mask:0xf bank_mask:0xf
	v_fmac_f32_dpp v125, v103, v83 row_newbcast:3 row_mask:0xf bank_mask:0xf
	v_mfma_f32_32x32x2_f32 v[48:63], v139, v109, v[80:95]
	v_fmac_f32_dpp v124, v103, v84 row_newbcast:4 row_mask:0xf bank_mask:0xf
	v_fmac_f32_dpp v125, v103, v85 row_newbcast:5 row_mask:0xf bank_mask:0xf
	v_fmac_f32_dpp v124, v103, v86 row_newbcast:6 row_mask:0xf bank_mask:0xf
	v_fmac_f32_dpp v125, v103, v87 row_newbcast:7 row_mask:0xf bank_mask:0xf
	v_fmac_f32_dpp v124, v103, v88 row_newbcast:8 row_mask:0xf bank_mask:0xf
	v_fmac_f32_dpp v125, v103, v89 row_newbcast:9 row_mask:0xf bank_mask:0xf
	v_fmac_f32_dpp v124, v103, v90 row_newbcast:10 row_mask:0xf bank_mask:0xf
	v_fmac_f32_dpp v125, v103, v91 row_newbcast:11 row_mask:0xf bank_mask:0xf
	v_fmac_f32_dpp v124, v103, v92 row_newbcast:12 row_mask:0xf bank_mask:0xf
	v_fmac_f32_dpp v125, v103, v93 row_newbcast:13 row_mask:0xf bank_mask:0xf
	v_fmac_f32_dpp v124, v103, v94 row_newbcast:14 row_mask:0xf bank_mask:0xf
	v_fmac_f32_dpp v125, v103, v95 row_newbcast:15 row_mask:0xf bank_mask:0xf
	v_add_f32_e32 v130, v124, v125
	s_waitcnt lgkmcnt(0)
	ds_read2st64_b32 v[114:115], v14 offset0:67 offset1:70
	ds_read2st64_b32 v[116:117], v17 offset0:67 offset1:70
	ds_read_b32 v138, v15 offset:16896
	ds_read_b32 v139, v15 offset:17024
	ds_read_b32 v109, v16 offset:16896
	v_mul_f32_dpp v120, v110, v32 row_newbcast:0 row_mask:0xf bank_mask:0xf
	v_mul_f32_dpp v121, v110, v33 row_newbcast:1 row_mask:0xf bank_mask:0xf
	v_fmac_f32_dpp v120, v110, v34 row_newbcast:2 row_mask:0xf bank_mask:0xf
	v_fmac_f32_dpp v121, v110, v35 row_newbcast:3 row_mask:0xf bank_mask:0xf
	v_fmac_f32_dpp v120, v110, v36 row_newbcast:4 row_mask:0xf bank_mask:0xf
	v_fmac_f32_dpp v121, v110, v37 row_newbcast:5 row_mask:0xf bank_mask:0xf
	v_fmac_f32_dpp v120, v110, v38 row_newbcast:6 row_mask:0xf bank_mask:0xf
	v_fmac_f32_dpp v121, v110, v39 row_newbcast:7 row_mask:0xf bank_mask:0xf
	v_fmac_f32_dpp v120, v110, v40 row_newbcast:8 row_mask:0xf bank_mask:0xf
	v_fmac_f32_dpp v121, v110, v41 row_newbcast:9 row_mask:0xf bank_mask:0xf
	v_fmac_f32_dpp v120, v110, v42 row_newbcast:10 row_mask:0xf bank_mask:0xf
	v_fmac_f32_dpp v121, v110, v43 row_newbcast:11 row_mask:0xf bank_mask:0xf
	v_fmac_f32_dpp v120, v110, v44 row_newbcast:12 row_mask:0xf bank_mask:0xf
	v_fmac_f32_dpp v121, v110, v45 row_newbcast:13 row_mask:0xf bank_mask:0xf
	v_fmac_f32_dpp v120, v110, v46 row_newbcast:14 row_mask:0xf bank_mask:0xf
	v_fmac_f32_dpp v121, v110, v47 row_newbcast:15 row_mask:0xf bank_mask:0xf
	v_fmac_f32_dpp v120, v112, v48 row_newbcast:0 row_mask:0xf bank_mask:0xf
	v_fmac_f32_dpp v121, v112, v49 row_newbcast:1 row_mask:0xf bank_mask:0xf
	v_fmac_f32_dpp v120, v112, v50 row_newbcast:2 row_mask:0xf bank_mask:0xf
	v_fmac_f32_dpp v121, v112, v51 row_newbcast:3 row_mask:0xf bank_mask:0xf
	v_fmac_f32_dpp v120, v112, v52 row_newbcast:4 row_mask:0xf bank_mask:0xf
	v_fmac_f32_dpp v121, v112, v53 row_newbcast:5 row_mask:0xf bank_mask:0xf
	v_fmac_f32_dpp v120, v112, v54 row_newbcast:6 row_mask:0xf bank_mask:0xf
	v_fmac_f32_dpp v121, v112, v55 row_newbcast:7 row_mask:0xf bank_mask:0xf
	v_fmac_f32_dpp v120, v112, v56 row_newbcast:8 row_mask:0xf bank_mask:0xf
	v_fmac_f32_dpp v121, v112, v57 row_newbcast:9 row_mask:0xf bank_mask:0xf
	v_fmac_f32_dpp v120, v112, v58 row_newbcast:10 row_mask:0xf bank_mask:0xf
	v_fmac_f32_dpp v121, v112, v59 row_newbcast:11 row_mask:0xf bank_mask:0xf
	v_fmac_f32_dpp v120, v112, v60 row_newbcast:12 row_mask:0xf bank_mask:0xf
	v_fmac_f32_dpp v121, v112, v61 row_newbcast:13 row_mask:0xf bank_mask:0xf
	v_fmac_f32_dpp v120, v112, v62 row_newbcast:14 row_mask:0xf bank_mask:0xf
	v_fmac_f32_dpp v121, v112, v63 row_newbcast:15 row_mask:0xf bank_mask:0xf
	v_add_f32_e32 v128, v120, v121
	v_mul_f32_dpp v124, v105, v32 row_newbcast:0 row_mask:0xf bank_mask:0xf
	v_mul_f32_dpp v125, v105, v33 row_newbcast:1 row_mask:0xf bank_mask:0xf
	v_permlane32_swap_b32 v129, v128
	v_fmac_f32_dpp v124, v105, v34 row_newbcast:2 row_mask:0xf bank_mask:0xf
	v_fmac_f32_dpp v125, v105, v35 row_newbcast:3 row_mask:0xf bank_mask:0xf
	v_add_f32_dpp v108, -v129, -v128 quad_perm:[0,1,2,3] row_mask:0xc bank_mask:0xf
	v_fmac_f32_dpp v124, v105, v36 row_newbcast:4 row_mask:0xf bank_mask:0xf
	v_fmac_f32_dpp v125, v105, v37 row_newbcast:5 row_mask:0xf bank_mask:0xf
	v_mfma_f32_32x32x2_f32 v[64:79], v136, v108, v[32:47]
	v_fmac_f32_dpp v124, v105, v38 row_newbcast:6 row_mask:0xf bank_mask:0xf
	v_fmac_f32_dpp v125, v105, v39 row_newbcast:7 row_mask:0xf bank_mask:0xf
	v_fmac_f32_dpp v124, v105, v40 row_newbcast:8 row_mask:0xf bank_mask:0xf
	v_fmac_f32_dpp v125, v105, v41 row_newbcast:9 row_mask:0xf bank_mask:0xf
	v_fmac_f32_dpp v124, v105, v42 row_newbcast:10 row_mask:0xf bank_mask:0xf
	v_fmac_f32_dpp v125, v105, v43 row_newbcast:11 row_mask:0xf bank_mask:0xf
	v_fmac_f32_dpp v124, v105, v44 row_newbcast:12 row_mask:0xf bank_mask:0xf
	v_fmac_f32_dpp v125, v105, v45 row_newbcast:13 row_mask:0xf bank_mask:0xf
	v_fmac_f32_dpp v124, v105, v46 row_newbcast:14 row_mask:0xf bank_mask:0xf
	v_fmac_f32_dpp v125, v105, v47 row_newbcast:15 row_mask:0xf bank_mask:0xf
	v_fmac_f32_dpp v124, v107, v48 row_newbcast:0 row_mask:0xf bank_mask:0xf
	v_fmac_f32_dpp v125, v107, v49 row_newbcast:1 row_mask:0xf bank_mask:0xf
	v_fmac_f32_dpp v124, v107, v50 row_newbcast:2 row_mask:0xf bank_mask:0xf
	v_fmac_f32_dpp v125, v107, v51 row_newbcast:3 row_mask:0xf bank_mask:0xf
	v_mfma_f32_32x32x2_f32 v[80:95], v137, v108, v[48:63]
	v_fmac_f32_dpp v124, v107, v52 row_newbcast:4 row_mask:0xf bank_mask:0xf
	v_fmac_f32_dpp v125, v107, v53 row_newbcast:5 row_mask:0xf bank_mask:0xf
	v_fmac_f32_dpp v124, v107, v54 row_newbcast:6 row_mask:0xf bank_mask:0xf
	v_fmac_f32_dpp v125, v107, v55 row_newbcast:7 row_mask:0xf bank_mask:0xf
	v_fmac_f32_dpp v124, v107, v56 row_newbcast:8 row_mask:0xf bank_mask:0xf
	v_fmac_f32_dpp v125, v107, v57 row_newbcast:9 row_mask:0xf bank_mask:0xf
	v_fmac_f32_dpp v124, v107, v58 row_newbcast:10 row_mask:0xf bank_mask:0xf
	v_fmac_f32_dpp v125, v107, v59 row_newbcast:11 row_mask:0xf bank_mask:0xf
	v_fmac_f32_dpp v124, v107, v60 row_newbcast:12 row_mask:0xf bank_mask:0xf
	v_fmac_f32_dpp v125, v107, v61 row_newbcast:13 row_mask:0xf bank_mask:0xf
	v_fmac_f32_dpp v124, v107, v62 row_newbcast:14 row_mask:0xf bank_mask:0xf
	v_fmac_f32_dpp v125, v107, v63 row_newbcast:15 row_mask:0xf bank_mask:0xf
	v_add_f32_e32 v131, v124, v125
	s_nop 1
	v_permlane32_swap_b32 v130, v131
	v_add_f32_e32 v133, v130, v131
	v_cvt_pk_bf16_f32 v133, v133, v133
	global_store_short v13, v133, s[16:17]
	s_add_u32 s16, s16, s20
	s_addc_u32 s17, s17, s21
	s_waitcnt lgkmcnt(0)
	ds_read2st64_b32 v[100:101], v14 offset0:73 offset1:76
	ds_read2st64_b32 v[102:103], v17 offset0:73 offset1:76
	ds_read_b32 v136, v15 offset:18432
	ds_read_b32 v137, v15 offset:18560
	ds_read_b32 v108, v16 offset:18432
	v_mul_f32_dpp v120, v114, v64 row_newbcast:0 row_mask:0xf bank_mask:0xf
	v_mul_f32_dpp v121, v114, v65 row_newbcast:1 row_mask:0xf bank_mask:0xf
	v_fmac_f32_dpp v120, v114, v66 row_newbcast:2 row_mask:0xf bank_mask:0xf
	v_fmac_f32_dpp v121, v114, v67 row_newbcast:3 row_mask:0xf bank_mask:0xf
	v_fmac_f32_dpp v120, v114, v68 row_newbcast:4 row_mask:0xf bank_mask:0xf
	v_fmac_f32_dpp v121, v114, v69 row_newbcast:5 row_mask:0xf bank_mask:0xf
	v_fmac_f32_dpp v120, v114, v70 row_newbcast:6 row_mask:0xf bank_mask:0xf
	v_fmac_f32_dpp v121, v114, v71 row_newbcast:7 row_mask:0xf bank_mask:0xf
	v_fmac_f32_dpp v120, v114, v72 row_newbcast:8 row_mask:0xf bank_mask:0xf
	v_fmac_f32_dpp v121, v114, v73 row_newbcast:9 row_mask:0xf bank_mask:0xf
	v_fmac_f32_dpp v120, v114, v74 row_newbcast:10 row_mask:0xf bank_mask:0xf
	v_fmac_f32_dpp v121, v114, v75 row_newbcast:11 row_mask:0xf bank_mask:0xf
	v_fmac_f32_dpp v120, v114, v76 row_newbcast:12 row_mask:0xf bank_mask:0xf
	v_fmac_f32_dpp v121, v114, v77 row_newbcast:13 row_mask:0xf bank_mask:0xf
	v_fmac_f32_dpp v120, v114, v78 row_newbcast:14 row_mask:0xf bank_mask:0xf
	v_fmac_f32_dpp v121, v114, v79 row_newbcast:15 row_mask:0xf bank_mask:0xf
	v_fmac_f32_dpp v120, v116, v80 row_newbcast:0 row_mask:0xf bank_mask:0xf
	v_fmac_f32_dpp v121, v116, v81 row_newbcast:1 row_mask:0xf bank_mask:0xf
	v_fmac_f32_dpp v120, v116, v82 row_newbcast:2 row_mask:0xf bank_mask:0xf
	v_fmac_f32_dpp v121, v116, v83 row_newbcast:3 row_mask:0xf bank_mask:0xf
	v_fmac_f32_dpp v120, v116, v84 row_newbcast:4 row_mask:0xf bank_mask:0xf
	v_fmac_f32_dpp v121, v116, v85 row_newbcast:5 row_mask:0xf bank_mask:0xf
	v_fmac_f32_dpp v120, v116, v86 row_newbcast:6 row_mask:0xf bank_mask:0xf
	v_fmac_f32_dpp v121, v116, v87 row_newbcast:7 row_mask:0xf bank_mask:0xf
	v_fmac_f32_dpp v120, v116, v88 row_newbcast:8 row_mask:0xf bank_mask:0xf
	v_fmac_f32_dpp v121, v116, v89 row_newbcast:9 row_mask:0xf bank_mask:0xf
	v_fmac_f32_dpp v120, v116, v90 row_newbcast:10 row_mask:0xf bank_mask:0xf
	v_fmac_f32_dpp v121, v116, v91 row_newbcast:11 row_mask:0xf bank_mask:0xf
	v_fmac_f32_dpp v120, v116, v92 row_newbcast:12 row_mask:0xf bank_mask:0xf
	v_fmac_f32_dpp v121, v116, v93 row_newbcast:13 row_mask:0xf bank_mask:0xf
	v_fmac_f32_dpp v120, v116, v94 row_newbcast:14 row_mask:0xf bank_mask:0xf
	v_fmac_f32_dpp v121, v116, v95 row_newbcast:15 row_mask:0xf bank_mask:0xf
	v_add_f32_e32 v128, v120, v121
	v_mul_f32_dpp v124, v111, v64 row_newbcast:0 row_mask:0xf bank_mask:0xf
	v_mul_f32_dpp v125, v111, v65 row_newbcast:1 row_mask:0xf bank_mask:0xf
	v_permlane32_swap_b32 v129, v128
	v_fmac_f32_dpp v124, v111, v66 row_newbcast:2 row_mask:0xf bank_mask:0xf
	v_fmac_f32_dpp v125, v111, v67 row_newbcast:3 row_mask:0xf bank_mask:0xf
	v_add_f32_dpp v109, -v129, -v128 quad_perm:[0,1,2,3] row_mask:0xc bank_mask:0xf
; __device__ void scan_chain(PRef p, int l, int chain, ScanSm* sm) {
;     ...
; #pragma unroll 1
;     for (int c = 0; c < 144; c++) {
;       __syncthreads();
;       const ScanRec* rc0 = &sm->rec[c & 1][0];
;       LDSET(A, rc0)
; #pragma unroll 1
;       for (int i2 = 0; i2 < 8; i2++) {
;         const ScanRec* rcA = rc0 + 2 * i2;
;         const ScanRec* rcC = (i2 < 7) ? rcA + 2 : rcA + 1;
;         LDSET(B, rcA + 1)
;         SCAN_STEP(A, c * 16 + 2 * i2)
;         LDSET(A, rcC)
;         SCAN_STEP(B, c * 16 + 2 * i2 + 1)
;       }
;     }
	v_fmac_f32_dpp v124, v111, v68 row_newbcast:4 row_mask:0xf bank_mask:0xf
	v_fmac_f32_dpp v125, v111, v69 row_newbcast:5 row_mask:0xf bank_mask:0xf
	v_mfma_f32_32x32x2_f32 v[32:47], v138, v109, v[64:79]
	v_fmac_f32_dpp v124, v111, v70 row_newbcast:6 row_mask:0xf bank_mask:0xf
	v_fmac_f32_dpp v125, v111, v71 row_newbcast:7 row_mask:0xf bank_mask:0xf
	v_fmac_f32_dpp v124, v111, v72 row_newbcast:8 row_mask:0xf bank_mask:0xf
	v_fmac_f32_dpp v125, v111, v73 row_newbcast:9 row_mask:0xf bank_mask:0xf
	v_fmac_f32_dpp v124, v111, v74 row_newbcast:10 row_mask:0xf bank_mask:0xf
	v_fmac_f32_dpp v125, v111, v75 row_newbcast:11 row_mask:0xf bank_mask:0xf
	v_fmac_f32_dpp v124, v111, v76 row_newbcast:12 row_mask:0xf bank_mask:0xf
	v_fmac_f32_dpp v125, v111, v77 row_newbcast:13 row_mask:0xf bank_mask:0xf
	v_fmac_f32_dpp v124, v111, v78 row_newbcast:14 row_mask:0xf bank_mask:0xf
	v_fmac_f32_dpp v125, v111, v79 row_newbcast:15 row_mask:0xf bank_mask:0xf
	v_fmac_f32_dpp v124, v113, v80 row_newbcast:0 row_mask:0xf bank_mask:0xf
	v_fmac_f32_dpp v125, v113, v81 row_newbcast:1 row_mask:0xf bank_mask:0xf
	v_fmac_f32_dpp v124, v113, v82 row_newbcast:2 row_mask:0xf bank_mask:0xf
	v_fmac_f32_dpp v125, v113, v83 row_newbcast:3 row_mask:0xf bank_mask:0xf
	v_mfma_f32_32x32x2_f32 v[48:63], v139, v109, v[80:95]
	v_fmac_f32_dpp v124, v113, v84 row_newbcast:4 row_mask:0xf bank_mask:0xf
	v_fmac_f32_dpp v125, v113, v85 row_newbcast:5 row_mask:0xf bank_mask:0xf
	v_fmac_f32_dpp v124, v113, v86 row_newbcast:6 row_mask:0xf bank_mask:0xf
	v_fmac_f32_dpp v125, v113, v87 row_newbcast:7 row_mask:0xf bank_mask:0xf
	v_fmac_f32_dpp v124, v113, v88 row_newbcast:8 row_mask:0xf bank_mask:0xf
	v_fmac_f32_dpp v125, v113, v89 row_newbcast:9 row_mask:0xf bank_mask:0xf
	v_fmac_f32_dpp v124, v113, v90 row_newbcast:10 row_mask:0xf bank_mask:0xf
	v_fmac_f32_dpp v125, v113, v91 row_newbcast:11 row_mask:0xf bank_mask:0xf
	v_fmac_f32_dpp v124, v113, v92 row_newbcast:12 row_mask:0xf bank_mask:0xf
	v_fmac_f32_dpp v125, v113, v93 row_newbcast:13 row_mask:0xf bank_mask:0xf
	v_fmac_f32_dpp v124, v113, v94 row_newbcast:14 row_mask:0xf bank_mask:0xf
	v_fmac_f32_dpp v125, v113, v95 row_newbcast:15 row_mask:0xf bank_mask:0xf
	v_add_f32_e32 v130, v124, v125
	s_waitcnt lgkmcnt(0)
	ds_read2st64_b32 v[104:105], v14 offset0:79 offset1:82
	ds_read2st64_b32 v[106:107], v17 offset0:79 offset1:82
	ds_read_b32 v138, v15 offset:19968
	ds_read_b32 v139, v15 offset:20096
	ds_read_b32 v109, v16 offset:19968
	v_mul_f32_dpp v120, v100, v32 row_newbcast:0 row_mask:0xf bank_mask:0xf
	v_mul_f32_dpp v121, v100, v33 row_newbcast:1 row_mask:0xf bank_mask:0xf
	v_fmac_f32_dpp v120, v100, v34 row_newbcast:2 row_mask:0xf bank_mask:0xf
	v_fmac_f32_dpp v121, v100, v35 row_newbcast:3 row_mask:0xf bank_mask:0xf
	v_fmac_f32_dpp v120, v100, v36 row_newbcast:4 row_mask:0xf bank_mask:0xf
	v_fmac_f32_dpp v121, v100, v37 row_newbcast:5 row_mask:0xf bank_mask:0xf
	v_fmac_f32_dpp v120, v100, v38 row_newbcast:6 row_mask:0xf bank_mask:0xf
	v_fmac_f32_dpp v121, v100, v39 row_newbcast:7 row_mask:0xf bank_mask:0xf
	v_fmac_f32_dpp v120, v100, v40 row_newbcast:8 row_mask:0xf bank_mask:0xf
	v_fmac_f32_dpp v121, v100, v41 row_newbcast:9 row_mask:0xf bank_mask:0xf
	v_fmac_f32_dpp v120, v100, v42 row_newbcast:10 row_mask:0xf bank_mask:0xf
	v_fmac_f32_dpp v121, v100, v43 row_newbcast:11 row_mask:0xf bank_mask:0xf
	v_fmac_f32_dpp v120, v100, v44 row_newbcast:12 row_mask:0xf bank_mask:0xf
	v_fmac_f32_dpp v121, v100, v45 row_newbcast:13 row_mask:0xf bank_mask:0xf
	v_fmac_f32_dpp v120, v100, v46 row_newbcast:14 row_mask:0xf bank_mask:0xf
	v_fmac_f32_dpp v121, v100, v47 row_newbcast:15 row_mask:0xf bank_mask:0xf
	v_fmac_f32_dpp v120, v102, v48 row_newbcast:0 row_mask:0xf bank_mask:0xf
	v_fmac_f32_dpp v121, v102, v49 row_newbcast:1 row_mask:0xf bank_mask:0xf
	v_fmac_f32_dpp v120, v102, v50 row_newbcast:2 row_mask:0xf bank_mask:0xf
	v_fmac_f32_dpp v121, v102, v51 row_newbcast:3 row_mask:0xf bank_mask:0xf
	v_fmac_f32_dpp v120, v102, v52 row_newbcast:4 row_mask:0xf bank_mask:0xf
	v_fmac_f32_dpp v121, v102, v53 row_newbcast:5 row_mask:0xf bank_mask:0xf
	v_fmac_f32_dpp v120, v102, v54 row_newbcast:6 row_mask:0xf bank_mask:0xf
	v_fmac_f32_dpp v121, v102, v55 row_newbcast:7 row_mask:0xf bank_mask:0xf
	v_fmac_f32_dpp v120, v102, v56 row_newbcast:8 row_mask:0xf bank_mask:0xf
	v_fmac_f32_dpp v121, v102, v57 row_newbcast:9 row_mask:0xf bank_mask:0xf
	v_fmac_f32_dpp v120, v102, v58 row_newbcast:10 row_mask:0xf bank_mask:0xf
	v_fmac_f32_dpp v121, v102, v59 row_newbcast:11 row_mask:0xf bank_mask:0xf
	v_fmac_f32_dpp v120, v102, v60 row_newbcast:12 row_mask:0xf bank_mask:0xf
	v_fmac_f32_dpp v121, v102, v61 row_newbcast:13 row_mask:0xf bank_mask:0xf
	v_fmac_f32_dpp v120, v102, v62 row_newbcast:14 row_mask:0xf bank_mask:0xf
	v_fmac_f32_dpp v121, v102, v63 row_newbcast:15 row_mask:0xf bank_mask:0xf
	v_add_f32_e32 v128, v120, v121
	v_mul_f32_dpp v124, v115, v32 row_newbcast:0 row_mask:0xf bank_mask:0xf
	v_mul_f32_dpp v125, v115, v33 row_newbcast:1 row_mask:0xf bank_mask:0xf
	v_permlane32_swap_b32 v129, v128
	v_fmac_f32_dpp v124, v115, v34 row_newbcast:2 row_mask:0xf bank_mask:0xf
	v_fmac_f32_dpp v125, v115, v35 row_newbcast:3 row_mask:0xf bank_mask:0xf
	v_add_f32_dpp v108, -v129, -v128 quad_perm:[0,1,2,3] row_mask:0xc bank_mask:0xf
	v_fmac_f32_dpp v124, v115, v36 row_newbcast:4 row_mask:0xf bank_mask:0xf
	v_fmac_f32_dpp v125, v115, v37 row_newbcast:5 row_mask:0xf bank_mask:0xf
	v_mfma_f32_32x32x2_f32 v[64:79], v136, v108, v[32:47]
	v_fmac_f32_dpp v124, v115, v38 row_newbcast:6 row_mask:0xf bank_mask:0xf
	v_fmac_f32_dpp v125, v115, v39 row_newbcast:7 row_mask:0xf bank_mask:0xf
	v_fmac_f32_dpp v124, v115, v40 row_newbcast:8 row_mask:0xf bank_mask:0xf
	v_fmac_f32_dpp v125, v115, v41 row_newbcast:9 row_mask:0xf bank_mask:0xf
	v_fmac_f32_dpp v124, v115, v42 row_newbcast:10 row_mask:0xf bank_mask:0xf
	v_fmac_f32_dpp v125, v115, v43 row_newbcast:11 row_mask:0xf bank_mask:0xf
	v_fmac_f32_dpp v124, v115, v44 row_newbcast:12 row_mask:0xf bank_mask:0xf
	v_fmac_f32_dpp v125, v115, v45 row_newbcast:13 row_mask:0xf bank_mask:0xf
	v_fmac_f32_dpp v124, v115, v46 row_newbcast:14 row_mask:0xf bank_mask:0xf
	v_fmac_f32_dpp v125, v115, v47 row_newbcast:15 row_mask:0xf bank_mask:0xf
	v_fmac_f32_dpp v124, v117, v48 row_newbcast:0 row_mask:0xf bank_mask:0xf
	v_fmac_f32_dpp v125, v117, v49 row_newbcast:1 row_mask:0xf bank_mask:0xf
	v_fmac_f32_dpp v124, v117, v50 row_newbcast:2 row_mask:0xf bank_mask:0xf
	v_fmac_f32_dpp v125, v117, v51 row_newbcast:3 row_mask:0xf bank_mask:0xf
	v_mfma_f32_32x32x2_f32 v[80:95], v137, v108, v[48:63]
	v_fmac_f32_dpp v124, v117, v52 row_newbcast:4 row_mask:0xf bank_mask:0xf
	v_fmac_f32_dpp v125, v117, v53 row_newbcast:5 row_mask:0xf bank_mask:0xf
	v_fmac_f32_dpp v124, v117, v54 row_newbcast:6 row_mask:0xf bank_mask:0xf
	v_fmac_f32_dpp v125, v117, v55 row_newbcast:7 row_mask:0xf bank_mask:0xf
	v_fmac_f32_dpp v124, v117, v56 row_newbcast:8 row_mask:0xf bank_mask:0xf
	v_fmac_f32_dpp v125, v117, v57 row_newbcast:9 row_mask:0xf bank_mask:0xf
	v_fmac_f32_dpp v124, v117, v58 row_newbcast:10 row_mask:0xf bank_mask:0xf
	v_fmac_f32_dpp v125, v117, v59 row_newbcast:11 row_mask:0xf bank_mask:0xf
	v_fmac_f32_dpp v124, v117, v60 row_newbcast:12 row_mask:0xf bank_mask:0xf
	v_fmac_f32_dpp v125, v117, v61 row_newbcast:13 row_mask:0xf bank_mask:0xf
	v_fmac_f32_dpp v124, v117, v62 row_newbcast:14 row_mask:0xf bank_mask:0xf
	v_fmac_f32_dpp v125, v117, v63 row_newbcast:15 row_mask:0xf bank_mask:0xf
	v_add_f32_e32 v131, v124, v125
	s_nop 1
	v_permlane32_swap_b32 v130, v131
	v_add_f32_e32 v133, v130, v131
	v_cvt_pk_bf16_f32 v133, v133, v133
	global_store_short v13, v133, s[16:17]
	s_add_u32 s16, s16, s20
	s_addc_u32 s17, s17, s21
	s_waitcnt lgkmcnt(0)
	ds_read2st64_b32 v[110:111], v14 offset0:85 offset1:88
	ds_read2st64_b32 v[112:113], v17 offset0:85 offset1:88
	ds_read_b32 v136, v15 offset:21504
	ds_read_b32 v137, v15 offset:21632
	ds_read_b32 v108, v16 offset:21504
	v_mul_f32_dpp v120, v104, v64 row_newbcast:0 row_mask:0xf bank_mask:0xf
	v_mul_f32_dpp v121, v104, v65 row_newbcast:1 row_mask:0xf bank_mask:0xf
	v_fmac_f32_dpp v120, v104, v66 row_newbcast:2 row_mask:0xf bank_mask:0xf
	v_fmac_f32_dpp v121, v104, v67 row_newbcast:3 row_mask:0xf bank_mask:0xf
	v_fmac_f32_dpp v120, v104, v68 row_newbcast:4 row_mask:0xf bank_mask:0xf
	v_fmac_f32_dpp v121, v104, v69 row_newbcast:5 row_mask:0xf bank_mask:0xf
	v_fmac_f32_dpp v120, v104, v70 row_newbcast:6 row_mask:0xf bank_mask:0xf
	v_fmac_f32_dpp v121, v104, v71 row_newbcast:7 row_mask:0xf bank_mask:0xf
	v_fmac_f32_dpp v120, v104, v72 row_newbcast:8 row_mask:0xf bank_mask:0xf
	v_fmac_f32_dpp v121, v104, v73 row_newbcast:9 row_mask:0xf bank_mask:0xf
	v_fmac_f32_dpp v120, v104, v74 row_newbcast:10 row_mask:0xf bank_mask:0xf
	v_fmac_f32_dpp v121, v104, v75 row_newbcast:11 row_mask:0xf bank_mask:0xf
	v_fmac_f32_dpp v120, v104, v76 row_newbcast:12 row_mask:0xf bank_mask:0xf
	v_fmac_f32_dpp v121, v104, v77 row_newbcast:13 row_mask:0xf bank_mask:0xf
	v_fmac_f32_dpp v120, v104, v78 row_newbcast:14 row_mask:0xf bank_mask:0xf
	v_fmac_f32_dpp v121, v104, v79 row_newbcast:15 row_mask:0xf bank_mask:0xf
	v_fmac_f32_dpp v120, v106, v80 row_newbcast:0 row_mask:0xf bank_mask:0xf
	v_fmac_f32_dpp v121, v106, v81 row_newbcast:1 row_mask:0xf bank_mask:0xf
	v_fmac_f32_dpp v120, v106, v82 row_newbcast:2 row_mask:0xf bank_mask:0xf
	v_fmac_f32_dpp v121, v106, v83 row_newbcast:3 row_mask:0xf bank_mask:0xf
	v_fmac_f32_dpp v120, v106, v84 row_newbcast:4 row_mask:0xf bank_mask:0xf
	v_fmac_f32_dpp v121, v106, v85 row_newbcast:5 row_mask:0xf bank_mask:0xf
	v_fmac_f32_dpp v120, v106, v86 row_newbcast:6 row_mask:0xf bank_mask:0xf
	v_fmac_f32_dpp v121, v106, v87 row_newbcast:7 row_mask:0xf bank_mask:0xf
	v_fmac_f32_dpp v120, v106, v88 row_newbcast:8 row_mask:0xf bank_mask:0xf
	v_fmac_f32_dpp v121, v106, v89 row_newbcast:9 row_mask:0xf bank_mask:0xf
	v_fmac_f32_dpp v120, v106, v90 row_newbcast:10 row_mask:0xf bank_mask:0xf
	v_fmac_f32_dpp v121, v106, v91 row_newbcast:11 row_mask:0xf bank_mask:0xf
	v_fmac_f32_dpp v120, v106, v92 row_newbcast:12 row_mask:0xf bank_mask:0xf
	v_fmac_f32_dpp v121, v106, v93 row_newbcast:13 row_mask:0xf bank_mask:0xf
	v_fmac_f32_dpp v120, v106, v94 row_newbcast:14 row_mask:0xf bank_mask:0xf
	v_fmac_f32_dpp v121, v106, v95 row_newbcast:15 row_mask:0xf bank_mask:0xf
	v_add_f32_e32 v128, v120, v121
	v_mul_f32_dpp v124, v101, v64 row_newbcast:0 row_mask:0xf bank_mask:0xf
	v_mul_f32_dpp v125, v101, v65 row_newbcast:1 row_mask:0xf bank_mask:0xf
	v_permlane32_swap_b32 v129, v128
	v_fmac_f32_dpp v124, v101, v66 row_newbcast:2 row_mask:0xf bank_mask:0xf
	v_fmac_f32_dpp v125, v101, v67 row_newbcast:3 row_mask:0xf bank_mask:0xf
	v_add_f32_dpp v109, -v129, -v128 quad_perm:[0,1,2,3] row_mask:0xc bank_mask:0xf
	v_fmac_f32_dpp v124, v101, v68 row_newbcast:4 row_mask:0xf bank_mask:0xf
	v_fmac_f32_dpp v125, v101, v69 row_newbcast:5 row_mask:0xf bank_mask:0xf
	v_mfma_f32_32x32x2_f32 v[32:47], v138, v109, v[64:79]
	v_fmac_f32_dpp v124, v101, v70 row_newbcast:6 row_mask:0xf bank_mask:0xf
	v_fmac_f32_dpp v125, v101, v71 row_newbcast:7 row_mask:0xf bank_mask:0xf
	v_fmac_f32_dpp v124, v101, v72 row_newbcast:8 row_mask:0xf bank_mask:0xf
	v_fmac_f32_dpp v125, v101, v73 row_newbcast:9 row_mask:0xf bank_mask:0xf
	v_fmac_f32_dpp v124, v101, v74 row_newbcast:10 row_mask:0xf bank_mask:0xf
	v_fmac_f32_dpp v125, v101, v75 row_newbcast:11 row_mask:0xf bank_mask:0xf
	v_fmac_f32_dpp v124, v101, v76 row_newbcast:12 row_mask:0xf bank_mask:0xf
	v_fmac_f32_dpp v125, v101, v77 row_newbcast:13 row_mask:0xf bank_mask:0xf
	v_fmac_f32_dpp v124, v101, v78 row_newbcast:14 row_mask:0xf bank_mask:0xf
	v_fmac_f32_dpp v125, v101, v79 row_newbcast:15 row_mask:0xf bank_mask:0xf
	v_fmac_f32_dpp v124, v103, v80 row_newbcast:0 row_mask:0xf bank_mask:0xf
	v_fmac_f32_dpp v125, v103, v81 row_newbcast:1 row_mask:0xf bank_mask:0xf
	v_fmac_f32_dpp v124, v103, v82 row_newbcast:2 row_mask:0xf bank_mask:0xf
	v_fmac_f32_dpp v125, v103, v83 row_newbcast:3 row_mask:0xf bank_mask:0xf
	v_mfma_f32_32x32x2_f32 v[48:63], v139, v109, v[80:95]
	v_fmac_f32_dpp v124, v103, v84 row_newbcast:4 row_mask:0xf bank_mask:0xf
	v_fmac_f32_dpp v125, v103, v85 row_newbcast:5 row_mask:0xf bank_mask:0xf
	v_fmac_f32_dpp v124, v103, v86 row_newbcast:6 row_mask:0xf bank_mask:0xf
	v_fmac_f32_dpp v125, v103, v87 row_newbcast:7 row_mask:0xf bank_mask:0xf
	v_fmac_f32_dpp v124, v103, v88 row_newbcast:8 row_mask:0xf bank_mask:0xf
	v_fmac_f32_dpp v125, v103, v89 row_newbcast:9 row_mask:0xf bank_mask:0xf
	v_fmac_f32_dpp v124, v103, v90 row_newbcast:10 row_mask:0xf bank_mask:0xf
	v_fmac_f32_dpp v125, v103, v91 row_newbcast:11 row_mask:0xf bank_mask:0xf
	v_fmac_f32_dpp v124, v103, v92 row_newbcast:12 row_mask:0xf bank_mask:0xf
	v_fmac_f32_dpp v125, v103, v93 row_newbcast:13 row_mask:0xf bank_mask:0xf
	v_fmac_f32_dpp v124, v103, v94 row_newbcast:14 row_mask:0xf bank_mask:0xf
	v_fmac_f32_dpp v125, v103, v95 row_newbcast:15 row_mask:0xf bank_mask:0xf
	v_add_f32_e32 v130, v124, v125
	s_waitcnt lgkmcnt(0)
	ds_read2st64_b32 v[114:115], v14 offset0:91 offset1:94
	ds_read2st64_b32 v[116:117], v17 offset0:91 offset1:94
	ds_read_b32 v138, v15 offset:23040
	ds_read_b32 v139, v15 offset:23168
	ds_read_b32 v109, v16 offset:23040
	ds_read_b32 v118, v14 offset:23040
	ds_read_b32 v119, v14 offset:23168
	v_mul_f32_dpp v120, v110, v32 row_newbcast:0 row_mask:0xf bank_mask:0xf
	v_mul_f32_dpp v121, v110, v33 row_newbcast:1 row_mask:0xf bank_mask:0xf
	v_fmac_f32_dpp v120, v110, v34 row_newbcast:2 row_mask:0xf bank_mask:0xf
	v_fmac_f32_dpp v121, v110, v35 row_newbcast:3 row_mask:0xf bank_mask:0xf
	v_fmac_f32_dpp v120, v110, v36 row_newbcast:4 row_mask:0xf bank_mask:0xf
	v_fmac_f32_dpp v121, v110, v37 row_newbcast:5 row_mask:0xf bank_mask:0xf
	v_fmac_f32_dpp v120, v110, v38 row_newbcast:6 row_mask:0xf bank_mask:0xf
	v_fmac_f32_dpp v121, v110, v39 row_newbcast:7 row_mask:0xf bank_mask:0xf
	v_fmac_f32_dpp v120, v110, v40 row_newbcast:8 row_mask:0xf bank_mask:0xf
	v_fmac_f32_dpp v121, v110, v41 row_newbcast:9 row_mask:0xf bank_mask:0xf
	v_fmac_f32_dpp v120, v110, v42 row_newbcast:10 row_mask:0xf bank_mask:0xf
	v_fmac_f32_dpp v121, v110, v43 row_newbcast:11 row_mask:0xf bank_mask:0xf
	v_fmac_f32_dpp v120, v110, v44 row_newbcast:12 row_mask:0xf bank_mask:0xf
	v_fmac_f32_dpp v121, v110, v45 row_newbcast:13 row_mask:0xf bank_mask:0xf
	v_fmac_f32_dpp v120, v110, v46 row_newbcast:14 row_mask:0xf bank_mask:0xf
	v_fmac_f32_dpp v121, v110, v47 row_newbcast:15 row_mask:0xf bank_mask:0xf
	v_fmac_f32_dpp v120, v112, v48 row_newbcast:0 row_mask:0xf bank_mask:0xf
	v_fmac_f32_dpp v121, v112, v49 row_newbcast:1 row_mask:0xf bank_mask:0xf
	v_fmac_f32_dpp v120, v112, v50 row_newbcast:2 row_mask:0xf bank_mask:0xf
	v_fmac_f32_dpp v121, v112, v51 row_newbcast:3 row_mask:0xf bank_mask:0xf
	v_fmac_f32_dpp v120, v112, v52 row_newbcast:4 row_mask:0xf bank_mask:0xf
	v_fmac_f32_dpp v121, v112, v53 row_newbcast:5 row_mask:0xf bank_mask:0xf
	v_fmac_f32_dpp v120, v112, v54 row_newbcast:6 row_mask:0xf bank_mask:0xf
	v_fmac_f32_dpp v121, v112, v55 row_newbcast:7 row_mask:0xf bank_mask:0xf
	v_fmac_f32_dpp v120, v112, v56 row_newbcast:8 row_mask:0xf bank_mask:0xf
	v_fmac_f32_dpp v121, v112, v57 row_newbcast:9 row_mask:0xf bank_mask:0xf
	v_fmac_f32_dpp v120, v112, v58 row_newbcast:10 row_mask:0xf bank_mask:0xf
	v_fmac_f32_dpp v121, v112, v59 row_newbcast:11 row_mask:0xf bank_mask:0xf
	v_fmac_f32_dpp v120, v112, v60 row_newbcast:12 row_mask:0xf bank_mask:0xf
	v_fmac_f32_dpp v121, v112, v61 row_newbcast:13 row_mask:0xf bank_mask:0xf
	v_fmac_f32_dpp v120, v112, v62 row_newbcast:14 row_mask:0xf bank_mask:0xf
	v_fmac_f32_dpp v121, v112, v63 row_newbcast:15 row_mask:0xf bank_mask:0xf
	v_add_f32_e32 v128, v120, v121
	v_mul_f32_dpp v124, v105, v32 row_newbcast:0 row_mask:0xf bank_mask:0xf
	v_mul_f32_dpp v125, v105, v33 row_newbcast:1 row_mask:0xf bank_mask:0xf
	v_permlane32_swap_b32 v129, v128
	v_fmac_f32_dpp v124, v105, v34 row_newbcast:2 row_mask:0xf bank_mask:0xf
	v_fmac_f32_dpp v125, v105, v35 row_newbcast:3 row_mask:0xf bank_mask:0xf
	v_add_f32_dpp v108, -v129, -v128 quad_perm:[0,1,2,3] row_mask:0xc bank_mask:0xf
	v_fmac_f32_dpp v124, v105, v36 row_newbcast:4 row_mask:0xf bank_mask:0xf
	v_fmac_f32_dpp v125, v105, v37 row_newbcast:5 row_mask:0xf bank_mask:0xf
	v_mfma_f32_32x32x2_f32 v[64:79], v136, v108, v[32:47]
	v_fmac_f32_dpp v124, v105, v38 row_newbcast:6 row_mask:0xf bank_mask:0xf
	v_fmac_f32_dpp v125, v105, v39 row_newbcast:7 row_mask:0xf bank_mask:0xf
	v_fmac_f32_dpp v124, v105, v40 row_newbcast:8 row_mask:0xf bank_mask:0xf
	v_fmac_f32_dpp v125, v105, v41 row_newbcast:9 row_mask:0xf bank_mask:0xf
	v_fmac_f32_dpp v124, v105, v42 row_newbcast:10 row_mask:0xf bank_mask:0xf
	v_fmac_f32_dpp v125, v105, v43 row_newbcast:11 row_mask:0xf bank_mask:0xf
	v_fmac_f32_dpp v124, v105, v44 row_newbcast:12 row_mask:0xf bank_mask:0xf
	v_fmac_f32_dpp v125, v105, v45 row_newbcast:13 row_mask:0xf bank_mask:0xf
	v_fmac_f32_dpp v124, v105, v46 row_newbcast:14 row_mask:0xf bank_mask:0xf
	v_fmac_f32_dpp v125, v105, v47 row_newbcast:15 row_mask:0xf bank_mask:0xf
	v_fmac_f32_dpp v124, v107, v48 row_newbcast:0 row_mask:0xf bank_mask:0xf
	v_fmac_f32_dpp v125, v107, v49 row_newbcast:1 row_mask:0xf bank_mask:0xf
	v_fmac_f32_dpp v124, v107, v50 row_newbcast:2 row_mask:0xf bank_mask:0xf
	v_fmac_f32_dpp v125, v107, v51 row_newbcast:3 row_mask:0xf bank_mask:0xf
	v_mfma_f32_32x32x2_f32 v[80:95], v137, v108, v[48:63]
	v_fmac_f32_dpp v124, v107, v52 row_newbcast:4 row_mask:0xf bank_mask:0xf
	v_fmac_f32_dpp v125, v107, v53 row_newbcast:5 row_mask:0xf bank_mask:0xf
	v_fmac_f32_dpp v124, v107, v54 row_newbcast:6 row_mask:0xf bank_mask:0xf
	v_fmac_f32_dpp v125, v107, v55 row_newbcast:7 row_mask:0xf bank_mask:0xf
	v_fmac_f32_dpp v124, v107, v56 row_newbcast:8 row_mask:0xf bank_mask:0xf
	v_fmac_f32_dpp v125, v107, v57 row_newbcast:9 row_mask:0xf bank_mask:0xf
	v_fmac_f32_dpp v124, v107, v58 row_newbcast:10 row_mask:0xf bank_mask:0xf
	v_fmac_f32_dpp v125, v107, v59 row_newbcast:11 row_mask:0xf bank_mask:0xf
	v_fmac_f32_dpp v124, v107, v60 row_newbcast:12 row_mask:0xf bank_mask:0xf
	v_fmac_f32_dpp v125, v107, v61 row_newbcast:13 row_mask:0xf bank_mask:0xf
	v_fmac_f32_dpp v124, v107, v62 row_newbcast:14 row_mask:0xf bank_mask:0xf
	v_fmac_f32_dpp v125, v107, v63 row_newbcast:15 row_mask:0xf bank_mask:0xf
	v_add_f32_e32 v131, v124, v125
	s_nop 1
	v_permlane32_swap_b32 v130, v131
	v_add_f32_e32 v133, v130, v131
	v_cvt_pk_bf16_f32 v133, v133, v133
	global_store_short v13, v133, s[16:17]
	s_add_u32 s16, s16, s20
	s_addc_u32 s17, s17, s21
	s_waitcnt lgkmcnt(0)
	v_mul_f32_dpp v120, v114, v64 row_newbcast:0 row_mask:0xf bank_mask:0xf
	v_mul_f32_dpp v121, v114, v65 row_newbcast:1 row_mask:0xf bank_mask:0xf
	v_fmac_f32_dpp v120, v114, v66 row_newbcast:2 row_mask:0xf bank_mask:0xf
	v_fmac_f32_dpp v121, v114, v67 row_newbcast:3 row_mask:0xf bank_mask:0xf
	v_fmac_f32_dpp v120, v114, v68 row_newbcast:4 row_mask:0xf bank_mask:0xf
	v_fmac_f32_dpp v121, v114, v69 row_newbcast:5 row_mask:0xf bank_mask:0xf
	v_fmac_f32_dpp v120, v114, v70 row_newbcast:6 row_mask:0xf bank_mask:0xf
	v_fmac_f32_dpp v121, v114, v71 row_newbcast:7 row_mask:0xf bank_mask:0xf
	v_fmac_f32_dpp v120, v114, v72 row_newbcast:8 row_mask:0xf bank_mask:0xf
	v_fmac_f32_dpp v121, v114, v73 row_newbcast:9 row_mask:0xf bank_mask:0xf
	v_fmac_f32_dpp v120, v114, v74 row_newbcast:10 row_mask:0xf bank_mask:0xf
	v_fmac_f32_dpp v121, v114, v75 row_newbcast:11 row_mask:0xf bank_mask:0xf
	v_fmac_f32_dpp v120, v114, v76 row_newbcast:12 row_mask:0xf bank_mask:0xf
	v_fmac_f32_dpp v121, v114, v77 row_newbcast:13 row_mask:0xf bank_mask:0xf
	v_fmac_f32_dpp v120, v114, v78 row_newbcast:14 row_mask:0xf bank_mask:0xf
	v_fmac_f32_dpp v121, v114, v79 row_newbcast:15 row_mask:0xf bank_mask:0xf
	v_fmac_f32_dpp v120, v116, v80 row_newbcast:0 row_mask:0xf bank_mask:0xf
	v_fmac_f32_dpp v121, v116, v81 row_newbcast:1 row_mask:0xf bank_mask:0xf
	v_fmac_f32_dpp v120, v116, v82 row_newbcast:2 row_mask:0xf bank_mask:0xf
	v_fmac_f32_dpp v121, v116, v83 row_newbcast:3 row_mask:0xf bank_mask:0xf
	v_fmac_f32_dpp v120, v116, v84 row_newbcast:4 row_mask:0xf bank_mask:0xf
	v_fmac_f32_dpp v121, v116, v85 row_newbcast:5 row_mask:0xf bank_mask:0xf
	v_fmac_f32_dpp v120, v116, v86 row_newbcast:6 row_mask:0xf bank_mask:0xf
	v_fmac_f32_dpp v121, v116, v87 row_newbcast:7 row_mask:0xf bank_mask:0xf
	v_fmac_f32_dpp v120, v116, v88 row_newbcast:8 row_mask:0xf bank_mask:0xf
	v_fmac_f32_dpp v121, v116, v89 row_newbcast:9 row_mask:0xf bank_mask:0xf
	v_fmac_f32_dpp v120, v116, v90 row_newbcast:10 row_mask:0xf bank_mask:0xf
	v_fmac_f32_dpp v121, v116, v91 row_newbcast:11 row_mask:0xf bank_mask:0xf
	v_fmac_f32_dpp v120, v116, v92 row_newbcast:12 row_mask:0xf bank_mask:0xf
	v_fmac_f32_dpp v121, v116, v93 row_newbcast:13 row_mask:0xf bank_mask:0xf
	v_fmac_f32_dpp v120, v116, v94 row_newbcast:14 row_mask:0xf bank_mask:0xf
	v_fmac_f32_dpp v121, v116, v95 row_newbcast:15 row_mask:0xf bank_mask:0xf
	v_add_f32_e32 v128, v120, v121
	v_mul_f32_dpp v124, v111, v64 row_newbcast:0 row_mask:0xf bank_mask:0xf
	v_mul_f32_dpp v125, v111, v65 row_newbcast:1 row_mask:0xf bank_mask:0xf
	v_permlane32_swap_b32 v129, v128
	v_fmac_f32_dpp v124, v111, v66 row_newbcast:2 row_mask:0xf bank_mask:0xf
	v_fmac_f32_dpp v125, v111, v67 row_newbcast:3 row_mask:0xf bank_mask:0xf
	v_add_f32_dpp v109, -v129, -v128 quad_perm:[0,1,2,3] row_mask:0xc bank_mask:0xf
	v_fmac_f32_dpp v124, v111, v68 row_newbcast:4 row_mask:0xf bank_mask:0xf
	v_fmac_f32_dpp v125, v111, v69 row_newbcast:5 row_mask:0xf bank_mask:0xf
	v_mfma_f32_32x32x2_f32 v[32:47], v138, v109, v[64:79]
	v_fmac_f32_dpp v124, v111, v70 row_newbcast:6 row_mask:0xf bank_mask:0xf
	v_fmac_f32_dpp v125, v111, v71 row_newbcast:7 row_mask:0xf bank_mask:0xf
	v_fmac_f32_dpp v124, v111, v72 row_newbcast:8 row_mask:0xf bank_mask:0xf
	v_fmac_f32_dpp v125, v111, v73 row_newbcast:9 row_mask:0xf bank_mask:0xf
	v_fmac_f32_dpp v124, v111, v74 row_newbcast:10 row_mask:0xf bank_mask:0xf
	v_fmac_f32_dpp v125, v111, v75 row_newbcast:11 row_mask:0xf bank_mask:0xf
	v_fmac_f32_dpp v124, v111, v76 row_newbcast:12 row_mask:0xf bank_mask:0xf
	v_fmac_f32_dpp v125, v111, v77 row_newbcast:13 row_mask:0xf bank_mask:0xf
	v_fmac_f32_dpp v124, v111, v78 row_newbcast:14 row_mask:0xf bank_mask:0xf
	v_fmac_f32_dpp v125, v111, v79 row_newbcast:15 row_mask:0xf bank_mask:0xf
	v_fmac_f32_dpp v124, v113, v80 row_newbcast:0 row_mask:0xf bank_mask:0xf
	v_fmac_f32_dpp v125, v113, v81 row_newbcast:1 row_mask:0xf bank_mask:0xf
	v_fmac_f32_dpp v124, v113, v82 row_newbcast:2 row_mask:0xf bank_mask:0xf
; __device__ void scan_chain(PRef p, int l, int chain, ScanSm* sm) {
;     ...
; #pragma unroll 1
;     for (int c = 0; c < 144; c++) {
;       __syncthreads();
;       const ScanRec* rc0 = &sm->rec[c & 1][0];
;       LDSET(A, rc0)
; #pragma unroll 1
;       for (int i2 = 0; i2 < 8; i2++) {
;         const ScanRec* rcA = rc0 + 2 * i2;
;         const ScanRec* rcC = (i2 < 7) ? rcA + 2 : rcA + 1;
;         LDSET(B, rcA + 1)
;         SCAN_STEP(A, c * 16 + 2 * i2)
;         LDSET(A, rcC)
;         SCAN_STEP(B, c * 16 + 2 * i2 + 1)
;       }
;     }
	v_fmac_f32_dpp v125, v113, v83 row_newbcast:3 row_mask:0xf bank_mask:0xf
	v_mfma_f32_32x32x2_f32 v[48:63], v139, v109, v[80:95]
	v_fmac_f32_dpp v124, v113, v84 row_newbcast:4 row_mask:0xf bank_mask:0xf
	v_fmac_f32_dpp v125, v113, v85 row_newbcast:5 row_mask:0xf bank_mask:0xf
	v_fmac_f32_dpp v124, v113, v86 row_newbcast:6 row_mask:0xf bank_mask:0xf
	v_fmac_f32_dpp v125, v113, v87 row_newbcast:7 row_mask:0xf bank_mask:0xf
	v_fmac_f32_dpp v124, v113, v88 row_newbcast:8 row_mask:0xf bank_mask:0xf
	v_fmac_f32_dpp v125, v113, v89 row_newbcast:9 row_mask:0xf bank_mask:0xf
	v_fmac_f32_dpp v124, v113, v90 row_newbcast:10 row_mask:0xf bank_mask:0xf
	v_fmac_f32_dpp v125, v113, v91 row_newbcast:11 row_mask:0xf bank_mask:0xf
	v_fmac_f32_dpp v124, v113, v92 row_newbcast:12 row_mask:0xf bank_mask:0xf
	v_fmac_f32_dpp v125, v113, v93 row_newbcast:13 row_mask:0xf bank_mask:0xf
	v_fmac_f32_dpp v124, v113, v94 row_newbcast:14 row_mask:0xf bank_mask:0xf
	v_fmac_f32_dpp v125, v113, v95 row_newbcast:15 row_mask:0xf bank_mask:0xf
	v_add_f32_e32 v130, v124, v125
	v_mul_f32_dpp v124, v115, v32 row_newbcast:0 row_mask:0xf bank_mask:0xf
	v_mul_f32_dpp v125, v115, v33 row_newbcast:1 row_mask:0xf bank_mask:0xf
	v_fmac_f32_dpp v124, v115, v34 row_newbcast:2 row_mask:0xf bank_mask:0xf
	v_fmac_f32_dpp v125, v115, v35 row_newbcast:3 row_mask:0xf bank_mask:0xf
	v_fmac_f32_dpp v124, v115, v36 row_newbcast:4 row_mask:0xf bank_mask:0xf
	v_fmac_f32_dpp v125, v115, v37 row_newbcast:5 row_mask:0xf bank_mask:0xf
	v_fmac_f32_dpp v124, v115, v38 row_newbcast:6 row_mask:0xf bank_mask:0xf
	v_fmac_f32_dpp v125, v115, v39 row_newbcast:7 row_mask:0xf bank_mask:0xf
	v_fmac_f32_dpp v124, v115, v40 row_newbcast:8 row_mask:0xf bank_mask:0xf
	v_fmac_f32_dpp v125, v115, v41 row_newbcast:9 row_mask:0xf bank_mask:0xf
	v_fmac_f32_dpp v124, v115, v42 row_newbcast:10 row_mask:0xf bank_mask:0xf
	v_fmac_f32_dpp v125, v115, v43 row_newbcast:11 row_mask:0xf bank_mask:0xf
	v_fmac_f32_dpp v124, v115, v44 row_newbcast:12 row_mask:0xf bank_mask:0xf
	v_fmac_f32_dpp v125, v115, v45 row_newbcast:13 row_mask:0xf bank_mask:0xf
	v_fmac_f32_dpp v124, v115, v46 row_newbcast:14 row_mask:0xf bank_mask:0xf
	v_fmac_f32_dpp v125, v115, v47 row_newbcast:15 row_mask:0xf bank_mask:0xf
	v_fmac_f32_dpp v124, v117, v48 row_newbcast:0 row_mask:0xf bank_mask:0xf
	v_fmac_f32_dpp v125, v117, v49 row_newbcast:1 row_mask:0xf bank_mask:0xf
	v_fmac_f32_dpp v124, v117, v50 row_newbcast:2 row_mask:0xf bank_mask:0xf
	v_fmac_f32_dpp v125, v117, v51 row_newbcast:3 row_mask:0xf bank_mask:0xf
	v_fmac_f32_dpp v124, v117, v52 row_newbcast:4 row_mask:0xf bank_mask:0xf
	v_fmac_f32_dpp v125, v117, v53 row_newbcast:5 row_mask:0xf bank_mask:0xf
	v_fmac_f32_dpp v124, v117, v54 row_newbcast:6 row_mask:0xf bank_mask:0xf
	v_fmac_f32_dpp v125, v117, v55 row_newbcast:7 row_mask:0xf bank_mask:0xf
	v_fmac_f32_dpp v124, v117, v56 row_newbcast:8 row_mask:0xf bank_mask:0xf
	v_fmac_f32_dpp v125, v117, v57 row_newbcast:9 row_mask:0xf bank_mask:0xf
	v_fmac_f32_dpp v124, v117, v58 row_newbcast:10 row_mask:0xf bank_mask:0xf
	v_fmac_f32_dpp v125, v117, v59 row_newbcast:11 row_mask:0xf bank_mask:0xf
	v_fmac_f32_dpp v124, v117, v60 row_newbcast:12 row_mask:0xf bank_mask:0xf
	v_fmac_f32_dpp v125, v117, v61 row_newbcast:13 row_mask:0xf bank_mask:0xf
	v_fmac_f32_dpp v124, v117, v62 row_newbcast:14 row_mask:0xf bank_mask:0xf
	v_fmac_f32_dpp v125, v117, v63 row_newbcast:15 row_mask:0xf bank_mask:0xf
	v_add_f32_e32 v131, v124, v125
	s_nop 1
	v_permlane32_swap_b32 v130, v131
	v_add_f32_e32 v133, v130, v131
	v_cvt_pk_bf16_f32 v133, v133, v133
	global_store_short v13, v133, s[16:17]
	s_add_u32 s16, s16, s20
	s_addc_u32 s17, s17, s21
	v_mul_f32_dpp v32, v118, v32 row_newbcast:0 row_mask:0xf bank_mask:0xf
	v_mul_f32_dpp v33, v118, v33 row_newbcast:1 row_mask:0xf bank_mask:0xf
	v_mul_f32_dpp v34, v118, v34 row_newbcast:2 row_mask:0xf bank_mask:0xf
	v_mul_f32_dpp v35, v118, v35 row_newbcast:3 row_mask:0xf bank_mask:0xf
	v_mul_f32_dpp v36, v118, v36 row_newbcast:4 row_mask:0xf bank_mask:0xf
	v_mul_f32_dpp v37, v118, v37 row_newbcast:5 row_mask:0xf bank_mask:0xf
	v_mul_f32_dpp v38, v118, v38 row_newbcast:6 row_mask:0xf bank_mask:0xf
	v_mul_f32_dpp v39, v118, v39 row_newbcast:7 row_mask:0xf bank_mask:0xf
	v_mul_f32_dpp v40, v118, v40 row_newbcast:8 row_mask:0xf bank_mask:0xf
	v_mul_f32_dpp v41, v118, v41 row_newbcast:9 row_mask:0xf bank_mask:0xf
	v_mul_f32_dpp v42, v118, v42 row_newbcast:10 row_mask:0xf bank_mask:0xf
	v_mul_f32_dpp v43, v118, v43 row_newbcast:11 row_mask:0xf bank_mask:0xf
	v_mul_f32_dpp v44, v118, v44 row_newbcast:12 row_mask:0xf bank_mask:0xf
	v_mul_f32_dpp v45, v118, v45 row_newbcast:13 row_mask:0xf bank_mask:0xf
	v_mul_f32_dpp v46, v118, v46 row_newbcast:14 row_mask:0xf bank_mask:0xf
	v_mul_f32_dpp v47, v118, v47 row_newbcast:15 row_mask:0xf bank_mask:0xf
	v_mul_f32_dpp v48, v119, v48 row_newbcast:0 row_mask:0xf bank_mask:0xf
	v_mul_f32_dpp v49, v119, v49 row_newbcast:1 row_mask:0xf bank_mask:0xf
	v_mul_f32_dpp v50, v119, v50 row_newbcast:2 row_mask:0xf bank_mask:0xf
	v_mul_f32_dpp v51, v119, v51 row_newbcast:3 row_mask:0xf bank_mask:0xf
	v_mul_f32_dpp v52, v119, v52 row_newbcast:4 row_mask:0xf bank_mask:0xf
	v_mul_f32_dpp v53, v119, v53 row_newbcast:5 row_mask:0xf bank_mask:0xf
	v_mul_f32_dpp v54, v119, v54 row_newbcast:6 row_mask:0xf bank_mask:0xf
	v_mul_f32_dpp v55, v119, v55 row_newbcast:7 row_mask:0xf bank_mask:0xf
	v_mul_f32_dpp v56, v119, v56 row_newbcast:8 row_mask:0xf bank_mask:0xf
	v_mul_f32_dpp v57, v119, v57 row_newbcast:9 row_mask:0xf bank_mask:0xf
	v_mul_f32_dpp v58, v119, v58 row_newbcast:10 row_mask:0xf bank_mask:0xf
	v_mul_f32_dpp v59, v119, v59 row_newbcast:11 row_mask:0xf bank_mask:0xf
	v_mul_f32_dpp v60, v119, v60 row_newbcast:12 row_mask:0xf bank_mask:0xf
	v_mul_f32_dpp v61, v119, v61 row_newbcast:13 row_mask:0xf bank_mask:0xf
	v_mul_f32_dpp v62, v119, v62 row_newbcast:14 row_mask:0xf bank_mask:0xf
	v_mul_f32_dpp v63, v119, v63 row_newbcast:15 row_mask:0xf bank_mask:0xf
	s_add_i32 s15, s15, 1
	s_cmpk_lg_i32 s15, 0x90
	s_cbranch_scc1 .Lscan_chunk
	s_branch .LBB0_564

; template <int NI>
; DEV void stage_tile(const f32x16 (&acc)[2][NI], bf16* sC) {
;     ...
;   for (int mi = 0; mi < 2; mi++)
; #pragma unroll
;     for (int ni = 0; ni < NI; ni++)
; #pragma unroll
;       for (int g = 0; g < 4; g++) {
;         int row = wm * 64 + mi * 32 + (lane & 31);
;         int col = wn * NI * 32 + ni * 32 + 8 * g + 4 * (lane >> 5);
;         uint2 v;
;         v.x = pack2(acc[mi][ni][4 * g], acc[mi][ni][4 * g + 1]);
;         v.y = pack2(acc[mi][ni][4 * g + 2], acc[mi][ni][4 * g + 3]);
;         *(uint2*)(sC + row * LDC + col) = v;
;       }
; __device__ void phase_gates(PRef p, int l, const bf16* H2, bf16* sA, bf16* sB) {
;     ...
;     int n = ct >> 2, c0 = (ct & 3) * 128;
;     bf16* dst = n == 0 ? p.HY : (n == 1 ? p.ZB : p.ZC);
;     int ld = n == 2 ? 768 : 512;
;     stage_tile<2>(acc, sA);
;     TILE_CHUNKS(2, sA, {
;       u32x4* pp = (u32x4*)(dst + (size_t)(rt * 128 + trow) * ld + c0 + tcol);
;       u32x4 yv = *pp;
;       u32x4 ov;
;       _Pragma("unroll") for (int j = 0; j < 4; j++) {
;         float g0 = __uint_as_float(cv[j] << 16), g1 = __uint_as_float(cv[j] & 0xffff0000u);
;         g0 = g0 / (1.f + __expf(-g0));
;         g1 = g1 / (1.f + __expf(-g1));
;         float y0 = __uint_as_float(yv[j] << 16), y1 = __uint_as_float(yv[j] & 0xffff0000u);
;         ov[j] = pack2(y0 * g0, y1 * g1);
;       }
;       *pp = ov;
;     })
.LBB0_867:
	s_ashr_i32 s11, s12, 2
	s_cmp_eq_u32 s11, 1
	s_movk_i32 s0, 0x160
	s_cselect_b32 s0, s0, 0x168
	s_cmp_gt_u32 s12, 3
	s_cselect_b32 s0, s0, 0x150
	s_add_u32 s0, s22, s0
	s_addc_u32 s1, s23, 0
	v_mov_b32_e32 v0, v196
	s_load_dwordx2 s[14:15], s[0:1], 0x0
	v_cvt_pk_bf16_f32 v52, v52, v53
	v_lshrrev_b32_e32 v1, 1, v0
	v_and_b32_e32 v2, 31, v0
	v_and_or_b32 v1, v1, s75, v2
	v_and_b32_e32 v2, 64, v0
	v_lshrrev_b32_e32 v0, 2, v0
	v_and_b32_e32 v0, 8, v0
	v_lshl_or_b32 v0, v2, 1, v0
	v_mad_u64_u32 v[0:1], s[0:1], v1, s52, v[0:1]
	v_cvt_pk_bf16_f32 v53, v54, v55
	v_cvt_pk_bf16_f32 v54, v56, v57
	v_cvt_pk_bf16_f32 v55, v58, v59
	v_cvt_pk_bf16_f32 v36, v36, v37
	v_cvt_pk_bf16_f32 v37, v38, v39
	v_cvt_pk_bf16_f32 v38, v40, v41
	v_cvt_pk_bf16_f32 v39, v42, v43
	s_waitcnt lgkmcnt(0)
	s_barrier
	ds_write2_b64 v0, v[52:53], v[54:55] offset1:2
	v_cvt_pk_bf16_f32 v52, v60, v61
	v_cvt_pk_bf16_f32 v53, v62, v63
	v_cvt_pk_bf16_f32 v54, v64, v65
	v_cvt_pk_bf16_f32 v55, v66, v67
	ds_write2_b64 v0, v[36:37], v[38:39] offset0:8 offset1:10
	v_cvt_pk_bf16_f32 v36, v44, v45
	v_cvt_pk_bf16_f32 v37, v46, v47
	v_cvt_pk_bf16_f32 v38, v48, v49
	v_cvt_pk_bf16_f32 v39, v50, v51
	v_cvt_pk_bf16_f32 v20, v20, v21
	v_cvt_pk_bf16_f32 v21, v22, v23
	v_cvt_pk_bf16_f32 v22, v24, v25
	v_cvt_pk_bf16_f32 v23, v26, v27
	v_add_u32_e32 v2, 0x2000, v0
	ds_write2_b64 v0, v[52:53], v[54:55] offset0:4 offset1:6
	ds_write2_b64 v0, v[36:37], v[38:39] offset0:12 offset1:14
	ds_write2_b64 v2, v[20:21], v[22:23] offset0:64 offset1:66
	v_cvt_pk_bf16_f32 v0, v28, v29
	v_cvt_pk_bf16_f32 v1, v30, v31
	v_cvt_pk_bf16_f32 v20, v32, v33
	v_cvt_pk_bf16_f32 v21, v34, v35
	ds_write2_b64 v2, v[0:1], v[20:21] offset0:68 offset1:70
	v_cvt_pk_bf16_f32 v0, v4, v5
	v_cvt_pk_bf16_f32 v1, v6, v7
	v_cvt_pk_bf16_f32 v4, v8, v9
	v_cvt_pk_bf16_f32 v5, v10, v11
	ds_write2_b64 v2, v[0:1], v[4:5] offset0:72 offset1:74
	v_cvt_pk_bf16_f32 v0, v12, v13
	v_cvt_pk_bf16_f32 v1, v14, v15
	v_cvt_pk_bf16_f32 v4, v16, v17
	v_cvt_pk_bf16_f32 v5, v18, v19
	ds_write2_b64 v2, v[0:1], v[4:5] offset0:76 offset1:78
	v_mov_b32_e32 v2, v196
	s_waitcnt lgkmcnt(0)
	s_barrier
	s_cmp_eq_u32 s11, 2
	v_ashrrev_i32_e32 v0, 31, v2
	v_lshrrev_b32_e32 v0, 28, v0
	v_add_u32_e32 v0, v2, v0
	s_cselect_b32 s13, s83, 0x200
	s_lshl_b32 s0, s12, 8
	v_ashrrev_i32_e32 v4, 4, v0
	v_and_b32_e32 v0, -16, v0
	s_lshl_b32 s18, s10, 7
	s_and_b32 s0, s0, 0x300
	v_sub_u32_e32 v5, v2, v0
	v_mul_lo_u32 v6, v4, s52
	s_add_u32 s10, s14, s0
	v_lshlrev_b32_e32 v0, 3, v5
	v_lshl_add_u32 v5, v5, 4, v6
	v_add_u32_e32 v4, s18, v4
	s_addc_u32 s11, s15, 0
	ds_read_b128 v[8:11], v5
	v_mad_i64_i32 v[4:5], s[0:1], s13, v4, 0
	v_ashrrev_i32_e32 v1, 31, v0
	v_lshl_add_u64 v[4:5], v[4:5], 1, s[10:11]
	v_lshl_add_u64 v[0:1], v[0:1], 1, v[4:5]
	global_load_dwordx4 v[4:7], v[0:1], off
	s_waitcnt lgkmcnt(0)
	v_lshlrev_b32_e32 v14, 16, v8
	v_and_b32_e32 v8, 0xffff0000, v8
	v_mul_f32_e32 v12, 0xbfb8aa3b, v14
	v_mul_f32_e32 v13, 0xbfb8aa3b, v8
	v_exp_f32_e32 v12, v12
	v_exp_f32_e32 v13, v13
	s_nop 0
	v_pk_add_f32 v[12:13], v[12:13], 1.0 op_sel_hi:[1,0]
	s_nop 0
	v_rcp_f32_e32 v16, v13
	s_nop 0
	v_mul_f32_e32 v13, v8, v16
	v_rcp_f32_e32 v15, v12
	s_nop 0
	v_mul_f32_e32 v12, v14, v15
	s_waitcnt vmcnt(0)
	v_lshlrev_b32_e32 v14, 16, v4
	v_and_b32_e32 v15, 0xffff0000, v4
	v_pk_mul_f32 v[12:13], v[12:13], v[14:15]
	s_nop 0
	v_cvt_pk_bf16_f32 v4, v12, v13
	v_lshlrev_b32_e32 v12, 16, v9
	v_and_b32_e32 v13, 0xffff0000, v9
	v_mul_f32_e32 v8, 0xbfb8aa3b, v12
	v_mul_f32_e32 v9, 0xbfb8aa3b, v13
	v_exp_f32_e32 v8, v8
	v_exp_f32_e32 v9, v9
	s_nop 0
	v_pk_add_f32 v[8:9], v[8:9], 1.0 op_sel_hi:[1,0]
	s_nop 0
	v_rcp_f32_e32 v15, v9
	s_nop 0
	v_mul_f32_e32 v9, v13, v15
	v_rcp_f32_e32 v14, v8
	s_nop 0
	v_mul_f32_e32 v8, v12, v14
	v_lshlrev_b32_e32 v12, 16, v5
	v_and_b32_e32 v13, 0xffff0000, v5
	v_pk_mul_f32 v[8:9], v[8:9], v[12:13]
	v_lshlrev_b32_e32 v12, 16, v10
	v_and_b32_e32 v10, 0xffff0000, v10
	v_cvt_pk_bf16_f32 v5, v8, v9
	v_mul_f32_e32 v8, 0xbfb8aa3b, v12
	v_mul_f32_e32 v9, 0xbfb8aa3b, v10
	v_exp_f32_e32 v8, v8
	v_exp_f32_e32 v9, v9
	s_nop 0
	v_pk_add_f32 v[8:9], v[8:9], 1.0 op_sel_hi:[1,0]
	s_nop 0
	v_rcp_f32_e32 v14, v9
	s_nop 0
	v_mul_f32_e32 v9, v10, v14
	v_rcp_f32_e32 v13, v8
	s_nop 0
	v_mul_f32_e32 v8, v12, v13
	v_lshlrev_b32_e32 v12, 16, v6
	v_and_b32_e32 v13, 0xffff0000, v6
	v_pk_mul_f32 v[8:9], v[8:9], v[12:13]
	v_lshlrev_b32_e32 v10, 16, v11
	v_and_b32_e32 v11, 0xffff0000, v11
	v_cvt_pk_bf16_f32 v6, v8, v9
	v_mul_f32_e32 v8, 0xbfb8aa3b, v10
	v_mul_f32_e32 v9, 0xbfb8aa3b, v11
	v_exp_f32_e32 v8, v8
	v_exp_f32_e32 v9, v9
	s_nop 0
	v_pk_add_f32 v[8:9], v[8:9], 1.0 op_sel_hi:[1,0]
	s_nop 0
	v_rcp_f32_e32 v13, v9
	s_nop 0
	v_mul_f32_e32 v9, v11, v13
	v_rcp_f32_e32 v12, v8
	s_nop 0
	v_mul_f32_e32 v8, v10, v12
	v_lshlrev_b32_e32 v10, 16, v7
	v_and_b32_e32 v11, 0xffff0000, v7
	v_pk_mul_f32 v[8:9], v[8:9], v[10:11]
	s_nop 0
	v_cvt_pk_bf16_f32 v7, v8, v9
	global_store_dwordx4 v[0:1], v[4:7], off
	v_add_u32_e32 v0, 0x100, v2
	v_ashrrev_i32_e32 v1, 31, v0
	v_lshrrev_b32_e32 v1, 28, v1
	v_add_u32_e32 v1, v0, v1
	v_ashrrev_i32_e32 v4, 4, v1
	v_and_b32_e32 v1, -16, v1
	v_sub_u32_e32 v5, v0, v1
	v_mul_lo_u32 v6, v4, s52
	v_lshlrev_b32_e32 v0, 3, v5
	v_lshl_add_u32 v5, v5, 4, v6
	v_add_u32_e32 v4, s18, v4
	ds_read_b128 v[8:11], v5
	v_mad_i64_i32 v[4:5], s[0:1], s13, v4, 0
	v_ashrrev_i32_e32 v1, 31, v0
	v_lshl_add_u64 v[4:5], v[4:5], 1, s[10:11]
	v_lshl_add_u64 v[0:1], v[0:1], 1, v[4:5]
	global_load_dwordx4 v[4:7], v[0:1], off
	s_waitcnt lgkmcnt(0)
; __device__ void phase_gates(PRef p, int l, const bf16* H2, bf16* sA, bf16* sB) {
;     ...
;     TILE_CHUNKS(2, sA, {
;       u32x4* pp = (u32x4*)(dst + (size_t)(rt * 128 + trow) * ld + c0 + tcol);
;       u32x4 yv = *pp;
;       u32x4 ov;
;       _Pragma("unroll") for (int j = 0; j < 4; j++) {
;         float g0 = __uint_as_float(cv[j] << 16), g1 = __uint_as_float(cv[j] & 0xffff0000u);
;         g0 = g0 / (1.f + __expf(-g0));
;         g1 = g1 / (1.f + __expf(-g1));
;         float y0 = __uint_as_float(yv[j] << 16), y1 = __uint_as_float(yv[j] & 0xffff0000u);
;         ov[j] = pack2(y0 * g0, y1 * g1);
;       }
;       *pp = ov;
;     })
	v_lshlrev_b32_e32 v14, 16, v8
	v_and_b32_e32 v8, 0xffff0000, v8
	v_mul_f32_e32 v12, 0xbfb8aa3b, v14
	v_mul_f32_e32 v13, 0xbfb8aa3b, v8
	v_exp_f32_e32 v12, v12
	v_exp_f32_e32 v13, v13
	s_nop 0
	v_pk_add_f32 v[12:13], v[12:13], 1.0 op_sel_hi:[1,0]
	s_nop 0
	v_rcp_f32_e32 v16, v13
	s_nop 0
	v_mul_f32_e32 v13, v8, v16
	v_rcp_f32_e32 v15, v12
	s_nop 0
	v_mul_f32_e32 v12, v14, v15
	s_waitcnt vmcnt(0)
	v_lshlrev_b32_e32 v14, 16, v4
	v_and_b32_e32 v15, 0xffff0000, v4
	v_pk_mul_f32 v[12:13], v[12:13], v[14:15]
	s_nop 0
	v_cvt_pk_bf16_f32 v4, v12, v13
	v_lshlrev_b32_e32 v12, 16, v9
	v_and_b32_e32 v13, 0xffff0000, v9
	v_mul_f32_e32 v8, 0xbfb8aa3b, v12
	v_mul_f32_e32 v9, 0xbfb8aa3b, v13
	v_exp_f32_e32 v8, v8
	v_exp_f32_e32 v9, v9
	s_nop 0
	v_pk_add_f32 v[8:9], v[8:9], 1.0 op_sel_hi:[1,0]
	s_nop 0
	v_rcp_f32_e32 v15, v9
	s_nop 0
	v_mul_f32_e32 v9, v13, v15
	v_rcp_f32_e32 v14, v8
	s_nop 0
	v_mul_f32_e32 v8, v12, v14
	v_lshlrev_b32_e32 v12, 16, v5
	v_and_b32_e32 v13, 0xffff0000, v5
	v_pk_mul_f32 v[8:9], v[8:9], v[12:13]
	v_lshlrev_b32_e32 v12, 16, v10
	v_and_b32_e32 v10, 0xffff0000, v10
	v_cvt_pk_bf16_f32 v5, v8, v9
	v_mul_f32_e32 v8, 0xbfb8aa3b, v12
	v_mul_f32_e32 v9, 0xbfb8aa3b, v10
	v_exp_f32_e32 v8, v8
	v_exp_f32_e32 v9, v9
	s_nop 0
	v_pk_add_f32 v[8:9], v[8:9], 1.0 op_sel_hi:[1,0]
	s_nop 0
	v_rcp_f32_e32 v14, v9
	s_nop 0
	v_mul_f32_e32 v9, v10, v14
	v_rcp_f32_e32 v13, v8
	s_nop 0
	v_mul_f32_e32 v8, v12, v13
	v_lshlrev_b32_e32 v12, 16, v6
	v_and_b32_e32 v13, 0xffff0000, v6
	v_pk_mul_f32 v[8:9], v[8:9], v[12:13]
	v_lshlrev_b32_e32 v10, 16, v11
	v_and_b32_e32 v11, 0xffff0000, v11
	v_cvt_pk_bf16_f32 v6, v8, v9
	v_mul_f32_e32 v8, 0xbfb8aa3b, v10
	v_mul_f32_e32 v9, 0xbfb8aa3b, v11
	v_exp_f32_e32 v8, v8
	v_exp_f32_e32 v9, v9
	s_nop 0
	v_pk_add_f32 v[8:9], v[8:9], 1.0 op_sel_hi:[1,0]
	s_nop 0
	v_rcp_f32_e32 v13, v9
	s_nop 0
	v_mul_f32_e32 v9, v11, v13
	v_rcp_f32_e32 v12, v8
	s_nop 0
	v_mul_f32_e32 v8, v10, v12
	v_lshlrev_b32_e32 v10, 16, v7
	v_and_b32_e32 v11, 0xffff0000, v7
	v_pk_mul_f32 v[8:9], v[8:9], v[10:11]
	s_nop 0
	v_cvt_pk_bf16_f32 v7, v8, v9
	global_store_dwordx4 v[0:1], v[4:7], off
	v_add_u32_e32 v0, 0x200, v2
	v_ashrrev_i32_e32 v1, 31, v0
	v_lshrrev_b32_e32 v1, 28, v1
	v_add_u32_e32 v1, v0, v1
	v_ashrrev_i32_e32 v4, 4, v1
	v_and_b32_e32 v1, -16, v1
	v_sub_u32_e32 v5, v0, v1
	v_mul_lo_u32 v6, v4, s52
	v_lshlrev_b32_e32 v0, 3, v5
	v_lshl_add_u32 v5, v5, 4, v6
	v_add_u32_e32 v4, s18, v4
	ds_read_b128 v[8:11], v5
	v_mad_i64_i32 v[4:5], s[0:1], s13, v4, 0
	v_ashrrev_i32_e32 v1, 31, v0
	v_lshl_add_u64 v[4:5], v[4:5], 1, s[10:11]
	v_lshl_add_u64 v[0:1], v[0:1], 1, v[4:5]
	global_load_dwordx4 v[4:7], v[0:1], off
	s_waitcnt lgkmcnt(0)
	v_lshlrev_b32_e32 v14, 16, v8
	v_and_b32_e32 v8, 0xffff0000, v8
	v_mul_f32_e32 v12, 0xbfb8aa3b, v14
	v_mul_f32_e32 v13, 0xbfb8aa3b, v8
	v_exp_f32_e32 v12, v12
	v_exp_f32_e32 v13, v13
	s_nop 0
	v_pk_add_f32 v[12:13], v[12:13], 1.0 op_sel_hi:[1,0]
	s_nop 0
	v_rcp_f32_e32 v16, v13
	s_nop 0
	v_mul_f32_e32 v13, v8, v16
	v_rcp_f32_e32 v15, v12
	s_nop 0
	v_mul_f32_e32 v12, v14, v15
	s_waitcnt vmcnt(0)
	v_lshlrev_b32_e32 v14, 16, v4
	v_and_b32_e32 v15, 0xffff0000, v4
	v_pk_mul_f32 v[12:13], v[12:13], v[14:15]
	s_nop 0
	v_cvt_pk_bf16_f32 v4, v12, v13
	v_lshlrev_b32_e32 v12, 16, v9
	v_and_b32_e32 v13, 0xffff0000, v9
	v_mul_f32_e32 v8, 0xbfb8aa3b, v12
	v_mul_f32_e32 v9, 0xbfb8aa3b, v13
	v_exp_f32_e32 v8, v8
	v_exp_f32_e32 v9, v9
	s_nop 0
	v_pk_add_f32 v[8:9], v[8:9], 1.0 op_sel_hi:[1,0]
	s_nop 0
	v_rcp_f32_e32 v15, v9
	s_nop 0
	v_mul_f32_e32 v9, v13, v15
	v_rcp_f32_e32 v14, v8
	s_nop 0
	v_mul_f32_e32 v8, v12, v14
	v_lshlrev_b32_e32 v12, 16, v5
	v_and_b32_e32 v13, 0xffff0000, v5
	v_pk_mul_f32 v[8:9], v[8:9], v[12:13]
	v_lshlrev_b32_e32 v12, 16, v10
	v_and_b32_e32 v10, 0xffff0000, v10
	v_cvt_pk_bf16_f32 v5, v8, v9
	v_mul_f32_e32 v8, 0xbfb8aa3b, v12
	v_mul_f32_e32 v9, 0xbfb8aa3b, v10
	v_exp_f32_e32 v8, v8
	v_exp_f32_e32 v9, v9
	s_nop 0
	v_pk_add_f32 v[8:9], v[8:9], 1.0 op_sel_hi:[1,0]
	s_nop 0
	v_rcp_f32_e32 v14, v9
	s_nop 0
	v_mul_f32_e32 v9, v10, v14
	v_rcp_f32_e32 v13, v8
	s_nop 0
	v_mul_f32_e32 v8, v12, v13
	v_lshlrev_b32_e32 v12, 16, v6
	v_and_b32_e32 v13, 0xffff0000, v6
	v_pk_mul_f32 v[8:9], v[8:9], v[12:13]
	v_lshlrev_b32_e32 v10, 16, v11
	v_and_b32_e32 v11, 0xffff0000, v11
	v_cvt_pk_bf16_f32 v6, v8, v9
	v_mul_f32_e32 v8, 0xbfb8aa3b, v10
	v_mul_f32_e32 v9, 0xbfb8aa3b, v11
	v_exp_f32_e32 v8, v8
	v_exp_f32_e32 v9, v9
	s_nop 0
	v_pk_add_f32 v[8:9], v[8:9], 1.0 op_sel_hi:[1,0]
	s_nop 0
	v_rcp_f32_e32 v13, v9
	s_nop 0
	v_mul_f32_e32 v9, v11, v13
	v_rcp_f32_e32 v12, v8
	s_nop 0
	v_mul_f32_e32 v8, v10, v12
	v_lshlrev_b32_e32 v10, 16, v7
	v_and_b32_e32 v11, 0xffff0000, v7
	v_pk_mul_f32 v[8:9], v[8:9], v[10:11]
	s_nop 0
	v_cvt_pk_bf16_f32 v7, v8, v9
	global_store_dwordx4 v[0:1], v[4:7], off
	v_add_u32_e32 v0, 0x300, v2
	v_ashrrev_i32_e32 v1, 31, v0
	v_lshrrev_b32_e32 v1, 28, v1
	v_add_u32_e32 v1, v0, v1
	v_ashrrev_i32_e32 v4, 4, v1
	v_and_b32_e32 v1, -16, v1
	v_sub_u32_e32 v5, v0, v1
	v_mul_lo_u32 v6, v4, s52
	v_lshlrev_b32_e32 v0, 3, v5
	v_lshl_add_u32 v5, v5, 4, v6
	v_add_u32_e32 v4, s18, v4
	ds_read_b128 v[8:11], v5
	v_mad_i64_i32 v[4:5], s[0:1], s13, v4, 0
	v_ashrrev_i32_e32 v1, 31, v0
	v_lshl_add_u64 v[4:5], v[4:5], 1, s[10:11]
	v_lshl_add_u64 v[0:1], v[0:1], 1, v[4:5]
	global_load_dwordx4 v[4:7], v[0:1], off
	s_waitcnt lgkmcnt(0)
	v_lshlrev_b32_e32 v14, 16, v8
	v_and_b32_e32 v8, 0xffff0000, v8
	v_mul_f32_e32 v12, 0xbfb8aa3b, v14
	v_mul_f32_e32 v13, 0xbfb8aa3b, v8
	v_exp_f32_e32 v12, v12
	v_exp_f32_e32 v13, v13
	s_nop 0
	v_pk_add_f32 v[12:13], v[12:13], 1.0 op_sel_hi:[1,0]
	s_nop 0
	v_rcp_f32_e32 v16, v13
	s_nop 0
	v_mul_f32_e32 v13, v8, v16
	v_rcp_f32_e32 v15, v12
	s_nop 0
	v_mul_f32_e32 v12, v14, v15
	s_waitcnt vmcnt(0)
; __device__ void phase_gates(PRef p, int l, const bf16* H2, bf16* sA, bf16* sB) {
;     ...
;     TILE_CHUNKS(2, sA, {
;       u32x4* pp = (u32x4*)(dst + (size_t)(rt * 128 + trow) * ld + c0 + tcol);
;       u32x4 yv = *pp;
;       u32x4 ov;
;       _Pragma("unroll") for (int j = 0; j < 4; j++) {
;         float g0 = __uint_as_float(cv[j] << 16), g1 = __uint_as_float(cv[j] & 0xffff0000u);
;         g0 = g0 / (1.f + __expf(-g0));
;         g1 = g1 / (1.f + __expf(-g1));
;         float y0 = __uint_as_float(yv[j] << 16), y1 = __uint_as_float(yv[j] & 0xffff0000u);
;         ov[j] = pack2(y0 * g0, y1 * g1);
;       }
;       *pp = ov;
;     })
	v_lshlrev_b32_e32 v14, 16, v4
	v_and_b32_e32 v15, 0xffff0000, v4
	v_pk_mul_f32 v[12:13], v[12:13], v[14:15]
	s_nop 0
	v_cvt_pk_bf16_f32 v4, v12, v13
	v_lshlrev_b32_e32 v12, 16, v9
	v_and_b32_e32 v13, 0xffff0000, v9
	v_mul_f32_e32 v8, 0xbfb8aa3b, v12
	v_mul_f32_e32 v9, 0xbfb8aa3b, v13
	v_exp_f32_e32 v8, v8
	v_exp_f32_e32 v9, v9
	s_nop 0
	v_pk_add_f32 v[8:9], v[8:9], 1.0 op_sel_hi:[1,0]
	s_nop 0
	v_rcp_f32_e32 v15, v9
	s_nop 0
	v_mul_f32_e32 v9, v13, v15
	v_rcp_f32_e32 v14, v8
	s_nop 0
	v_mul_f32_e32 v8, v12, v14
	v_lshlrev_b32_e32 v12, 16, v5
	v_and_b32_e32 v13, 0xffff0000, v5
	v_pk_mul_f32 v[8:9], v[8:9], v[12:13]
	v_lshlrev_b32_e32 v12, 16, v10
	v_and_b32_e32 v10, 0xffff0000, v10
	v_cvt_pk_bf16_f32 v5, v8, v9
	v_mul_f32_e32 v8, 0xbfb8aa3b, v12
	v_mul_f32_e32 v9, 0xbfb8aa3b, v10
	v_exp_f32_e32 v8, v8
	v_exp_f32_e32 v9, v9
	s_nop 0
	v_pk_add_f32 v[8:9], v[8:9], 1.0 op_sel_hi:[1,0]
	s_nop 0
	v_rcp_f32_e32 v14, v9
	s_nop 0
	v_mul_f32_e32 v9, v10, v14
	v_rcp_f32_e32 v13, v8
	s_nop 0
	v_mul_f32_e32 v8, v12, v13
	v_lshlrev_b32_e32 v12, 16, v6
	v_and_b32_e32 v13, 0xffff0000, v6
	v_pk_mul_f32 v[8:9], v[8:9], v[12:13]
	v_lshlrev_b32_e32 v10, 16, v11
	v_and_b32_e32 v11, 0xffff0000, v11
	v_cvt_pk_bf16_f32 v6, v8, v9
	v_mul_f32_e32 v8, 0xbfb8aa3b, v10
	v_mul_f32_e32 v9, 0xbfb8aa3b, v11
	v_exp_f32_e32 v8, v8
	v_exp_f32_e32 v9, v9
	s_nop 0
	v_pk_add_f32 v[8:9], v[8:9], 1.0 op_sel_hi:[1,0]
	s_nop 0
	v_rcp_f32_e32 v13, v9
	s_nop 0
	v_mul_f32_e32 v9, v11, v13
	v_rcp_f32_e32 v12, v8
	s_nop 0
	v_mul_f32_e32 v8, v10, v12
	v_lshlrev_b32_e32 v10, 16, v7
	v_and_b32_e32 v11, 0xffff0000, v7
	v_pk_mul_f32 v[8:9], v[8:9], v[10:11]
	s_nop 0
	v_cvt_pk_bf16_f32 v7, v8, v9
	global_store_dwordx4 v[0:1], v[4:7], off
	v_add_u32_e32 v0, 0x400, v2
	v_ashrrev_i32_e32 v1, 31, v0
	v_lshrrev_b32_e32 v1, 28, v1
	v_add_u32_e32 v1, v0, v1
	v_ashrrev_i32_e32 v4, 4, v1
	v_and_b32_e32 v1, -16, v1
	v_sub_u32_e32 v5, v0, v1
	v_mul_lo_u32 v6, v4, s52
	v_lshlrev_b32_e32 v0, 3, v5
	v_lshl_add_u32 v5, v5, 4, v6
	v_add_u32_e32 v4, s18, v4
	ds_read_b128 v[8:11], v5
	v_mad_i64_i32 v[4:5], s[0:1], s13, v4, 0
	v_ashrrev_i32_e32 v1, 31, v0
	v_lshl_add_u64 v[4:5], v[4:5], 1, s[10:11]
	v_lshl_add_u64 v[0:1], v[0:1], 1, v[4:5]
	global_load_dwordx4 v[4:7], v[0:1], off
	s_waitcnt lgkmcnt(0)
	v_lshlrev_b32_e32 v14, 16, v8
	v_and_b32_e32 v8, 0xffff0000, v8
	v_mul_f32_e32 v12, 0xbfb8aa3b, v14
	v_mul_f32_e32 v13, 0xbfb8aa3b, v8
	v_exp_f32_e32 v12, v12
	v_exp_f32_e32 v13, v13
	s_nop 0
	v_pk_add_f32 v[12:13], v[12:13], 1.0 op_sel_hi:[1,0]
	s_nop 0
	v_rcp_f32_e32 v16, v13
	s_nop 0
	v_mul_f32_e32 v13, v8, v16
	v_rcp_f32_e32 v15, v12
	s_nop 0
	v_mul_f32_e32 v12, v14, v15
	s_waitcnt vmcnt(0)
	v_lshlrev_b32_e32 v14, 16, v4
	v_and_b32_e32 v15, 0xffff0000, v4
	v_pk_mul_f32 v[12:13], v[12:13], v[14:15]
	s_nop 0
	v_cvt_pk_bf16_f32 v4, v12, v13
	v_lshlrev_b32_e32 v12, 16, v9
	v_and_b32_e32 v13, 0xffff0000, v9
	v_mul_f32_e32 v8, 0xbfb8aa3b, v12
	v_mul_f32_e32 v9, 0xbfb8aa3b, v13
	v_exp_f32_e32 v8, v8
	v_exp_f32_e32 v9, v9
	s_nop 0
	v_pk_add_f32 v[8:9], v[8:9], 1.0 op_sel_hi:[1,0]
	s_nop 0
	v_rcp_f32_e32 v15, v9
	s_nop 0
	v_mul_f32_e32 v9, v13, v15
	v_rcp_f32_e32 v14, v8
	s_nop 0
	v_mul_f32_e32 v8, v12, v14
	v_lshlrev_b32_e32 v12, 16, v5
	v_and_b32_e32 v13, 0xffff0000, v5
	v_pk_mul_f32 v[8:9], v[8:9], v[12:13]
	v_lshlrev_b32_e32 v12, 16, v10
	v_and_b32_e32 v10, 0xffff0000, v10
	v_cvt_pk_bf16_f32 v5, v8, v9
	v_mul_f32_e32 v8, 0xbfb8aa3b, v12
	v_mul_f32_e32 v9, 0xbfb8aa3b, v10
	v_exp_f32_e32 v8, v8
	v_exp_f32_e32 v9, v9
	s_nop 0
	v_pk_add_f32 v[8:9], v[8:9], 1.0 op_sel_hi:[1,0]
	s_nop 0
	v_rcp_f32_e32 v14, v9
	s_nop 0
	v_mul_f32_e32 v9, v10, v14
	v_rcp_f32_e32 v13, v8
	s_nop 0
	v_mul_f32_e32 v8, v12, v13
	v_lshlrev_b32_e32 v12, 16, v6
	v_and_b32_e32 v13, 0xffff0000, v6
	v_pk_mul_f32 v[8:9], v[8:9], v[12:13]
	v_lshlrev_b32_e32 v10, 16, v11
	v_and_b32_e32 v11, 0xffff0000, v11
	v_cvt_pk_bf16_f32 v6, v8, v9
	v_mul_f32_e32 v8, 0xbfb8aa3b, v10
	v_mul_f32_e32 v9, 0xbfb8aa3b, v11
	v_exp_f32_e32 v8, v8
	v_exp_f32_e32 v9, v9
	s_nop 0
	v_pk_add_f32 v[8:9], v[8:9], 1.0 op_sel_hi:[1,0]
	s_nop 0
	v_rcp_f32_e32 v13, v9
	s_nop 0
	v_mul_f32_e32 v9, v11, v13
	v_rcp_f32_e32 v12, v8
	s_nop 0
	v_mul_f32_e32 v8, v10, v12
	v_lshlrev_b32_e32 v10, 16, v7
	v_and_b32_e32 v11, 0xffff0000, v7
	v_pk_mul_f32 v[8:9], v[8:9], v[10:11]
	s_nop 0
	v_cvt_pk_bf16_f32 v7, v8, v9
	global_store_dwordx4 v[0:1], v[4:7], off
	v_add_u32_e32 v0, 0x500, v2
	v_ashrrev_i32_e32 v1, 31, v0
	v_lshrrev_b32_e32 v1, 28, v1
	v_add_u32_e32 v1, v0, v1
	v_ashrrev_i32_e32 v4, 4, v1
	v_and_b32_e32 v1, -16, v1
	v_sub_u32_e32 v5, v0, v1
	v_mul_lo_u32 v6, v4, s52
	v_lshlrev_b32_e32 v0, 3, v5
	v_lshl_add_u32 v5, v5, 4, v6
	v_add_u32_e32 v4, s18, v4
	ds_read_b128 v[8:11], v5
	v_mad_i64_i32 v[4:5], s[0:1], s13, v4, 0
	v_ashrrev_i32_e32 v1, 31, v0
	v_lshl_add_u64 v[4:5], v[4:5], 1, s[10:11]
	v_lshl_add_u64 v[0:1], v[0:1], 1, v[4:5]
	global_load_dwordx4 v[4:7], v[0:1], off
	s_waitcnt lgkmcnt(0)
	v_lshlrev_b32_e32 v14, 16, v8
	v_and_b32_e32 v8, 0xffff0000, v8
	v_mul_f32_e32 v12, 0xbfb8aa3b, v14
	v_mul_f32_e32 v13, 0xbfb8aa3b, v8
	v_exp_f32_e32 v12, v12
	v_exp_f32_e32 v13, v13
	s_nop 0
	v_pk_add_f32 v[12:13], v[12:13], 1.0 op_sel_hi:[1,0]
	s_nop 0
	v_rcp_f32_e32 v16, v13
	s_nop 0
	v_mul_f32_e32 v13, v8, v16
	v_rcp_f32_e32 v15, v12
	s_nop 0
	v_mul_f32_e32 v12, v14, v15
	s_waitcnt vmcnt(0)
; __device__ void phase_gates(PRef p, int l, const bf16* H2, bf16* sA, bf16* sB) {
;     ...
;     TILE_CHUNKS(2, sA, {
;       u32x4* pp = (u32x4*)(dst + (size_t)(rt * 128 + trow) * ld + c0 + tcol);
;       u32x4 yv = *pp;
;       u32x4 ov;
;       _Pragma("unroll") for (int j = 0; j < 4; j++) {
;         float g0 = __uint_as_float(cv[j] << 16), g1 = __uint_as_float(cv[j] & 0xffff0000u);
;         g0 = g0 / (1.f + __expf(-g0));
;         g1 = g1 / (1.f + __expf(-g1));
;         float y0 = __uint_as_float(yv[j] << 16), y1 = __uint_as_float(yv[j] & 0xffff0000u);
;         ov[j] = pack2(y0 * g0, y1 * g1);
;       }
;       *pp = ov;
;     })
	v_lshlrev_b32_e32 v14, 16, v4
	v_and_b32_e32 v15, 0xffff0000, v4
	v_pk_mul_f32 v[12:13], v[12:13], v[14:15]
	s_nop 0
	v_cvt_pk_bf16_f32 v4, v12, v13
	v_lshlrev_b32_e32 v12, 16, v9
	v_and_b32_e32 v13, 0xffff0000, v9
	v_mul_f32_e32 v8, 0xbfb8aa3b, v12
	v_mul_f32_e32 v9, 0xbfb8aa3b, v13
	v_exp_f32_e32 v8, v8
	v_exp_f32_e32 v9, v9
	s_nop 0
	v_pk_add_f32 v[8:9], v[8:9], 1.0 op_sel_hi:[1,0]
	s_nop 0
	v_rcp_f32_e32 v15, v9
	s_nop 0
	v_mul_f32_e32 v9, v13, v15
	v_rcp_f32_e32 v14, v8
	s_nop 0
	v_mul_f32_e32 v8, v12, v14
	v_lshlrev_b32_e32 v12, 16, v5
	v_and_b32_e32 v13, 0xffff0000, v5
	v_pk_mul_f32 v[8:9], v[8:9], v[12:13]
	v_lshlrev_b32_e32 v12, 16, v10
	v_and_b32_e32 v10, 0xffff0000, v10
	v_cvt_pk_bf16_f32 v5, v8, v9
	v_mul_f32_e32 v8, 0xbfb8aa3b, v12
	v_mul_f32_e32 v9, 0xbfb8aa3b, v10
	v_exp_f32_e32 v8, v8
	v_exp_f32_e32 v9, v9
	s_nop 0
	v_pk_add_f32 v[8:9], v[8:9], 1.0 op_sel_hi:[1,0]
	s_nop 0
	v_rcp_f32_e32 v14, v9
	s_nop 0
	v_mul_f32_e32 v9, v10, v14
	v_rcp_f32_e32 v13, v8
	s_nop 0
	v_mul_f32_e32 v8, v12, v13
	v_lshlrev_b32_e32 v12, 16, v6
	v_and_b32_e32 v13, 0xffff0000, v6
	v_pk_mul_f32 v[8:9], v[8:9], v[12:13]
	v_lshlrev_b32_e32 v10, 16, v11
	v_and_b32_e32 v11, 0xffff0000, v11
	v_cvt_pk_bf16_f32 v6, v8, v9
	v_mul_f32_e32 v8, 0xbfb8aa3b, v10
	v_mul_f32_e32 v9, 0xbfb8aa3b, v11
	v_exp_f32_e32 v8, v8
	v_exp_f32_e32 v9, v9
	s_nop 0
	v_pk_add_f32 v[8:9], v[8:9], 1.0 op_sel_hi:[1,0]
	s_nop 0
	v_rcp_f32_e32 v13, v9
	s_nop 0
	v_mul_f32_e32 v9, v11, v13
	v_rcp_f32_e32 v12, v8
	s_nop 0
	v_mul_f32_e32 v8, v10, v12
	v_lshlrev_b32_e32 v10, 16, v7
	v_and_b32_e32 v11, 0xffff0000, v7
	v_pk_mul_f32 v[8:9], v[8:9], v[10:11]
	s_nop 0
	v_cvt_pk_bf16_f32 v7, v8, v9
	global_store_dwordx4 v[0:1], v[4:7], off
	v_add_u32_e32 v0, 0x600, v2
	v_ashrrev_i32_e32 v1, 31, v0
	v_lshrrev_b32_e32 v1, 28, v1
	v_add_u32_e32 v1, v0, v1
	v_ashrrev_i32_e32 v4, 4, v1
	v_and_b32_e32 v1, -16, v1
	v_sub_u32_e32 v5, v0, v1
	v_mul_lo_u32 v6, v4, s52
	v_lshlrev_b32_e32 v0, 3, v5
	v_lshl_add_u32 v5, v5, 4, v6
	v_add_u32_e32 v4, s18, v4
	ds_read_b128 v[8:11], v5
	v_mad_i64_i32 v[4:5], s[0:1], s13, v4, 0
	v_ashrrev_i32_e32 v1, 31, v0
	v_lshl_add_u64 v[4:5], v[4:5], 1, s[10:11]
	v_lshl_add_u64 v[0:1], v[0:1], 1, v[4:5]
	global_load_dwordx4 v[4:7], v[0:1], off
	s_waitcnt lgkmcnt(0)
	v_lshlrev_b32_e32 v14, 16, v8
	v_and_b32_e32 v8, 0xffff0000, v8
	v_mul_f32_e32 v12, 0xbfb8aa3b, v14
	v_mul_f32_e32 v13, 0xbfb8aa3b, v8
	v_exp_f32_e32 v12, v12
	v_exp_f32_e32 v13, v13
	s_nop 0
	v_pk_add_f32 v[12:13], v[12:13], 1.0 op_sel_hi:[1,0]
	s_nop 0
	v_rcp_f32_e32 v16, v13
	s_nop 0
	v_mul_f32_e32 v13, v8, v16
	v_rcp_f32_e32 v15, v12
	s_nop 0
	v_mul_f32_e32 v12, v14, v15
	s_waitcnt vmcnt(0)
	v_lshlrev_b32_e32 v14, 16, v4
	v_and_b32_e32 v15, 0xffff0000, v4
	v_pk_mul_f32 v[12:13], v[12:13], v[14:15]
	s_nop 0
	v_cvt_pk_bf16_f32 v4, v12, v13
	v_lshlrev_b32_e32 v12, 16, v9
	v_and_b32_e32 v13, 0xffff0000, v9
	v_mul_f32_e32 v8, 0xbfb8aa3b, v12
	v_mul_f32_e32 v9, 0xbfb8aa3b, v13
	v_exp_f32_e32 v8, v8
	v_exp_f32_e32 v9, v9
	s_nop 0
	v_pk_add_f32 v[8:9], v[8:9], 1.0 op_sel_hi:[1,0]
	s_nop 0
	v_rcp_f32_e32 v15, v9
	s_nop 0
	v_mul_f32_e32 v9, v13, v15
	v_rcp_f32_e32 v14, v8
	s_nop 0
	v_mul_f32_e32 v8, v12, v14
	v_lshlrev_b32_e32 v12, 16, v5
	v_and_b32_e32 v13, 0xffff0000, v5
	v_pk_mul_f32 v[8:9], v[8:9], v[12:13]
	v_lshlrev_b32_e32 v12, 16, v10
	v_and_b32_e32 v10, 0xffff0000, v10
	v_cvt_pk_bf16_f32 v5, v8, v9
	v_mul_f32_e32 v8, 0xbfb8aa3b, v12
	v_mul_f32_e32 v9, 0xbfb8aa3b, v10
	v_exp_f32_e32 v8, v8
	v_exp_f32_e32 v9, v9
	s_nop 0
	v_pk_add_f32 v[8:9], v[8:9], 1.0 op_sel_hi:[1,0]
	s_nop 0
	v_rcp_f32_e32 v14, v9
	s_nop 0
	v_mul_f32_e32 v9, v10, v14
	v_rcp_f32_e32 v13, v8
	s_nop 0
	v_mul_f32_e32 v8, v12, v13
	v_lshlrev_b32_e32 v12, 16, v6
	v_and_b32_e32 v13, 0xffff0000, v6
	v_pk_mul_f32 v[8:9], v[8:9], v[12:13]
	v_lshlrev_b32_e32 v10, 16, v11
	v_and_b32_e32 v11, 0xffff0000, v11
	v_cvt_pk_bf16_f32 v6, v8, v9
	v_mul_f32_e32 v8, 0xbfb8aa3b, v10
	v_mul_f32_e32 v9, 0xbfb8aa3b, v11
	v_exp_f32_e32 v8, v8
	v_exp_f32_e32 v9, v9
	s_nop 0
	v_pk_add_f32 v[8:9], v[8:9], 1.0 op_sel_hi:[1,0]
	s_nop 0
	v_rcp_f32_e32 v13, v9
	s_nop 0
	v_mul_f32_e32 v9, v11, v13
	v_rcp_f32_e32 v12, v8
	s_nop 0
	v_mul_f32_e32 v8, v10, v12
	v_lshlrev_b32_e32 v10, 16, v7
	v_and_b32_e32 v11, 0xffff0000, v7
	v_pk_mul_f32 v[8:9], v[8:9], v[10:11]
	s_nop 0
	v_cvt_pk_bf16_f32 v7, v8, v9
	global_store_dwordx4 v[0:1], v[4:7], off
	v_add_u32_e32 v0, 0x700, v2
	v_ashrrev_i32_e32 v1, 31, v0
	v_lshrrev_b32_e32 v1, 28, v1
	v_add_u32_e32 v1, v0, v1
	v_ashrrev_i32_e32 v2, 4, v1
	v_and_b32_e32 v1, -16, v1
	v_sub_u32_e32 v4, v0, v1
	v_mul_lo_u32 v5, v2, s52
	v_lshlrev_b32_e32 v0, 3, v4
	v_lshl_add_u32 v4, v4, 4, v5
	v_add_u32_e32 v2, s18, v2
	ds_read_b128 v[8:11], v4
	v_mad_i64_i32 v[4:5], s[0:1], s13, v2, 0
	v_ashrrev_i32_e32 v1, 31, v0
	v_lshl_add_u64 v[4:5], v[4:5], 1, s[10:11]
	v_lshl_add_u64 v[0:1], v[0:1], 1, v[4:5]
	global_load_dwordx4 v[4:7], v[0:1], off
	s_waitcnt lgkmcnt(0)
	v_lshlrev_b32_e32 v2, 16, v8
	v_and_b32_e32 v8, 0xffff0000, v8
	v_mul_f32_e32 v12, 0xbfb8aa3b, v2
	v_mul_f32_e32 v13, 0xbfb8aa3b, v8
	v_exp_f32_e32 v12, v12
	v_exp_f32_e32 v13, v13
	s_nop 0
	v_pk_add_f32 v[12:13], v[12:13], 1.0 op_sel_hi:[1,0]
	s_nop 0
	v_rcp_f32_e32 v15, v13
	s_nop 0
	v_mul_f32_e32 v13, v8, v15
	v_rcp_f32_e32 v14, v12
	s_nop 0
	v_mul_f32_e32 v12, v2, v14
	v_lshlrev_b32_e32 v2, 16, v9
	v_mul_f32_e32 v8, 0xbfb8aa3b, v2
	v_exp_f32_e32 v8, v8
	s_waitcnt vmcnt(0)
	v_lshlrev_b32_e32 v14, 16, v4
	v_and_b32_e32 v15, 0xffff0000, v4
	v_pk_mul_f32 v[12:13], v[12:13], v[14:15]
	s_nop 0
	v_cvt_pk_bf16_f32 v4, v12, v13
	v_and_b32_e32 v12, 0xffff0000, v9
	v_mul_f32_e32 v9, 0xbfb8aa3b, v12
	v_exp_f32_e32 v9, v9
	s_nop 0
	v_pk_add_f32 v[8:9], v[8:9], 1.0 op_sel_hi:[1,0]
	s_nop 0
	v_rcp_f32_e32 v14, v9
	s_nop 0
	v_mul_f32_e32 v9, v12, v14
	v_rcp_f32_e32 v13, v8
	s_nop 0
	v_mul_f32_e32 v8, v2, v13
	v_lshlrev_b32_e32 v12, 16, v5
	v_and_b32_e32 v13, 0xffff0000, v5
	v_pk_mul_f32 v[8:9], v[8:9], v[12:13]
	v_lshlrev_b32_e32 v2, 16, v10
	v_and_b32_e32 v10, 0xffff0000, v10
	v_cvt_pk_bf16_f32 v5, v8, v9
	v_mul_f32_e32 v8, 0xbfb8aa3b, v2
	v_mul_f32_e32 v9, 0xbfb8aa3b, v10
	v_exp_f32_e32 v8, v8
	v_exp_f32_e32 v9, v9
	s_nop 0
	v_pk_add_f32 v[8:9], v[8:9], 1.0 op_sel_hi:[1,0]
	s_nop 0
	v_rcp_f32_e32 v13, v9
	s_nop 0
	v_mul_f32_e32 v9, v10, v13
	v_rcp_f32_e32 v12, v8
	s_nop 0
	v_mul_f32_e32 v8, v2, v12
	v_lshlrev_b32_e32 v12, 16, v6
	v_and_b32_e32 v13, 0xffff0000, v6
	v_pk_mul_f32 v[8:9], v[8:9], v[12:13]
	v_lshlrev_b32_e32 v2, 16, v11
	v_and_b32_e32 v10, 0xffff0000, v11
	v_cvt_pk_bf16_f32 v6, v8, v9
	v_mul_f32_e32 v8, 0xbfb8aa3b, v2
	v_mul_f32_e32 v9, 0xbfb8aa3b, v10
	v_exp_f32_e32 v8, v8
	v_exp_f32_e32 v9, v9
	s_nop 0
	v_pk_add_f32 v[8:9], v[8:9], 1.0 op_sel_hi:[1,0]
	s_nop 0
	v_rcp_f32_e32 v12, v9
	s_nop 0
	v_mul_f32_e32 v9, v10, v12
	v_rcp_f32_e32 v11, v8
	s_nop 0
	v_mul_f32_e32 v8, v2, v11
	v_lshlrev_b32_e32 v10, 16, v7
	v_and_b32_e32 v11, 0xffff0000, v7
	v_pk_mul_f32 v[8:9], v[8:9], v[10:11]
	s_nop 0
	v_cvt_pk_bf16_f32 v7, v8, v9
	global_store_dwordx4 v[0:1], v[4:7], off

; __device__ void phase_merge(PRef p, int l, const bf16* H2, bf16* M, bf16* sA, bf16* sB) {
;     ...
; #pragma unroll
;         for (int a = 0; a < 2; a++)
; #pragma unroll
;           for (int bb = 0; bb < 2; bb++)
; #pragma unroll
;             for (int r = 0; r < 8; r++) {
;               float g0 = __fdividef(1.f, 1.f + __expf(-a2[a][bb][2 * r]));
;               float g1 = __fdividef(1.f, 1.f + __expf(-a2[a][bb][2 * r + 1]));
;               gp[a][bb][r] = pack2(g0, g1);
;             }
.LBB0_972:
	v_mul_f32_e32 v0, 0xbfb8aa3b, v116
	v_mul_f32_e32 v1, 0xbfb8aa3b, v117
	v_exp_f32_e32 v0, v0
	v_exp_f32_e32 v1, v1
	v_mul_f32_e32 v100, 0xbfb8aa3b, v100
	v_mul_f32_e32 v101, 0xbfb8aa3b, v101
	v_exp_f32_e32 v100, v100
	v_pk_add_f32 v[0:1], v[0:1], 1.0 op_sel_hi:[1,0]
	v_exp_f32_e32 v101, v101
	v_div_scale_f32 v2, s[0:1], v1, v1, 1.0
	v_rcp_f32_e32 v116, v2
	v_pk_add_f32 v[100:101], v[100:101], 1.0 op_sel_hi:[1,0]
	v_mul_f32_e32 v68, 0xbfb8aa3b, v68
	v_mul_f32_e32 v69, 0xbfb8aa3b, v69
	v_fma_f32 v117, -v2, v116, 1.0
	v_fmac_f32_e32 v116, v117, v116
	v_div_scale_f32 v117, vcc, 1.0, v1, 1.0
	v_mul_f32_e32 v133, v117, v116
	s_waitcnt vmcnt(6)
	v_fma_f32 v134, -v2, v133, v117
	v_fmac_f32_e32 v133, v134, v116
	v_fma_f32 v2, -v2, v133, v117
	v_div_fmas_f32 v2, v2, v116, v133
	v_div_fixup_f32 v1, v2, v1, 1.0
	v_div_scale_f32 v2, s[0:1], v0, v0, 1.0
	v_rcp_f32_e32 v116, v2
	v_exp_f32_e32 v68, v68
	v_exp_f32_e32 v69, v69
	v_mul_f32_e32 v4, 0xbfb8aa3b, v4
	v_fma_f32 v117, -v2, v116, 1.0
	v_fmac_f32_e32 v116, v117, v116
	v_div_scale_f32 v117, vcc, 1.0, v0, 1.0
	v_mul_f32_e32 v133, v117, v116
	v_fma_f32 v134, -v2, v133, v117
	v_fmac_f32_e32 v133, v134, v116
	v_fma_f32 v2, -v2, v133, v117
	v_div_fmas_f32 v2, v2, v116, v133
	v_div_fixup_f32 v0, v2, v0, 1.0
	v_cvt_pk_bf16_f32 v0, v0, v1
	v_mul_f32_e32 v1, 0xbfb8aa3b, v118
	v_exp_f32_e32 v116, v1
	v_mul_f32_e32 v1, 0xbfb8aa3b, v119
	v_exp_f32_e32 v117, v1
	v_pk_add_f32 v[68:69], v[68:69], 1.0 op_sel_hi:[1,0]
	v_mul_f32_e32 v5, 0xbfb8aa3b, v5
	v_exp_f32_e32 v4, v4
	v_pk_add_f32 v[116:117], v[116:117], 1.0 op_sel_hi:[1,0]
	v_exp_f32_e32 v5, v5
	v_div_scale_f32 v1, s[0:1], v117, v117, 1.0
	v_rcp_f32_e32 v2, v1
	v_pk_add_f32 v[4:5], v[4:5], 1.0 op_sel_hi:[1,0]
	s_cmp_lg_u32 s95, 0
	s_cselect_b64 s[54:55], -1, 0
	v_fma_f32 v118, -v1, v2, 1.0
	v_fmac_f32_e32 v2, v118, v2
	v_div_scale_f32 v118, vcc, 1.0, v117, 1.0
	v_mul_f32_e32 v119, v118, v2
	v_fma_f32 v133, -v1, v119, v118
	v_fmac_f32_e32 v119, v133, v2
	v_fma_f32 v1, -v1, v119, v118
	v_div_fmas_f32 v1, v1, v2, v119
	v_div_scale_f32 v2, s[0:1], v116, v116, 1.0
	v_div_fixup_f32 v1, v1, v117, 1.0
	v_rcp_f32_e32 v117, v2
	s_nop 0
	v_fma_f32 v118, -v2, v117, 1.0
	v_fmac_f32_e32 v117, v118, v117
	v_div_scale_f32 v118, vcc, 1.0, v116, 1.0
	v_mul_f32_e32 v119, v118, v117
	v_fma_f32 v133, -v2, v119, v118
	v_fmac_f32_e32 v119, v133, v117
	v_fma_f32 v2, -v2, v119, v118
	v_div_fmas_f32 v2, v2, v117, v119
	v_div_fixup_f32 v2, v2, v116, 1.0
	v_cvt_pk_bf16_f32 v1, v2, v1
	v_mul_f32_e32 v2, 0xbfb8aa3b, v120
	v_exp_f32_e32 v116, v2
	v_mul_f32_e32 v2, 0xbfb8aa3b, v121
	v_exp_f32_e32 v117, v2
	s_nop 0
	v_pk_add_f32 v[116:117], v[116:117], 1.0 op_sel_hi:[1,0]
	s_nop 0
	v_rcp_f32_e32 v118, v117
	s_nop 0
	v_mul_f32_e32 v2, 1.0, v118
	v_rcp_f32_e32 v118, v116
	s_nop 0
	v_mul_f32_e32 v116, 1.0, v118
	v_cvt_pk_bf16_f32 v2, v116, v2
	v_mul_f32_e32 v116, 0xbfb8aa3b, v122
	v_mul_f32_e32 v117, 0xbfb8aa3b, v123
	v_exp_f32_e32 v116, v116
	v_exp_f32_e32 v117, v117
	s_nop 0
	v_pk_add_f32 v[116:117], v[116:117], 1.0 op_sel_hi:[1,0]
	s_nop 0
	v_rcp_f32_e32 v119, v117
	s_nop 0
	v_mul_f32_e32 v117, 1.0, v119
	v_rcp_f32_e32 v119, v116
	s_nop 0
	v_mul_f32_e32 v116, 1.0, v119
	v_cvt_pk_bf16_f32 v116, v116, v117
	v_mul_f32_e32 v117, 0xbfb8aa3b, v124
	v_exp_f32_e32 v118, v117
	v_mul_f32_e32 v117, 0xbfb8aa3b, v125
	v_exp_f32_e32 v119, v117
	s_nop 0
	v_pk_add_f32 v[118:119], v[118:119], 1.0 op_sel_hi:[1,0]
	s_nop 0
	v_rcp_f32_e32 v120, v119
	s_nop 0
	v_mul_f32_e32 v117, 1.0, v120
	v_rcp_f32_e32 v120, v118
	s_nop 0
	v_mul_f32_e32 v118, 1.0, v120
	v_cvt_pk_bf16_f32 v117, v118, v117
	v_mul_f32_e32 v118, 0xbfb8aa3b, v126
	v_mul_f32_e32 v119, 0xbfb8aa3b, v127
	v_exp_f32_e32 v118, v118
	v_exp_f32_e32 v119, v119
	s_nop 0
	v_pk_add_f32 v[118:119], v[118:119], 1.0 op_sel_hi:[1,0]
	s_nop 0
	v_rcp_f32_e32 v121, v119
	s_nop 0
	v_mul_f32_e32 v119, 1.0, v121
	v_rcp_f32_e32 v121, v118
	s_nop 0
	v_mul_f32_e32 v118, 1.0, v121
	v_cvt_pk_bf16_f32 v118, v118, v119
	v_mul_f32_e32 v119, 0xbfb8aa3b, v128
	v_exp_f32_e32 v120, v119
	v_mul_f32_e32 v119, 0xbfb8aa3b, v129
	v_exp_f32_e32 v121, v119
	s_nop 0
	v_pk_add_f32 v[120:121], v[120:121], 1.0 op_sel_hi:[1,0]
	s_nop 0
	v_rcp_f32_e32 v122, v121
	s_nop 0
	v_mul_f32_e32 v119, 1.0, v122
	v_rcp_f32_e32 v122, v120
	s_nop 0
	v_mul_f32_e32 v120, 1.0, v122
	v_cvt_pk_bf16_f32 v119, v120, v119
	v_mul_f32_e32 v120, 0xbfb8aa3b, v130
	v_mul_f32_e32 v121, 0xbfb8aa3b, v131
	v_exp_f32_e32 v120, v120
	v_exp_f32_e32 v121, v121
	s_nop 0
	v_pk_add_f32 v[120:121], v[120:121], 1.0 op_sel_hi:[1,0]
	s_nop 0
	v_rcp_f32_e32 v123, v121
	s_nop 0
	v_mul_f32_e32 v121, 1.0, v123
	v_rcp_f32_e32 v123, v120
	s_nop 0
	v_mul_f32_e32 v120, 1.0, v123
	v_cvt_pk_bf16_f32 v120, v120, v121
	v_rcp_f32_e32 v122, v101
	s_nop 0
	v_mul_f32_e32 v101, 1.0, v122
	v_rcp_f32_e32 v122, v100
	s_nop 0
	v_mul_f32_e32 v100, 1.0, v122
	v_cvt_pk_bf16_f32 v100, v100, v101
	v_mul_f32_e32 v101, 0xbfb8aa3b, v102
	v_exp_f32_e32 v102, v101
	v_mul_f32_e32 v101, 0xbfb8aa3b, v103
	v_exp_f32_e32 v103, v101
	s_nop 0
	v_pk_add_f32 v[102:103], v[102:103], 1.0 op_sel_hi:[1,0]
	s_nop 0
	v_rcp_f32_e32 v121, v103
	s_nop 0
	v_mul_f32_e32 v101, 1.0, v121
	v_rcp_f32_e32 v121, v102
	s_nop 0
	v_mul_f32_e32 v102, 1.0, v121
	v_cvt_pk_bf16_f32 v101, v102, v101
	v_mul_f32_e32 v102, 0xbfb8aa3b, v104
	v_mul_f32_e32 v103, 0xbfb8aa3b, v105
	v_exp_f32_e32 v102, v102
	v_exp_f32_e32 v103, v103
	s_nop 0
	v_pk_add_f32 v[102:103], v[102:103], 1.0 op_sel_hi:[1,0]
	s_nop 0
	v_rcp_f32_e32 v105, v103
	s_nop 0
	v_mul_f32_e32 v103, 1.0, v105
	v_rcp_f32_e32 v105, v102
	s_nop 0
	v_mul_f32_e32 v102, 1.0, v105
	v_cvt_pk_bf16_f32 v102, v102, v103
; __device__ void phase_merge(PRef p, int l, const bf16* H2, bf16* M, bf16* sA, bf16* sB) {
;     ...
; #pragma unroll
;         for (int a = 0; a < 2; a++)
; #pragma unroll
;           for (int bb = 0; bb < 2; bb++)
; #pragma unroll
;             for (int r = 0; r < 8; r++) {
;               float g0 = __fdividef(1.f, 1.f + __expf(-a2[a][bb][2 * r]));
;               float g1 = __fdividef(1.f, 1.f + __expf(-a2[a][bb][2 * r + 1]));
;               gp[a][bb][r] = pack2(g0, g1);
;             }
	v_mul_f32_e32 v103, 0xbfb8aa3b, v106
	v_exp_f32_e32 v104, v103
	v_mul_f32_e32 v103, 0xbfb8aa3b, v107
	v_exp_f32_e32 v105, v103
	s_nop 0
	v_pk_add_f32 v[104:105], v[104:105], 1.0 op_sel_hi:[1,0]
	s_nop 0
	v_rcp_f32_e32 v106, v105
	s_nop 0
	v_mul_f32_e32 v103, 1.0, v106
	v_rcp_f32_e32 v106, v104
	s_nop 0
	v_mul_f32_e32 v104, 1.0, v106
	v_cvt_pk_bf16_f32 v103, v104, v103
	v_mul_f32_e32 v104, 0xbfb8aa3b, v108
	v_mul_f32_e32 v105, 0xbfb8aa3b, v109
	v_exp_f32_e32 v104, v104
	v_exp_f32_e32 v105, v105
	s_nop 0
	v_pk_add_f32 v[104:105], v[104:105], 1.0 op_sel_hi:[1,0]
	s_nop 0
	v_rcp_f32_e32 v107, v105
	s_nop 0
	v_mul_f32_e32 v105, 1.0, v107
	v_rcp_f32_e32 v107, v104
	s_nop 0
	v_mul_f32_e32 v104, 1.0, v107
	v_cvt_pk_bf16_f32 v104, v104, v105
	v_mul_f32_e32 v105, 0xbfb8aa3b, v110
	v_exp_f32_e32 v106, v105
	v_mul_f32_e32 v105, 0xbfb8aa3b, v111
	v_exp_f32_e32 v107, v105
	s_nop 0
	v_pk_add_f32 v[106:107], v[106:107], 1.0 op_sel_hi:[1,0]
	s_nop 0
	v_rcp_f32_e32 v108, v107
	s_nop 0
	v_mul_f32_e32 v105, 1.0, v108
	v_rcp_f32_e32 v108, v106
	s_nop 0
	v_mul_f32_e32 v106, 1.0, v108
	v_cvt_pk_bf16_f32 v105, v106, v105
	v_mul_f32_e32 v106, 0xbfb8aa3b, v112
	v_mul_f32_e32 v107, 0xbfb8aa3b, v113
	v_exp_f32_e32 v106, v106
	v_exp_f32_e32 v107, v107
	s_nop 0
	v_pk_add_f32 v[106:107], v[106:107], 1.0 op_sel_hi:[1,0]
	s_nop 0
	v_rcp_f32_e32 v109, v107
	s_nop 0
	v_mul_f32_e32 v107, 1.0, v109
	v_rcp_f32_e32 v109, v106
	s_nop 0
	v_mul_f32_e32 v106, 1.0, v109
	v_cvt_pk_bf16_f32 v106, v106, v107
	v_mul_f32_e32 v107, 0xbfb8aa3b, v114
	v_exp_f32_e32 v108, v107
	v_mul_f32_e32 v107, 0xbfb8aa3b, v115
	v_exp_f32_e32 v109, v107
	s_nop 0
	v_pk_add_f32 v[108:109], v[108:109], 1.0 op_sel_hi:[1,0]
	s_nop 0
	v_rcp_f32_e32 v110, v109
	s_nop 0
	v_mul_f32_e32 v107, 1.0, v110
	v_rcp_f32_e32 v110, v108
	s_nop 0
	v_mul_f32_e32 v108, 1.0, v110
	v_cvt_pk_bf16_f32 v107, v108, v107
	v_rcp_f32_e32 v109, v69
	s_nop 0
	v_mul_f32_e32 v69, 1.0, v109
	v_rcp_f32_e32 v109, v68
	s_nop 0
	v_mul_f32_e32 v68, 1.0, v109
	v_cvt_pk_bf16_f32 v68, v68, v69
	v_mul_f32_e32 v69, 0xbfb8aa3b, v70
	v_exp_f32_e32 v70, v69
	v_mul_f32_e32 v69, 0xbfb8aa3b, v71
	v_exp_f32_e32 v71, v69
	s_nop 0
	v_pk_add_f32 v[70:71], v[70:71], 1.0 op_sel_hi:[1,0]
	s_nop 0
	v_rcp_f32_e32 v108, v71
	s_nop 0
	v_mul_f32_e32 v69, 1.0, v108
	v_rcp_f32_e32 v108, v70
	s_nop 0
	v_mul_f32_e32 v70, 1.0, v108
	v_cvt_pk_bf16_f32 v69, v70, v69
	v_mul_f32_e32 v70, 0xbfb8aa3b, v72
	v_mul_f32_e32 v71, 0xbfb8aa3b, v73
	v_exp_f32_e32 v70, v70
	v_exp_f32_e32 v71, v71
	s_nop 0
	v_pk_add_f32 v[70:71], v[70:71], 1.0 op_sel_hi:[1,0]
	s_nop 0
	v_rcp_f32_e32 v73, v71
	s_nop 0
	v_mul_f32_e32 v71, 1.0, v73
	v_rcp_f32_e32 v73, v70
	s_nop 0
	v_mul_f32_e32 v70, 1.0, v73
	v_cvt_pk_bf16_f32 v70, v70, v71
	v_mul_f32_e32 v71, 0xbfb8aa3b, v74
	v_exp_f32_e32 v72, v71
	v_mul_f32_e32 v71, 0xbfb8aa3b, v75
	v_exp_f32_e32 v73, v71
	s_nop 0
	v_pk_add_f32 v[72:73], v[72:73], 1.0 op_sel_hi:[1,0]
	s_nop 0
	v_rcp_f32_e32 v74, v73
	s_nop 0
	v_mul_f32_e32 v71, 1.0, v74
	v_rcp_f32_e32 v74, v72
	s_nop 0
	v_mul_f32_e32 v72, 1.0, v74
	v_cvt_pk_bf16_f32 v71, v72, v71
	v_mul_f32_e32 v72, 0xbfb8aa3b, v76
	v_mul_f32_e32 v73, 0xbfb8aa3b, v77
	v_exp_f32_e32 v72, v72
	v_exp_f32_e32 v73, v73
	s_nop 0
	v_pk_add_f32 v[72:73], v[72:73], 1.0 op_sel_hi:[1,0]
	s_nop 0
	v_rcp_f32_e32 v75, v73
	s_nop 0
	v_mul_f32_e32 v73, 1.0, v75
	v_rcp_f32_e32 v75, v72
	s_nop 0
	v_mul_f32_e32 v72, 1.0, v75
	v_cvt_pk_bf16_f32 v72, v72, v73
	v_mul_f32_e32 v73, 0xbfb8aa3b, v78
	v_exp_f32_e32 v74, v73
	v_mul_f32_e32 v73, 0xbfb8aa3b, v79
	v_exp_f32_e32 v75, v73
	s_nop 0
	v_pk_add_f32 v[74:75], v[74:75], 1.0 op_sel_hi:[1,0]
	s_nop 0
	v_rcp_f32_e32 v76, v75
	s_nop 0
	v_mul_f32_e32 v73, 1.0, v76
	v_rcp_f32_e32 v76, v74
	s_nop 0
	v_mul_f32_e32 v74, 1.0, v76
	v_cvt_pk_bf16_f32 v73, v74, v73
	v_mul_f32_e32 v74, 0xbfb8aa3b, v80
	v_mul_f32_e32 v75, 0xbfb8aa3b, v81
	v_exp_f32_e32 v74, v74
	v_exp_f32_e32 v75, v75
	s_nop 0
	v_pk_add_f32 v[74:75], v[74:75], 1.0 op_sel_hi:[1,0]
	s_nop 0
	v_rcp_f32_e32 v77, v75
	s_nop 0
	v_mul_f32_e32 v75, 1.0, v77
	v_rcp_f32_e32 v77, v74
	s_nop 0
	v_mul_f32_e32 v74, 1.0, v77
	v_cvt_pk_bf16_f32 v74, v74, v75
	v_mul_f32_e32 v75, 0xbfb8aa3b, v82
	v_exp_f32_e32 v76, v75
	v_mul_f32_e32 v75, 0xbfb8aa3b, v83
	v_exp_f32_e32 v77, v75
	s_nop 0
	v_pk_add_f32 v[76:77], v[76:77], 1.0 op_sel_hi:[1,0]
	s_nop 0
	v_rcp_f32_e32 v78, v77
	s_nop 0
	v_mul_f32_e32 v75, 1.0, v78
	v_rcp_f32_e32 v78, v76
	s_nop 0
	v_mul_f32_e32 v76, 1.0, v78
	v_cvt_pk_bf16_f32 v75, v76, v75
	v_rcp_f32_e32 v77, v5
	s_nop 0
	v_mul_f32_e32 v5, 1.0, v77
	v_rcp_f32_e32 v77, v4
	s_nop 0
	v_mul_f32_e32 v4, 1.0, v77
	v_cvt_pk_bf16_f32 v4, v4, v5
	v_mul_f32_e32 v5, 0xbfb8aa3b, v6
	v_exp_f32_e32 v6, v5
	v_mul_f32_e32 v5, 0xbfb8aa3b, v7
	v_exp_f32_e32 v7, v5
	s_nop 0
	v_pk_add_f32 v[6:7], v[6:7], 1.0 op_sel_hi:[1,0]
	s_nop 0
	v_rcp_f32_e32 v76, v7
	s_nop 0
	v_mul_f32_e32 v5, 1.0, v76
	v_rcp_f32_e32 v76, v6
	s_nop 0
	v_mul_f32_e32 v6, 1.0, v76
	v_cvt_pk_bf16_f32 v5, v6, v5
	v_mul_f32_e32 v6, 0xbfb8aa3b, v8
	v_mul_f32_e32 v7, 0xbfb8aa3b, v9
	v_exp_f32_e32 v6, v6
	v_exp_f32_e32 v7, v7
	v_and_b32_e32 v79, 0xffff0000, v100
	v_pk_add_f32 v[6:7], v[6:7], 1.0 op_sel_hi:[1,0]
	s_nop 0
	v_rcp_f32_e32 v9, v7
	s_nop 0
	v_mul_f32_e32 v7, 1.0, v9
	v_rcp_f32_e32 v9, v6
	s_nop 0
	v_mul_f32_e32 v6, 1.0, v9
	v_cvt_pk_bf16_f32 v6, v6, v7
	v_mul_f32_e32 v7, 0xbfb8aa3b, v10
	v_exp_f32_e32 v8, v7
	v_mul_f32_e32 v7, 0xbfb8aa3b, v11
	v_exp_f32_e32 v9, v7
	v_lshlrev_b32_e32 v78, 16, v100
	v_pk_mul_f32 v[52:53], v[52:53], v[78:79]
	v_lshlrev_b32_e32 v78, 16, v101
	v_pk_add_f32 v[8:9], v[8:9], 1.0 op_sel_hi:[1,0]
	v_and_b32_e32 v79, 0xffff0000, v101
	v_div_scale_f32 v7, s[0:1], v9, v9, 1.0
; DEV float bflo(uint32_t u) { return __uint_as_float(u << 16); }
; DEV float bfhi(uint32_t u) { return __uint_as_float(u & 0xffff0000u); }
; __device__ void phase_merge(PRef p, int l, const bf16* H2, bf16* M, bf16* sA, bf16* sB) {
;     ...
; #pragma unroll
;         for (int a = 0; a < 2; a++)
; #pragma unroll
;           for (int bb = 0; bb < 2; bb++)
; #pragma unroll
;             for (int r = 0; r < 8; r++) {
;               float g0 = __fdividef(1.f, 1.f + __expf(-a2[a][bb][2 * r]));
;               float g1 = __fdividef(1.f, 1.f + __expf(-a2[a][bb][2 * r + 1]));
;               gp[a][bb][r] = pack2(g0, g1);
;             }
;       }
;       f32x16 a1[2][2];
;       zero_acc<2>(a1);
;       gemm_tile<2, false>(a1, U + (size_t)rt * 128 * ldu, ldu, p.WBO + ((size_t)n * 1024 + ct * 128) * 512, 512, 512, sA, sB);
; #pragma unroll
;       for (int a = 0; a < 2; a++)
; #pragma unroll
;         for (int bb = 0; bb < 2; bb++)
; #pragma unroll
;           for (int r = 0; r < 8; r++) {
;             a1[a][bb][2 * r] *= bflo(gp[a][bb][r]);
;             a1[a][bb][2 * r + 1] *= bfhi(gp[a][bb][r]);
;           }
	v_rcp_f32_e32 v10, v7
	v_pk_mul_f32 v[54:55], v[54:55], v[78:79]
	v_lshlrev_b32_e32 v78, 16, v102
	v_and_b32_e32 v79, 0xffff0000, v102
	v_fma_f32 v11, -v7, v10, 1.0
	v_fmac_f32_e32 v10, v11, v10
	v_div_scale_f32 v11, vcc, 1.0, v9, 1.0
	v_mul_f32_e32 v76, v11, v10
	v_fma_f32 v77, -v7, v76, v11
	v_fmac_f32_e32 v76, v77, v10
	v_fma_f32 v7, -v7, v76, v11
	v_div_fmas_f32 v7, v7, v10, v76
	v_div_fixup_f32 v7, v7, v9, 1.0
	v_div_scale_f32 v9, s[0:1], v8, v8, 1.0
	v_rcp_f32_e32 v10, v9
	v_pk_mul_f32 v[56:57], v[56:57], v[78:79]
	v_lshlrev_b32_e32 v78, 16, v103
	v_and_b32_e32 v79, 0xffff0000, v103
	v_fma_f32 v11, -v9, v10, 1.0
	v_fmac_f32_e32 v10, v11, v10
	v_div_scale_f32 v11, vcc, 1.0, v8, 1.0
	v_mul_f32_e32 v76, v11, v10
	v_fma_f32 v77, -v9, v76, v11
	v_fmac_f32_e32 v76, v77, v10
	v_fma_f32 v9, -v9, v76, v11
	v_div_fmas_f32 v9, v9, v10, v76
	v_div_fixup_f32 v8, v9, v8, 1.0
	v_cvt_pk_bf16_f32 v7, v8, v7
	v_mul_f32_e32 v8, 0xbfb8aa3b, v12
	v_mul_f32_e32 v9, 0xbfb8aa3b, v13
	v_exp_f32_e32 v8, v8
	v_exp_f32_e32 v9, v9
	v_pk_mul_f32 v[58:59], v[58:59], v[78:79]
	v_lshlrev_b32_e32 v78, 16, v104
	v_and_b32_e32 v79, 0xffff0000, v104
	v_pk_add_f32 v[8:9], v[8:9], 1.0 op_sel_hi:[1,0]
	v_pk_mul_f32 v[60:61], v[60:61], v[78:79]
	v_div_scale_f32 v10, s[0:1], v9, v9, 1.0
	v_rcp_f32_e32 v11, v10
	v_lshlrev_b32_e32 v78, 16, v105
	v_and_b32_e32 v79, 0xffff0000, v105
	v_pk_mul_f32 v[62:63], v[62:63], v[78:79]
	v_fma_f32 v12, -v10, v11, 1.0
	v_fmac_f32_e32 v11, v12, v11
	v_div_scale_f32 v12, vcc, 1.0, v9, 1.0
	v_mul_f32_e32 v13, v12, v11
	v_fma_f32 v76, -v10, v13, v12
	v_fmac_f32_e32 v13, v76, v11
	v_fma_f32 v10, -v10, v13, v12
	v_div_fmas_f32 v10, v10, v11, v13
	v_div_fixup_f32 v9, v10, v9, 1.0
	v_div_scale_f32 v10, s[0:1], v8, v8, 1.0
	v_rcp_f32_e32 v11, v10
	v_lshlrev_b32_e32 v78, 16, v106
	v_and_b32_e32 v79, 0xffff0000, v106
	v_pk_mul_f32 v[64:65], v[64:65], v[78:79]
	v_fma_f32 v12, -v10, v11, 1.0
	v_fmac_f32_e32 v11, v12, v11
	v_div_scale_f32 v12, vcc, 1.0, v8, 1.0
	v_mul_f32_e32 v13, v12, v11
	v_fma_f32 v76, -v10, v13, v12
	v_fmac_f32_e32 v13, v76, v11
	v_fma_f32 v10, -v10, v13, v12
	v_div_fmas_f32 v10, v10, v11, v13
	v_div_fixup_f32 v8, v10, v8, 1.0
	v_cvt_pk_bf16_f32 v80, v8, v9
	v_mul_f32_e32 v8, 0xbfb8aa3b, v14
	v_mul_f32_e32 v9, 0xbfb8aa3b, v15
	v_exp_f32_e32 v8, v8
	v_exp_f32_e32 v9, v9
	v_lshlrev_b32_e32 v78, 16, v107
	v_and_b32_e32 v79, 0xffff0000, v107
	v_pk_mul_f32 v[66:67], v[66:67], v[78:79]
	v_pk_add_f32 v[8:9], v[8:9], 1.0 op_sel_hi:[1,0]
	v_lshlrev_b32_e32 v78, 16, v68
	v_div_scale_f32 v10, s[0:1], v9, v9, 1.0
	v_rcp_f32_e32 v11, v10
	v_and_b32_e32 v79, 0xffff0000, v68
	v_lshlrev_b32_e32 v68, 16, v69
	v_and_b32_e32 v69, 0xffff0000, v69
	v_fma_f32 v12, -v10, v11, 1.0
	v_fmac_f32_e32 v11, v12, v11
	v_div_scale_f32 v12, vcc, 1.0, v9, 1.0
	v_mul_f32_e32 v13, v12, v11
	v_fma_f32 v14, -v10, v13, v12
	v_fmac_f32_e32 v13, v14, v11
	v_fma_f32 v10, -v10, v13, v12
	v_div_fmas_f32 v10, v10, v11, v13
	v_div_fixup_f32 v9, v10, v9, 1.0
	v_div_scale_f32 v10, s[0:1], v8, v8, 1.0
	v_rcp_f32_e32 v11, v10
	v_pk_mul_f32 v[38:39], v[38:39], v[68:69]
	v_lshlrev_b32_e32 v68, 16, v70
	v_and_b32_e32 v69, 0xffff0000, v70
	v_fma_f32 v12, -v10, v11, 1.0
	v_fmac_f32_e32 v11, v12, v11
	v_div_scale_f32 v12, vcc, 1.0, v8, 1.0
	v_mul_f32_e32 v13, v12, v11
	v_fma_f32 v14, -v10, v13, v12
	v_fmac_f32_e32 v13, v14, v11
	v_fma_f32 v10, -v10, v13, v12
	v_div_fmas_f32 v10, v10, v11, v13
	v_div_fixup_f32 v8, v10, v8, 1.0
	v_cvt_pk_bf16_f32 v81, v8, v9
	v_mul_f32_e32 v8, 0xbfb8aa3b, v16
	v_mul_f32_e32 v9, 0xbfb8aa3b, v17
	v_exp_f32_e32 v8, v8
	v_exp_f32_e32 v9, v9
	v_pk_mul_f32 v[40:41], v[40:41], v[68:69]
	v_lshlrev_b32_e32 v68, 16, v71
	v_and_b32_e32 v69, 0xffff0000, v71
	v_pk_add_f32 v[8:9], v[8:9], 1.0 op_sel_hi:[1,0]
	v_pk_mul_f32 v[42:43], v[42:43], v[68:69]
	v_div_scale_f32 v10, s[0:1], v9, v9, 1.0
	v_rcp_f32_e32 v11, v10
	v_lshlrev_b32_e32 v68, 16, v72
	v_and_b32_e32 v69, 0xffff0000, v72
	v_pk_mul_f32 v[44:45], v[44:45], v[68:69]
	v_fma_f32 v12, -v10, v11, 1.0
	v_fmac_f32_e32 v11, v12, v11
	v_div_scale_f32 v12, vcc, 1.0, v9, 1.0
	v_mul_f32_e32 v13, v12, v11
	v_fma_f32 v14, -v10, v13, v12
	v_fmac_f32_e32 v13, v14, v11
	v_fma_f32 v10, -v10, v13, v12
	v_div_fmas_f32 v10, v10, v11, v13
	v_div_fixup_f32 v9, v10, v9, 1.0
	v_div_scale_f32 v10, s[0:1], v8, v8, 1.0
	v_rcp_f32_e32 v11, v10
	v_lshlrev_b32_e32 v68, 16, v73
	v_and_b32_e32 v69, 0xffff0000, v73
	v_pk_mul_f32 v[46:47], v[46:47], v[68:69]
	v_fma_f32 v12, -v10, v11, 1.0
	v_fmac_f32_e32 v11, v12, v11
	v_div_scale_f32 v12, vcc, 1.0, v8, 1.0
	v_mul_f32_e32 v13, v12, v11
	v_fma_f32 v14, -v10, v13, v12
	v_fmac_f32_e32 v13, v14, v11
	v_fma_f32 v10, -v10, v13, v12
	v_div_fmas_f32 v10, v10, v11, v13
	v_div_fixup_f32 v8, v10, v8, 1.0
	v_cvt_pk_bf16_f32 v82, v8, v9
	v_mul_f32_e32 v8, 0xbfb8aa3b, v18
	v_mul_f32_e32 v9, 0xbfb8aa3b, v19
	v_exp_f32_e32 v8, v8
	v_exp_f32_e32 v9, v9
	v_lshlrev_b32_e32 v68, 16, v74
	v_and_b32_e32 v69, 0xffff0000, v74
	v_pk_mul_f32 v[48:49], v[48:49], v[68:69]
	v_pk_add_f32 v[8:9], v[8:9], 1.0 op_sel_hi:[1,0]
	v_lshlrev_b32_e32 v68, 16, v75
	v_div_scale_f32 v10, s[0:1], v9, v9, 1.0
	v_rcp_f32_e32 v11, v10
	v_and_b32_e32 v69, 0xffff0000, v75
	v_pk_mul_f32 v[50:51], v[50:51], v[68:69]
	v_lshlrev_b32_e32 v68, 16, v4
	v_fma_f32 v12, -v10, v11, 1.0
	v_fmac_f32_e32 v11, v12, v11
	v_div_scale_f32 v12, vcc, 1.0, v9, 1.0
	v_mul_f32_e32 v13, v12, v11
	v_fma_f32 v14, -v10, v13, v12
	v_fmac_f32_e32 v13, v14, v11
	v_fma_f32 v10, -v10, v13, v12
	v_div_fmas_f32 v10, v10, v11, v13
; DEV int tid_() { int t = threadIdx.x; asm volatile("" : "+v"(t)); return t; }
; DEV float bflo(uint32_t u) { return __uint_as_float(u << 16); }
; DEV float bfhi(uint32_t u) { return __uint_as_float(u & 0xffff0000u); }
; template <int NI>
; DEV void stage_tile(const f32x16 (&acc)[2][NI], bf16* sC) {
;   constexpr int LDC = NI * 64 + 8;
;   int tid = tid_();
;   int lane = tid & 63, wave = tid >> 6;
;   int wm = wave >> 1, wn = wave & 1;
;   __syncthreads();
; #pragma unroll
;   for (int mi = 0; mi < 2; mi++)
; #pragma unroll
;     for (int ni = 0; ni < NI; ni++)
; #pragma unroll
;       for (int g = 0; g < 4; g++) {
;         int row = wm * 64 + mi * 32 + (lane & 31);
;         int col = wn * NI * 32 + ni * 32 + 8 * g + 4 * (lane >> 5);
;         uint2 v;
;         v.x = pack2(acc[mi][ni][4 * g], acc[mi][ni][4 * g + 1]);
;         v.y = pack2(acc[mi][ni][4 * g + 2], acc[mi][ni][4 * g + 3]);
;         *(uint2*)(sC + row * LDC + col) = v;
;       }
;   __syncthreads();
; __device__ void phase_merge(PRef p, int l, const bf16* H2, bf16* M, bf16* sA, bf16* sB) {
;     ...
; #pragma unroll
;       for (int a = 0; a < 2; a++)
; #pragma unroll
;         for (int bb = 0; bb < 2; bb++)
; #pragma unroll
;           for (int r = 0; r < 8; r++) {
;             a1[a][bb][2 * r] *= bflo(gp[a][bb][r]);
;             a1[a][bb][2 * r + 1] *= bfhi(gp[a][bb][r]);
;           }
;       stage_tile<2>(a1, sA);
;       TILE_CHUNKS(2, sA, {
;         u32x4* mp = (u32x4*)(M + (size_t)(rt * 128 + trow) * 1024 + ct * 128 + tcol);
;         u32x4 ov = cv;
;         if (n != 0) {
;           u32x4 pv = *mp;
;           _Pragma("unroll") for (int j = 0; j < 4; j++) ov[j] = pack2(bflo(pv[j]) + bflo(cv[j]), bfhi(pv[j]) + bfhi(cv[j]));
;         }
;         *mp = ov;
;       })
	v_div_fixup_f32 v9, v10, v9, 1.0
	v_div_scale_f32 v10, s[0:1], v8, v8, 1.0
	v_rcp_f32_e32 v11, v10
	v_and_b32_e32 v69, 0xffff0000, v4
	v_lshlrev_b32_e32 v4, 16, v5
	v_and_b32_e32 v5, 0xffff0000, v5
	v_fma_f32 v12, -v10, v11, 1.0
	v_fmac_f32_e32 v11, v12, v11
	v_div_scale_f32 v12, vcc, 1.0, v8, 1.0
	v_mul_f32_e32 v13, v12, v11
	v_fma_f32 v14, -v10, v13, v12
	v_fmac_f32_e32 v13, v14, v11
	v_fma_f32 v10, -v10, v13, v12
	v_pk_mul_f32 v[4:5], v[22:23], v[4:5]
	v_lshlrev_b32_e32 v22, 16, v6
	v_and_b32_e32 v23, 0xffff0000, v6
	v_div_fmas_f32 v10, v10, v11, v13
	v_pk_mul_f32 v[22:23], v[24:25], v[22:23]
	v_lshlrev_b32_e32 v24, 16, v80
	v_and_b32_e32 v25, 0xffff0000, v80
	v_div_fixup_f32 v8, v10, v8, 1.0
	v_lshlrev_b32_e32 v10, 16, v2
	v_and_b32_e32 v11, 0xffff0000, v2
	v_pk_mul_f32 v[24:25], v[28:29], v[24:25]
	v_lshlrev_b32_e32 v28, 16, v82
	v_and_b32_e32 v29, 0xffff0000, v82
	v_mov_b32_e32 v2, v196
	v_pk_mul_f32 v[28:29], v[32:33], v[28:29]
	v_cvt_pk_bf16_f32 v83, v8, v9
	v_lshrrev_b32_e32 v32, 1, v2
	v_and_b32_e32 v33, 31, v2
	v_and_or_b32 v32, v32, s75, v33
	v_and_b32_e32 v33, 64, v2
	v_lshrrev_b32_e32 v2, 2, v2
	v_lshlrev_b32_e32 v8, 16, v0
	v_and_b32_e32 v9, 0xffff0000, v0
	v_lshlrev_b32_e32 v0, 16, v1
	v_and_b32_e32 v1, 0xffff0000, v1
	v_lshlrev_b32_e32 v12, 16, v116
	v_and_b32_e32 v13, 0xffff0000, v116
	v_and_b32_e32 v2, 8, v2
	v_pk_mul_f32 v[8:9], v[84:85], v[8:9]
	v_pk_mul_f32 v[0:1], v[86:87], v[0:1]
	v_pk_mul_f32 v[10:11], v[88:89], v[10:11]
	v_pk_mul_f32 v[12:13], v[90:91], v[12:13]
	v_lshlrev_b32_e32 v14, 16, v117
	v_and_b32_e32 v15, 0xffff0000, v117
	v_lshlrev_b32_e32 v16, 16, v118
	v_and_b32_e32 v17, 0xffff0000, v118
	v_lshlrev_b32_e32 v18, 16, v119
	v_and_b32_e32 v19, 0xffff0000, v119
	v_lshlrev_b32_e32 v76, 16, v120
	v_and_b32_e32 v77, 0xffff0000, v120
	v_lshl_or_b32 v2, v33, 1, v2
	v_pk_mul_f32 v[14:15], v[92:93], v[14:15]
	v_pk_mul_f32 v[16:17], v[94:95], v[16:17]
	v_pk_mul_f32 v[18:19], v[96:97], v[18:19]
	v_pk_mul_f32 v[76:77], v[98:99], v[76:77]
	v_mad_u64_u32 v[32:33], s[0:1], v32, s52, v[2:3]
	v_cvt_pk_bf16_f32 v8, v8, v9
	v_cvt_pk_bf16_f32 v9, v0, v1
	v_cvt_pk_bf16_f32 v0, v10, v11
	v_cvt_pk_bf16_f32 v1, v12, v13
	s_barrier
	ds_write2_b64 v32, v[8:9], v[0:1] offset1:2
	v_cvt_pk_bf16_f32 v0, v14, v15
	v_cvt_pk_bf16_f32 v1, v16, v17
	v_cvt_pk_bf16_f32 v8, v18, v19
	v_cvt_pk_bf16_f32 v9, v76, v77
	ds_write2_b64 v32, v[0:1], v[8:9] offset0:4 offset1:6
	v_cvt_pk_bf16_f32 v0, v52, v53
	v_cvt_pk_bf16_f32 v1, v54, v55
	v_cvt_pk_bf16_f32 v8, v56, v57
	v_cvt_pk_bf16_f32 v9, v58, v59
	v_pk_mul_f32 v[36:37], v[36:37], v[78:79]
	v_lshlrev_b32_e32 v6, 16, v7
	v_and_b32_e32 v7, 0xffff0000, v7
	ds_write2_b64 v32, v[0:1], v[8:9] offset0:8 offset1:10
	v_cvt_pk_bf16_f32 v0, v60, v61
	v_cvt_pk_bf16_f32 v1, v62, v63
	v_cvt_pk_bf16_f32 v8, v64, v65
	v_cvt_pk_bf16_f32 v9, v66, v67
	v_pk_mul_f32 v[6:7], v[26:27], v[6:7]
	v_lshlrev_b32_e32 v26, 16, v81
	v_and_b32_e32 v27, 0xffff0000, v81
	ds_write2_b64 v32, v[0:1], v[8:9] offset0:12 offset1:14
	v_cvt_pk_bf16_f32 v0, v36, v37
	v_cvt_pk_bf16_f32 v1, v38, v39
	v_cvt_pk_bf16_f32 v8, v40, v41
	v_cvt_pk_bf16_f32 v9, v42, v43
	v_add_u32_e32 v2, 0x2000, v32
	v_pk_mul_f32 v[20:21], v[20:21], v[68:69]
	v_pk_mul_f32 v[26:27], v[30:31], v[26:27]
	v_lshlrev_b32_e32 v30, 16, v83
	v_and_b32_e32 v31, 0xffff0000, v83
	ds_write2_b64 v2, v[0:1], v[8:9] offset0:64 offset1:66
	v_cvt_pk_bf16_f32 v0, v44, v45
	v_cvt_pk_bf16_f32 v1, v46, v47
	v_cvt_pk_bf16_f32 v8, v48, v49
	v_cvt_pk_bf16_f32 v9, v50, v51
	v_pk_mul_f32 v[30:31], v[34:35], v[30:31]
	ds_write2_b64 v2, v[0:1], v[8:9] offset0:68 offset1:70
	v_cvt_pk_bf16_f32 v0, v20, v21
	v_cvt_pk_bf16_f32 v1, v4, v5
	v_cvt_pk_bf16_f32 v4, v22, v23
	v_cvt_pk_bf16_f32 v5, v6, v7
	ds_write2_b64 v2, v[0:1], v[4:5] offset0:72 offset1:74
	v_cvt_pk_bf16_f32 v0, v24, v25
	v_cvt_pk_bf16_f32 v1, v26, v27
	v_cvt_pk_bf16_f32 v4, v28, v29
	v_cvt_pk_bf16_f32 v5, v30, v31
	ds_write2_b64 v2, v[0:1], v[4:5] offset0:76 offset1:78
	v_mov_b32_e32 v2, v196
	s_waitcnt lgkmcnt(0)
	s_barrier
	s_and_b64 vcc, exec, s[54:55]
	v_ashrrev_i32_e32 v0, 31, v2
	v_lshrrev_b32_e32 v0, 28, v0
	v_add_u32_e32 v0, v2, v0
	v_ashrrev_i32_e32 v8, 4, v0
	v_and_b32_e32 v0, -16, v0
	v_sub_u32_e32 v4, v2, v0
	v_mul_lo_u32 v5, v8, s52
	v_lshlrev_b32_e32 v0, 3, v4
	v_lshl_add_u32 v4, v4, 4, v5
	ds_read_b128 v[4:7], v4
	v_add_u32_e32 v8, s94, v8
	v_ashrrev_i32_e32 v9, 31, v8
	v_lshlrev_b64 v[8:9], 11, v[8:9]
	v_ashrrev_i32_e32 v1, 31, v0
	v_lshl_add_u64 v[8:9], s[22:23], 0, v[8:9]
	v_lshl_add_u64 v[0:1], v[0:1], 1, v[8:9]
	s_cbranch_vccz .LBB0_995
	global_load_dwordx4 v[8:11], v[0:1], off
	s_waitcnt lgkmcnt(0)
	v_lshlrev_b32_e32 v14, 16, v4
	v_and_b32_e32 v15, 0xffff0000, v4
	s_waitcnt vmcnt(0)
	v_lshlrev_b32_e32 v12, 16, v8
	v_and_b32_e32 v13, 0xffff0000, v8
	v_pk_add_f32 v[12:13], v[14:15], v[12:13]
	v_lshlrev_b32_e32 v14, 16, v5
	v_cvt_pk_bf16_f32 v8, v12, v13
	v_lshlrev_b32_e32 v12, 16, v9
	v_and_b32_e32 v13, 0xffff0000, v9
	v_and_b32_e32 v15, 0xffff0000, v5
	v_pk_add_f32 v[12:13], v[14:15], v[12:13]
	v_lshlrev_b32_e32 v14, 16, v6
	v_cvt_pk_bf16_f32 v9, v12, v13
	v_lshlrev_b32_e32 v12, 16, v10
	v_and_b32_e32 v13, 0xffff0000, v10
	v_and_b32_e32 v15, 0xffff0000, v6
	v_pk_add_f32 v[12:13], v[14:15], v[12:13]
	v_lshlrev_b32_e32 v14, 16, v7
	v_cvt_pk_bf16_f32 v10, v12, v13
	v_lshlrev_b32_e32 v12, 16, v11
	v_and_b32_e32 v13, 0xffff0000, v11
	v_and_b32_e32 v15, 0xffff0000, v7
	v_pk_add_f32 v[12:13], v[14:15], v[12:13]
	s_nop 0
	v_cvt_pk_bf16_f32 v11, v12, v13
	s_cbranch_execnz .LBB0_975
